# attention body rewritten by hand: softmax VALU software-pipelined under the MFMAs, 6-step unrolled loop, V LDS image in natural key order (no permlane swaps), scale*log2e folded into Q in post_rows (s
# speedup vs baseline: 1.0689x; 1.0414x over previous
.LBB0_253:
	s_or_b64 exec, exec, s[72:73]
	s_waitcnt vmcnt(7)
	v_and_b32_e32 v143, 0xffff0000, v120
	v_lshlrev_b32_e32 v141, 16, v120
	v_mul_f32_e32 v156, v143, v143
	v_lshlrev_b32_e32 v145, 16, v121
	v_fmac_f32_e32 v156, v141, v141
	v_and_b32_e32 v155, 0xffff0000, v121
	v_fmac_f32_e32 v156, v145, v145
	v_lshlrev_b32_e32 v158, 16, v122
	v_fmac_f32_e32 v156, v155, v155
	v_and_b32_e32 v159, 0xffff0000, v122
	v_fmac_f32_e32 v156, v158, v158
	v_lshlrev_b32_e32 v160, 16, v123
	v_fmac_f32_e32 v156, v159, v159
	v_and_b32_e32 v161, 0xffff0000, v123
	v_fmac_f32_e32 v156, v160, v160
	v_and_b32_e32 v120, 0xffff0000, v116
	v_lshlrev_b32_e32 v121, 16, v116
	v_fmac_f32_e32 v156, v161, v161
	v_pk_mul_f32 v[122:123], v[120:121], v[120:121]
	v_lshl_or_b32 v92, v95, 3, v148
	v_add_f32_e32 v116, v123, v156
	v_add_f32_e32 v156, v122, v116
	v_and_b32_e32 v116, 0xffff0000, v117
	v_lshlrev_b32_e32 v117, 16, v117
	v_pk_mul_f32 v[122:123], v[116:117], v[116:117]
	v_ashrrev_i32_e32 v93, 31, v92
	v_add_f32_e32 v123, v123, v156
	v_add_f32_e32 v162, v122, v123
	v_and_b32_e32 v122, 0xffff0000, v118
	v_lshlrev_b32_e32 v123, 16, v118
	v_pk_mul_f32 v[156:157], v[122:123], v[122:123]
	v_lshlrev_b64 v[96:97], 7, v[124:125]
	v_add_f32_e32 v118, v157, v162
	v_add_f32_e32 v162, v156, v118
	v_and_b32_e32 v118, 0xffff0000, v119
	v_lshlrev_b32_e32 v119, 16, v119
	v_pk_mul_f32 v[156:157], v[118:119], v[118:119]
	v_lshlrev_b64 v[92:93], 13, v[92:93]
	v_add_f32_e32 v157, v157, v162
	v_add_f32_e32 v156, v156, v157
	ds_bpermute_b32 v157, v149, v156
	v_ashrrev_i32_e32 v95, 31, v94
	v_lshl_add_u64 v[98:99], v[128:129], 0, v[96:97]
	v_lshl_add_u64 v[108:109], v[130:131], 0, v[96:97]
	v_lshl_add_u64 v[146:147], v[92:93], 0, v[94:95]
	global_load_dwordx4 v[92:95], v[98:99], off offset:16
	global_load_dwordx4 v[104:107], v[98:99], off
	s_nop 0
	global_load_dwordx4 v[96:99], v[108:109], off offset:16
	s_nop 0
	global_load_dwordx4 v[108:111], v[108:109], off
	s_waitcnt lgkmcnt(0)
	v_add_f32_e32 v156, v156, v157
	ds_bpermute_b32 v157, v150, v156
	s_movk_i32 s1, 0x180
	s_waitcnt lgkmcnt(0)
	v_add_f32_e32 v156, v156, v157
	ds_bpermute_b32 v157, v151, v156
	s_waitcnt lgkmcnt(0)
	v_add_f32_e32 v156, v156, v157
	v_fmamk_f32 v156, v156, 0x3c000000, v189
	v_cmp_gt_f32_e32 vcc, s33, v156
	v_mul_f32_e32 v157, 0x4b800000, v156
	s_nop 0
	v_cndmask_b32_e32 v156, v156, v157, vcc
	v_rsq_f32_e32 v156, v156
	s_nop 0
	v_mul_f32_e32 v157, 0x45800000, v156
	v_cndmask_b32_e32 v156, v156, v157, vcc
	v_mul_f32_e32 v156, 0x3dd53b94, v156
	v_mul_f32_e32 v141, v156, v141
	v_mul_f32_e32 v157, v0, v141
	v_mul_f32_e32 v141, v156, v143
	v_mul_f32_e32 v143, v1, v141
	v_mul_f32_e32 v141, v156, v145
	v_mul_f32_e32 v116, v156, v116
	v_mul_f32_e32 v145, v2, v141
	v_mul_f32_e32 v141, v156, v155
	v_mul_f32_e32 v165, v11, v116
	v_mul_f32_e32 v116, v156, v123
	v_mul_f32_e32 v155, v3, v141
	v_mul_f32_e32 v141, v156, v158
	v_mul_f32_e32 v166, v12, v116
	v_mul_f32_e32 v116, v156, v122
	v_mul_f32_e32 v158, v4, v141
	v_mul_f32_e32 v141, v156, v159
	v_mul_f32_e32 v167, v13, v116
	v_mul_f32_e32 v116, v156, v119
	v_mul_f32_e32 v159, v5, v141
	v_mul_f32_e32 v141, v156, v160
	v_mul_f32_e32 v117, v156, v117
	v_mul_f32_e32 v168, v14, v116
	v_mul_f32_e32 v116, v156, v118
	v_mul_f32_e32 v160, v6, v141
	v_mul_f32_e32 v141, v156, v161
	v_mul_f32_e32 v121, v156, v121
	v_mul_f32_e32 v120, v156, v120
	v_mul_f32_e32 v164, v10, v117
	v_mul_f32_e32 v156, v15, v116
	v_mov_b64_e32 v[116:117], s[70:71]
	v_mad_u64_u32 v[116:117], s[2:3], v146, s1, v[116:117]
	v_mul_f32_e32 v161, v7, v141
	v_mad_i32_i24 v117, v147, s1, v117
	v_mov_b32_e32 v141, v177
	v_lshl_add_u64 v[122:123], v[116:117], 0, v[140:141]
	v_cvt_pk_bf16_f32 v118, v157, v143
	v_cvt_pk_bf16_f32 v119, v145, v155
	v_mul_f32_e32 v162, v8, v121
	v_mul_f32_e32 v163, v9, v120
	v_cvt_pk_bf16_f32 v120, v158, v159
	v_cvt_pk_bf16_f32 v121, v160, v161
	global_store_dwordx4 v[122:123], v[118:121], off
	s_waitcnt vmcnt(11)
	v_lshlrev_b32_e32 v157, 16, v114
	v_mov_b32_e32 v143, v177
	v_cvt_pk_bf16_f32 v118, v162, v163
	v_cvt_pk_bf16_f32 v119, v164, v165
	v_cvt_pk_bf16_f32 v120, v166, v167
	v_cvt_pk_bf16_f32 v121, v168, v156
	global_store_dwordx4 v[122:123], v[118:121], off offset:16
	v_and_b32_e32 v156, 0xffff0000, v114
	v_pk_mul_f32 v[158:159], v[156:157], v[156:157]
	v_lshlrev_b32_e32 v118, 16, v112
	v_and_b32_e32 v119, 0xffff0000, v112
	v_pk_mul_f32 v[120:121], v[118:119], v[118:119]
	v_and_b32_e32 v112, 0xffff0000, v113
	v_lshlrev_b32_e32 v113, 16, v113
	v_pk_mul_f32 v[122:123], v[112:113], v[112:113]
	v_add_f32_e32 v120, v120, v121
	v_add_f32_e32 v120, v123, v120
	v_add_f32_e32 v120, v122, v120
	v_and_b32_e32 v114, 0xffff0000, v115
	v_lshlrev_b32_e32 v115, 16, v115
	v_add_f32_e32 v120, v159, v120
	v_pk_mul_f32 v[160:161], v[114:115], v[114:115]
	v_add_f32_e32 v120, v158, v120
	v_add_f32_e32 v120, v161, v120
	v_add_f32_e32 v120, v160, v120
	ds_bpermute_b32 v121, v149, v120
	v_lshl_add_u64 v[116:117], v[116:117], 0, v[142:143]
	v_mov_b32_e32 v145, v177
	s_waitcnt lgkmcnt(0)
	v_add_f32_e32 v120, v120, v121
	ds_bpermute_b32 v121, v150, v120
	s_waitcnt lgkmcnt(0)
	v_add_f32_e32 v120, v120, v121
	ds_bpermute_b32 v121, v151, v120
	s_waitcnt lgkmcnt(0)
	v_add_f32_e32 v120, v120, v121
	v_fmamk_f32 v120, v120, 0x3c800000, v189
	v_cmp_gt_f32_e32 vcc, s33, v120
	v_mul_f32_e32 v121, 0x4b800000, v120
	s_nop 0
	v_cndmask_b32_e32 v120, v120, v121, vcc
	v_rsq_f32_e32 v120, v120
	s_nop 0
	v_mul_f32_e32 v121, 0x45800000, v120
	v_cndmask_b32_e32 v120, v120, v121, vcc
	v_mul_f32_e32 v120, 0x3dd53b94, v120
	v_mul_f32_e32 v118, v120, v118
	v_mul_f32_e32 v118, v48, v118
	ds_bpermute_b32 v121, v149, v118
	v_mul_f32_e32 v113, v120, v113
	v_mul_f32_e32 v113, v50, v113
	v_mul_f32_e32 v112, v120, v112
	v_mul_f32_e32 v112, v51, v112
	s_waitcnt vmcnt(2) lgkmcnt(0)
	v_mul_f32_e32 v121, v108, v121
	v_cndmask_b32_e64 v121, v121, -v121, s[40:41]
	v_fmac_f32_e32 v121, v104, v118
	v_mul_f32_e32 v118, v120, v119
	v_mul_f32_e32 v118, v49, v118
	ds_bpermute_b32 v119, v149, v118
	s_waitcnt lgkmcnt(0)
	v_mul_f32_e32 v119, v109, v119
	v_cndmask_b32_e64 v119, v119, -v119, s[40:41]
	v_fmac_f32_e32 v119, v105, v118
	ds_bpermute_b32 v118, v149, v113
	s_waitcnt lgkmcnt(0)
	v_mul_f32_e32 v118, v110, v118
	v_cndmask_b32_e64 v118, v118, -v118, s[40:41]
	v_fmac_f32_e32 v118, v106, v113
	ds_bpermute_b32 v113, v149, v112
	s_waitcnt lgkmcnt(0)
	v_mul_f32_e32 v113, v111, v113
	v_cndmask_b32_e64 v113, v113, -v113, s[40:41]
	v_fmac_f32_e32 v113, v107, v112
	v_mul_f32_e32 v112, v120, v157
	v_mul_f32_e32 v112, v52, v112
	ds_bpermute_b32 v122, v149, v112
	s_waitcnt lgkmcnt(0)
	v_mul_f32_e32 v122, v96, v122
	v_cndmask_b32_e64 v122, v122, -v122, s[40:41]
	v_fmac_f32_e32 v122, v92, v112
	v_mul_f32_e32 v112, v120, v156
	v_mul_f32_e32 v112, v53, v112
	ds_bpermute_b32 v123, v149, v112
	s_waitcnt lgkmcnt(0)
	v_mul_f32_e32 v123, v97, v123
	v_cndmask_b32_e64 v123, v123, -v123, s[40:41]
	v_fmac_f32_e32 v123, v93, v112
	v_mul_f32_e32 v112, v120, v115
	v_mul_f32_e32 v112, v54, v112
	ds_bpermute_b32 v115, v149, v112
	s_waitcnt lgkmcnt(0)
	v_mul_f32_e32 v115, v98, v115
	v_cndmask_b32_e64 v115, v115, -v115, s[40:41]
	v_fmac_f32_e32 v115, v94, v112
	v_mul_f32_e32 v112, v120, v114
	v_mul_f32_e32 v112, v55, v112
	ds_bpermute_b32 v114, v149, v112
	s_waitcnt lgkmcnt(0)
	v_mul_f32_e32 v114, v99, v114
	v_cndmask_b32_e64 v120, v114, -v114, s[40:41]
	v_fmac_f32_e32 v120, v95, v112
	v_cvt_pk_bf16_f32 v112, v121, v119
	v_cvt_pk_bf16_f32 v113, v118, v113
	v_cvt_pk_bf16_f32 v114, v122, v123
	v_cvt_pk_bf16_f32 v115, v115, v120
	global_store_dwordx4 v[116:117], v[112:115], off offset:256
	v_and_b32_e32 v118, 0xffff0000, v102
	v_lshlrev_b32_e32 v119, 16, v102
	v_lshlrev_b32_e32 v112, 16, v100
	v_and_b32_e32 v113, 0xffff0000, v100
	v_pk_mul_f32 v[114:115], v[112:113], v[112:113]
	v_and_b32_e32 v100, 0xffff0000, v101
	v_lshlrev_b32_e32 v101, 16, v101
	v_pk_mul_f32 v[116:117], v[100:101], v[100:101]
	v_add_f32_e32 v114, v114, v115
	v_add_f32_e32 v114, v117, v114
	v_pk_mul_f32 v[120:121], v[118:119], v[118:119]
	v_add_f32_e32 v114, v116, v114
	v_and_b32_e32 v102, 0xffff0000, v103
	v_lshlrev_b32_e32 v103, 16, v103
	v_add_f32_e32 v114, v121, v114
	v_pk_mul_f32 v[122:123], v[102:103], v[102:103]
	v_add_f32_e32 v114, v120, v114
	v_add_f32_e32 v114, v123, v114
	v_add_f32_e32 v114, v122, v114
	ds_bpermute_b32 v115, v149, v114
	s_waitcnt lgkmcnt(0)
	v_add_f32_e32 v114, v114, v115
	ds_bpermute_b32 v115, v150, v114
	s_waitcnt lgkmcnt(0)
	v_add_f32_e32 v114, v114, v115
	ds_bpermute_b32 v115, v151, v114
	s_waitcnt lgkmcnt(0)
	v_add_f32_e32 v114, v114, v115
	v_fmamk_f32 v114, v114, 0x3c800000, v189
	v_cmp_gt_f32_e32 vcc, s33, v114
	v_mul_f32_e32 v115, 0x4b800000, v114
	s_nop 0
	v_cndmask_b32_e32 v114, v114, v115, vcc
	v_rsq_f32_e32 v114, v114
	s_nop 0
	v_mul_f32_e32 v115, 0x45800000, v114
	v_cndmask_b32_e32 v114, v114, v115, vcc
	v_mul_f32_e32 v112, v114, v112
	v_mul_f32_e32 v112, v40, v112
	ds_bpermute_b32 v115, v149, v112
	v_mul_f32_e32 v101, v114, v101
	v_mul_f32_e32 v101, v42, v101
	v_mul_f32_e32 v100, v114, v100
	v_mul_f32_e32 v100, v43, v100
	s_waitcnt lgkmcnt(0)
	v_mul_f32_e32 v108, v108, v115
	v_cndmask_b32_e64 v108, v108, -v108, s[40:41]
	v_fmac_f32_e32 v108, v104, v112
	v_mul_f32_e32 v104, v114, v113
	v_mul_f32_e32 v104, v41, v104
	ds_bpermute_b32 v112, v149, v104
	s_waitcnt lgkmcnt(0)
	v_mul_f32_e32 v109, v109, v112
	v_cndmask_b32_e64 v109, v109, -v109, s[40:41]
	v_fmac_f32_e32 v109, v105, v104
	ds_bpermute_b32 v104, v149, v101
	s_waitcnt lgkmcnt(0)
	v_mul_f32_e32 v104, v110, v104
	v_cndmask_b32_e64 v104, v104, -v104, s[40:41]
	v_fmac_f32_e32 v104, v106, v101
	ds_bpermute_b32 v101, v149, v100
	s_waitcnt lgkmcnt(0)
	v_mul_f32_e32 v101, v111, v101
	v_cndmask_b32_e64 v101, v101, -v101, s[40:41]
	v_fmac_f32_e32 v101, v107, v100
	v_mul_f32_e32 v100, v114, v119
	v_mul_f32_e32 v100, v44, v100
	ds_bpermute_b32 v105, v149, v100
	s_waitcnt lgkmcnt(0)
	v_mul_f32_e32 v96, v96, v105
	v_cndmask_b32_e64 v96, v96, -v96, s[40:41]
	v_fmac_f32_e32 v96, v92, v100
	v_mul_f32_e32 v92, v114, v118
	v_mul_f32_e32 v92, v45, v92
	ds_bpermute_b32 v100, v149, v92
	s_waitcnt lgkmcnt(0)
	v_mul_f32_e32 v97, v97, v100
	v_cndmask_b32_e64 v97, v97, -v97, s[40:41]
	v_fmac_f32_e32 v97, v93, v92
	v_mul_f32_e32 v92, v114, v103
	v_mul_f32_e32 v92, v46, v92
	ds_bpermute_b32 v93, v149, v92
	v_lshlrev_b32_e32 v100, 16, v85
	v_and_b32_e32 v103, 0xffff0000, v85
	v_and_b32_e32 v85, 0xffff0000, v86
	s_waitcnt lgkmcnt(0)
	v_mul_f32_e32 v93, v98, v93
	v_cndmask_b32_e64 v98, v93, -v93, s[40:41]
	v_fmac_f32_e32 v98, v94, v92
	v_mul_f32_e32 v92, v114, v102
	v_mul_f32_e32 v92, v47, v92
	ds_bpermute_b32 v93, v149, v92
	v_and_b32_e32 v102, 0xffff0000, v81
	s_waitcnt lgkmcnt(0)
	v_mul_f32_e32 v93, v99, v93
	v_cndmask_b32_e64 v99, v93, -v93, s[40:41]
	v_fmac_f32_e32 v99, v95, v92
	v_cvt_pk_bf16_f32 v92, v108, v109
	v_cvt_pk_bf16_f32 v93, v104, v101
	v_cvt_pk_bf16_f32 v94, v96, v97
	v_mov_b64_e32 v[96:97], s[68:69]
	v_mad_u64_u32 v[96:97], s[2:3], v146, s1, v[96:97]
	v_mad_i32_i24 v97, v147, s1, v97
	v_lshl_add_u64 v[96:97], v[96:97], 0, v[142:143]
	s_mov_b32 s1, 0x2b000000
	v_add_co_u32_e32 v96, vcc, s1, v96
	v_cvt_pk_bf16_f32 v95, v98, v99
	v_lshlrev_b32_e32 v101, 16, v81
	s_nop 0
	v_addc_co_u32_e32 v97, vcc, 0, v97, vcc
	global_store_dwordx4 v[96:97], v[92:95], off offset:256
	v_lshlrev_b32_e32 v96, 16, v89
	v_and_b32_e32 v97, 0xffff0000, v89
	v_and_b32_e32 v95, 0xffff0000, v88
	v_lshlrev_b32_e32 v94, 16, v88
	v_mul_f32_e32 v98, v95, v95
	v_fmac_f32_e32 v98, v94, v94
	v_fmac_f32_e32 v98, v96, v96
	v_and_b32_e32 v88, 0xffff0000, v90
	v_lshlrev_b32_e32 v89, 16, v90
	v_fmac_f32_e32 v98, v97, v97
	v_pk_mul_f32 v[92:93], v[88:89], v[88:89]
	v_and_b32_e32 v81, 0xffff0000, v82
	v_add_f32_e32 v90, v93, v98
	v_add_f32_e32 v98, v92, v90
	v_and_b32_e32 v90, 0xffff0000, v91
	v_lshlrev_b32_e32 v91, 16, v91
	v_pk_mul_f32 v[92:93], v[90:91], v[90:91]
	v_and_b32_e32 v99, 0xffff0000, v84
	v_add_f32_e32 v93, v93, v98
	v_add_f32_e32 v92, v92, v93
	ds_bpermute_b32 v93, v152, v92
	s_waitcnt lgkmcnt(0)
	v_add_f32_e32 v92, v92, v93
	ds_bpermute_b32 v93, v153, v92
	s_waitcnt lgkmcnt(0)
	v_add_f32_e32 v92, v92, v93
	ds_bpermute_b32 v93, v154, v92
	s_waitcnt lgkmcnt(0)
	v_add_f32_e32 v92, v92, v93
	ds_bpermute_b32 v93, v149, v92
	s_waitcnt lgkmcnt(0)
	v_add_f32_e32 v92, v92, v93
	ds_bpermute_b32 v93, v150, v92
	s_waitcnt lgkmcnt(0)
	v_add_f32_e32 v92, v92, v93
	ds_bpermute_b32 v93, v151, v92
	s_waitcnt lgkmcnt(0)
	v_add_f32_e32 v92, v92, v93
	v_fmamk_f32 v92, v92, 0x3b000000, v189
	v_cmp_gt_f32_e32 vcc, s33, v92
	v_mul_f32_e32 v93, 0x4b800000, v92
	s_nop 0
	v_cndmask_b32_e32 v92, v92, v93, vcc
	v_rsq_f32_e32 v92, v92
	s_nop 0
	v_mul_f32_e32 v93, 0x45800000, v92
	v_cndmask_b32_e32 v92, v92, v93, vcc
	v_mul_f32_e32 v93, v92, v94
	v_mul_f32_e32 v94, v92, v95
	v_mul_f32_e32 v95, v92, v96
	v_mul_f32_e32 v96, v92, v97
	v_mul_f32_e32 v97, v92, v89
	v_mul_f32_e32 v98, v92, v88
	v_mul_f32_e32 v91, v92, v91
	v_mul_f32_e32 v92, v92, v90
	v_cvt_pk_bf16_f32 v88, v93, v94
	v_cvt_pk_bf16_f32 v89, v95, v96
	v_cvt_pk_bf16_f32 v90, v97, v98
	v_cvt_pk_bf16_f32 v91, v91, v92
	v_lshlrev_b64 v[92:93], 10, v[124:125]
	v_lshlrev_b32_e32 v96, 16, v80
	v_lshlrev_b32_e32 v97, 16, v84
	v_lshl_add_u64 v[92:93], v[126:127], 0, v[92:93]
	v_and_b32_e32 v98, 0xffff0000, v80
	v_lshlrev_b32_e32 v80, 16, v82
	v_mul_f32_e32 v82, v96, v97
	global_store_dwordx4 v[92:93], v[88:91], off
	v_and_b32_e32 v92, 0xffff0000, v57
	v_and_b32_e32 v93, 0xffff0000, v60
	v_lshlrev_b32_e32 v88, 16, v56
	v_and_b32_e32 v90, 0xffff0000, v56
	v_lshlrev_b32_e32 v91, 16, v57
	v_lshlrev_b32_e32 v89, 16, v60
	v_lshlrev_b32_e32 v94, 16, v61
	v_and_b32_e32 v95, 0xffff0000, v61
	v_lshlrev_b32_e32 v84, 16, v86
	v_lshlrev_b32_e32 v56, 16, v87
	v_lshlrev_b32_e32 v60, 16, v83
	v_and_b32_e32 v61, 0xffff0000, v83
	v_and_b32_e32 v57, 0xffff0000, v87
	v_fma_f32 v96, v16, v82, v24
	v_lshlrev_b32_e32 v83, 16, v76
	v_lshlrev_b32_e32 v82, 16, v68
	v_lshlrev_b32_e32 v87, 16, v72
	v_lshlrev_b32_e32 v86, 16, v64
	v_pk_mul_f32 v[82:83], v[82:83], v[86:87]
	v_pk_mul_f32 v[80:81], v[84:85], v[80:81]
	v_pk_mul_f32 v[82:83], v[138:139], v[82:83]
	v_pk_fma_f32 v[80:81], v[20:21], v[80:81], v[28:29]
	v_add_f32_e32 v82, v82, v96
	v_add_f32_e32 v82, v82, v83
	v_mul_f32_e32 v83, 0xbfb8aa3b, v89
	v_exp_f32_e32 v83, v83
	v_mul_f32_e32 v82, v82, v88
	v_pk_mul_f32 v[56:57], v[56:57], v[60:61]
	v_add_f32_e32 v83, 1.0, v83
	v_div_scale_f32 v86, s[2:3], v83, v83, v89
	v_rcp_f32_e32 v87, v86
	v_pk_fma_f32 v[56:57], v[22:23], v[56:57], v[30:31]
	v_fma_f32 v88, -v86, v87, 1.0
	v_fmac_f32_e32 v87, v88, v87
	v_div_scale_f32 v88, vcc, v89, v83, v89
	v_mul_f32_e32 v96, v88, v87
	v_fma_f32 v97, -v86, v96, v88
	v_fmac_f32_e32 v96, v97, v87
	v_fma_f32 v86, -v86, v96, v88
	v_div_fmas_f32 v86, v86, v87, v96
	v_div_fixup_f32 v83, v86, v83, v89
	v_and_b32_e32 v86, 0xffff0000, v68
	v_mul_f32_e32 v68, 0xbfb8aa3b, v93
	v_exp_f32_e32 v68, v68
	v_and_b32_e32 v89, 0xffff0000, v72
	v_and_b32_e32 v87, 0xffff0000, v76
	v_and_b32_e32 v88, 0xffff0000, v64
	v_add_f32_e32 v68, 1.0, v68
	v_div_scale_f32 v72, s[2:3], v68, v68, v93
	v_rcp_f32_e32 v76, v72
	v_mul_f32_e32 v82, v83, v82
	v_mul_f32_e32 v83, v98, v99
	v_pk_mul_f32 v[86:87], v[86:87], v[88:89]
	v_fma_f32 v83, v17, v83, v25
	v_pk_mul_f32 v[86:87], v[32:33], v[86:87]
	v_lshlrev_b32_e32 v89, 16, v73
	v_add_f32_e32 v64, v86, v83
	v_fma_f32 v83, -v72, v76, 1.0
	v_fmac_f32_e32 v76, v83, v76
	v_div_scale_f32 v83, vcc, v93, v68, v93
	v_mul_f32_e32 v86, v83, v76
	v_add_f32_e32 v64, v64, v87
	v_fma_f32 v87, -v72, v86, v83
	v_fmac_f32_e32 v86, v87, v76
	v_fma_f32 v72, -v72, v86, v83
	v_div_fmas_f32 v72, v72, v76, v86
	v_div_fixup_f32 v68, v72, v68, v93
	v_mul_f32_e32 v72, 0xbfb8aa3b, v94
	v_exp_f32_e32 v72, v72
	v_mul_f32_e32 v64, v64, v90
	v_lshlrev_b32_e32 v87, 16, v77
	v_lshlrev_b32_e32 v86, 16, v69
	v_lshlrev_b32_e32 v88, 16, v65
	v_mul_f32_e32 v68, v68, v64
	v_mul_f32_e32 v64, v101, v100
	v_pk_mul_f32 v[86:87], v[86:87], v[88:89]
	v_add_f32_e32 v72, 1.0, v72
	v_fma_f32 v64, v18, v64, v26
	v_pk_mul_f32 v[86:87], v[136:137], v[86:87]
	v_div_scale_f32 v76, s[2:3], v72, v72, v94
	v_add_f32_e32 v64, v86, v64
	v_rcp_f32_e32 v86, v76
	v_add_f32_e32 v64, v64, v87
	v_mul_f32_e32 v64, v64, v91
	v_and_b32_e32 v77, 0xffff0000, v77
	v_fma_f32 v87, -v76, v86, 1.0
	v_fmac_f32_e32 v86, v87, v86
	v_div_scale_f32 v87, vcc, v94, v72, v94
	v_mul_f32_e32 v88, v87, v86
	v_fma_f32 v89, -v76, v88, v87
	v_fmac_f32_e32 v88, v89, v86
	v_fma_f32 v76, -v76, v88, v87
	v_div_fmas_f32 v76, v76, v86, v88
	v_div_fixup_f32 v72, v76, v72, v94
	v_mul_f32_e32 v72, v72, v64
	v_mul_f32_e32 v64, v102, v103
	v_and_b32_e32 v76, 0xffff0000, v69
	v_and_b32_e32 v87, 0xffff0000, v73
	v_and_b32_e32 v86, 0xffff0000, v65
	v_fma_f32 v88, v19, v64, v27
	v_pk_mul_f32 v[64:65], v[76:77], v[86:87]
	v_and_b32_e32 v87, 0xffff0000, v74
	v_pk_mul_f32 v[64:65], v[34:35], v[64:65]
	v_mul_f32_e32 v83, v68, v68
	v_add_f32_e32 v64, v64, v88
	v_add_f32_e32 v64, v64, v65
	v_mul_f32_e32 v65, 0xbfb8aa3b, v95
	v_exp_f32_e32 v65, v65
	v_mul_f32_e32 v64, v64, v92
	v_fmac_f32_e32 v83, v82, v82
	v_fmac_f32_e32 v83, v72, v72
	v_add_f32_e32 v65, 1.0, v65
	v_div_scale_f32 v69, s[2:3], v65, v65, v95
	v_rcp_f32_e32 v73, v69
	s_nop 0
	v_fma_f32 v76, -v69, v73, 1.0
	v_fmac_f32_e32 v73, v76, v73
	v_div_scale_f32 v76, vcc, v95, v65, v95
	v_mul_f32_e32 v77, v76, v73
	v_fma_f32 v86, -v69, v77, v76
	v_fmac_f32_e32 v77, v86, v73
	v_fma_f32 v69, -v69, v77, v76
	v_div_fmas_f32 v69, v69, v73, v77
	v_div_fixup_f32 v65, v69, v65, v95
	v_mul_f32_e32 v69, v65, v64
	v_lshlrev_b32_e32 v65, 16, v78
	v_lshlrev_b32_e32 v64, 16, v70
	v_lshlrev_b32_e32 v77, 16, v74
	v_lshlrev_b32_e32 v76, 16, v66
	v_pk_mul_f32 v[64:65], v[64:65], v[76:77]
	v_and_b32_e32 v77, 0xffff0000, v78
	v_and_b32_e32 v76, 0xffff0000, v70
	v_and_b32_e32 v86, 0xffff0000, v66
	v_pk_mul_f32 v[76:77], v[76:77], v[86:87]
	v_and_b32_e32 v87, 0xffff0000, v58
	v_lshlrev_b32_e32 v86, 16, v58
	v_and_b32_e32 v58, 0xffff0000, v62
	v_lshlrev_b32_e32 v62, 16, v62
	v_mul_f32_e32 v66, 0xbfb8aa3b, v62
	v_exp_f32_e32 v88, v66
	v_mul_f32_e32 v66, 0xbfb8aa3b, v58
	v_exp_f32_e32 v89, v66
	v_pk_mul_f32 v[64:65], v[134:135], v[64:65]
	v_pk_mul_f32 v[76:77], v[36:37], v[76:77]
	v_mov_b32_e32 v84, v64
	v_mov_b32_e32 v85, v76
	v_pk_add_f32 v[80:81], v[84:85], v[80:81]
	v_mov_b32_e32 v76, v65
	v_pk_add_f32 v[64:65], v[80:81], v[76:77]
	v_pk_add_f32 v[76:77], v[88:89], 1.0 op_sel_hi:[1,0]
	v_pk_mul_f32 v[64:65], v[64:65], v[86:87]
	v_div_scale_f32 v66, s[2:3], v77, v77, v58
	v_rcp_f32_e32 v70, v66
	v_fmac_f32_e32 v83, v69, v69
	v_lshlrev_b32_e32 v80, 16, v67
	v_lshlrev_b32_e32 v81, 16, v75
	v_fma_f32 v73, -v66, v70, 1.0
	v_fmac_f32_e32 v70, v73, v70
	v_div_scale_f32 v73, vcc, v58, v77, v58
	v_mul_f32_e32 v74, v73, v70
	v_fma_f32 v78, -v66, v74, v73
	v_fmac_f32_e32 v74, v78, v70
	v_fma_f32 v66, -v66, v74, v73
	v_div_fmas_f32 v66, v66, v70, v74
	v_div_fixup_f32 v77, v66, v77, v58
	v_div_scale_f32 v58, s[2:3], v76, v76, v62
	v_rcp_f32_e32 v66, v58
	v_and_b32_e32 v78, 0xffff0000, v71
	v_fma_f32 v70, -v58, v66, 1.0
	v_fmac_f32_e32 v66, v70, v66
	v_div_scale_f32 v70, vcc, v62, v76, v62
	v_mul_f32_e32 v73, v70, v66
	v_fma_f32 v74, -v58, v73, v70
	v_fmac_f32_e32 v73, v74, v66
	v_fma_f32 v58, -v58, v73, v70
	v_div_fmas_f32 v58, v58, v66, v73
	v_div_fixup_f32 v76, v58, v76, v62
	v_pk_mul_f32 v[64:65], v[76:77], v[64:65]
	v_and_b32_e32 v70, 0xffff0000, v67
	v_pk_mul_f32 v[76:77], v[64:65], v[64:65]
	v_and_b32_e32 v73, 0xffff0000, v63
	v_add_f32_e32 v58, v76, v83
	v_add_f32_e32 v62, v77, v58
	v_lshlrev_b32_e32 v77, 16, v79
	v_lshlrev_b32_e32 v76, 16, v71
	v_and_b32_e32 v79, 0xffff0000, v79
	v_and_b32_e32 v71, 0xffff0000, v75
	v_lshlrev_b32_e32 v63, 16, v63
	v_pk_mul_f32 v[66:67], v[78:79], v[70:71]
	v_and_b32_e32 v71, 0xffff0000, v59
	v_lshlrev_b32_e32 v70, 16, v59
	v_mul_f32_e32 v58, 0xbfb8aa3b, v63
	v_mul_f32_e32 v59, 0xbfb8aa3b, v73
	v_exp_f32_e32 v58, v58
	v_exp_f32_e32 v59, v59
	v_pk_mul_f32 v[76:77], v[76:77], v[80:81]
	v_pk_mul_f32 v[66:67], v[38:39], v[66:67]
	v_pk_mul_f32 v[76:77], v[132:133], v[76:77]
	v_mov_b32_e32 v61, v66
	v_mov_b32_e32 v60, v76
	v_pk_add_f32 v[58:59], v[58:59], 1.0 op_sel_hi:[1,0]
	v_pk_add_f32 v[56:57], v[60:61], v[56:57]
	v_div_scale_f32 v60, s[2:3], v59, v59, v73
	v_rcp_f32_e32 v61, v60
	v_mov_b32_e32 v66, v77
	v_pk_add_f32 v[56:57], v[56:57], v[66:67]
	v_fma_f32 v66, -v60, v61, 1.0
	v_fmac_f32_e32 v61, v66, v61
	v_div_scale_f32 v66, vcc, v73, v59, v73
	v_mul_f32_e32 v67, v66, v61
	v_pk_mul_f32 v[56:57], v[56:57], v[70:71]
	v_fma_f32 v70, -v60, v67, v66
	v_fmac_f32_e32 v67, v70, v61
	v_fma_f32 v60, -v60, v67, v66
	v_div_fmas_f32 v60, v60, v61, v67
	v_div_fixup_f32 v59, v60, v59, v73
	v_div_scale_f32 v60, s[2:3], v58, v58, v63
	v_rcp_f32_e32 v61, v60
	s_nop 0
	v_fma_f32 v66, -v60, v61, 1.0
	v_fmac_f32_e32 v61, v66, v61
	v_div_scale_f32 v66, vcc, v63, v58, v63
	v_mul_f32_e32 v67, v66, v61
	v_fma_f32 v70, -v60, v67, v66
	v_fmac_f32_e32 v67, v70, v61
	v_fma_f32 v60, -v60, v67, v66
	v_div_fmas_f32 v60, v60, v61, v67
	v_div_fixup_f32 v58, v60, v58, v63
	v_pk_mul_f32 v[56:57], v[58:59], v[56:57]
	s_nop 0
	v_pk_mul_f32 v[58:59], v[56:57], v[56:57]
	s_nop 0
	v_add_f32_e32 v58, v58, v62
	v_add_f32_e32 v58, v59, v58
	ds_bpermute_b32 v59, v152, v58
	s_waitcnt lgkmcnt(0)
	v_add_f32_e32 v58, v58, v59
	ds_bpermute_b32 v59, v153, v58
	s_waitcnt lgkmcnt(0)
	v_add_f32_e32 v58, v58, v59
	ds_bpermute_b32 v59, v154, v58
	s_waitcnt lgkmcnt(0)
	v_add_f32_e32 v58, v58, v59
	ds_bpermute_b32 v59, v149, v58
	s_waitcnt lgkmcnt(0)
	v_add_f32_e32 v58, v58, v59
	ds_bpermute_b32 v59, v150, v58
	s_waitcnt lgkmcnt(0)
	v_add_f32_e32 v58, v58, v59
	ds_bpermute_b32 v59, v151, v58
	s_waitcnt lgkmcnt(0)
	v_add_f32_e32 v58, v58, v59
	v_fmamk_f32 v58, v58, 0x3b000000, v189
	v_cmp_gt_f32_e32 vcc, s33, v58
	v_mul_f32_e32 v59, 0x4b800000, v58
	s_nop 0
	v_cndmask_b32_e32 v58, v58, v59, vcc
	v_rsq_f32_e32 v58, v58
	s_nop 0
	v_mul_f32_e32 v59, 0x45800000, v58
	v_cndmask_b32_e32 v58, v58, v59, vcc
	v_mul_f32_e32 v60, v68, v58
	v_mul_f32_e32 v61, v72, v58
	v_mul_f32_e32 v59, v82, v58
	v_mul_f32_e32 v62, v69, v58
	v_mul_f32_e32 v63, v64, v58
	v_mul_f32_e32 v64, v65, v58
	v_mul_f32_e32 v65, v56, v58
	v_mul_f32_e32 v66, v57, v58
	v_cvt_pk_bf16_f32 v56, v59, v60
	v_cvt_pk_bf16_f32 v57, v61, v62
	v_lshlrev_b64 v[60:61], 12, v[124:125]
	v_lshl_add_u64 v[60:61], s[68:69], 0, v[60:61]
	v_lshl_add_u64 v[60:61], v[60:61], 0, v[144:145]
	v_add_co_u32_e32 v60, vcc, 0xd800000, v60
	v_add_u32_e32 v124, s48, v124
	s_nop 0
	v_addc_co_u32_e32 v61, vcc, 0, v61, vcc
	v_cmp_lt_i32_e32 vcc, s15, v124
	s_or_b64 s[44:45], vcc, s[44:45]
	v_cvt_pk_bf16_f32 v58, v63, v64
	v_cvt_pk_bf16_f32 v59, v65, v66
	global_store_dwordx4 v[60:61], v[56:59], off offset:3072
	s_andn2_b64 exec, exec, s[44:45]
	s_cbranch_execz .LBB0_262

.LBB0_417:
	s_ashr_i32 s40, s77, 8
	s_ashr_i32 s41, s40, 31
	s_and_b32 s49, s77, 7
	s_lshl_b32 s1, s77, 5
	s_and_b32 s34, s1, 0x1f00
	s_lshl_b32 s2, s40, 3
	s_or_b32 s2, s2, s49
	s_mul_i32 s3, s2, 0x300000
	s_mul_i32 s1, s34, 0x180
	s_add_u32 s12, s68, s3
	s_addc_u32 s13, s69, 0
	s_add_u32 s12, s12, s1
	s_addc_u32 s13, s13, 0
	s_add_u32 s42, s70, s3
	s_addc_u32 s43, s71, 0
	s_lshl_b32 s1, s40, 25
	s_lshl_b32 s3, s49, 9
	s_add_i32 s1, s1, s3
	s_add_i32 s1, s1, 0x24000100
	s_add_u32 s46, s38, s1
	s_addc_u32 s47, s39, 0
	s_lshr_b32 s15, s85, 6
	s_lshl_b32 s52, s15, 5
	s_lshl_b32 s1, s15, 8
	s_add_i32 s44, s1, 0x1e000
	s_mul_i32 s60, s15, 0xc00
	s_add_i32 s60, s60, 0xc000
	s_lshl_b32 s61, s15, 11
	v_mbcnt_lo_u32_b32 v176, -1, 0
	v_mbcnt_hi_u32_b32 v200, -1, v176
	v_and_b32_e32 v196, 31, v200
	v_lshrrev_b32_e32 v198, 5, v200
	v_or_b32_e32 v187, s52, v196
	v_mul_u32_u24_e32 v187, 0x180, v187
	v_lshl_add_u32 v187, v198, 4, v187
	global_load_dwordx4 v[96:99], v187, s[12:13] offset:0
	global_load_dwordx4 v[100:103], v187, s[12:13] offset:32
	global_load_dwordx4 v[104:107], v187, s[12:13] offset:64
	global_load_dwordx4 v[108:111], v187, s[12:13] offset:96
	global_load_dwordx4 v[112:115], v187, s[12:13] offset:128
	global_load_dwordx4 v[116:119], v187, s[12:13] offset:160
	global_load_dwordx4 v[120:123], v187, s[12:13] offset:192
	global_load_dwordx4 v[124:127], v187, s[12:13] offset:224
	global_load_dwordx4 v[128:131], v187, s[12:13] offset:256
	global_load_dwordx4 v[132:135], v187, s[12:13] offset:288
	global_load_dwordx4 v[136:139], v187, s[12:13] offset:320
	global_load_dwordx4 v[140:143], v187, s[12:13] offset:352
	s_mul_i32 s1, s15, 3
	s_add_i32 s1, s1, 0
	s_lshl_b32 s1, s1, 6
	v_add_u32_e32 v247, s1, v200
	v_mul_u32_u24_e32 v248, 0xaab, v247
	v_lshrrev_b32_e32 v248, 16, v248
	v_mul_u32_u24_e32 v249, 24, v248
	v_sub_u32_e32 v247, v247, v249
	v_bfe_u32 v249, v248, 1, 3
	v_xor_b32_e32 v247, v247, v249
	v_mul_u32_u24_e32 v248, 0x180, v248
	v_lshl_add_u32 v182, v247, 4, v248
	s_mul_i32 s1, s15, 3
	s_add_i32 s1, s1, 1
	s_lshl_b32 s1, s1, 6
	v_add_u32_e32 v247, s1, v200
	v_mul_u32_u24_e32 v248, 0xaab, v247
	v_lshrrev_b32_e32 v248, 16, v248
	v_mul_u32_u24_e32 v249, 24, v248
	v_sub_u32_e32 v247, v247, v249
	v_bfe_u32 v249, v248, 1, 3
	v_xor_b32_e32 v247, v247, v249
	v_mul_u32_u24_e32 v248, 0x180, v248
	v_lshl_add_u32 v183, v247, 4, v248
	s_mul_i32 s1, s15, 3
	s_add_i32 s1, s1, 2
	s_lshl_b32 s1, s1, 6
	v_add_u32_e32 v247, s1, v200
	v_mul_u32_u24_e32 v248, 0xaab, v247
	v_lshrrev_b32_e32 v248, 16, v248
	v_mul_u32_u24_e32 v249, 24, v248
	v_sub_u32_e32 v247, v247, v249
	v_bfe_u32 v249, v248, 1, 3
	v_xor_b32_e32 v247, v247, v249
	v_mul_u32_u24_e32 v248, 0x180, v248
	v_lshl_add_u32 v184, v247, 4, v248
	s_lshl_b32 s1, s15, 1
	s_add_i32 s1, s1, 0
	s_lshl_b32 s1, s1, 6
	v_add_u32_e32 v247, s1, v200
	v_lshrrev_b32_e32 v248, 7, v247
	v_lshlrev_b32_e32 v248, 3, v248
	v_bfe_u32 v249, v247, 2, 3
	v_or_b32_e32 v248, v248, v249
	v_bfe_u32 v249, v247, 5, 2
	v_and_b32_e32 v247, 3, v247
	v_lshlrev_b32_e32 v247, 4, v247
	v_lshl_add_u32 v247, v249, 6, v247
	v_lshl_add_u32 v185, v248, 12, v247
	s_lshl_b32 s1, s15, 1
	s_add_i32 s1, s1, 1
	s_lshl_b32 s1, s1, 6
	v_add_u32_e32 v247, s1, v200
	v_lshrrev_b32_e32 v248, 7, v247
	v_lshlrev_b32_e32 v248, 3, v248
	v_bfe_u32 v249, v247, 2, 3
	v_or_b32_e32 v248, v248, v249
	v_bfe_u32 v249, v247, 5, 2
	v_and_b32_e32 v247, 3, v247
	v_lshlrev_b32_e32 v247, 4, v247
	v_lshl_add_u32 v247, v249, 6, v247
	v_lshl_add_u32 v186, v248, 12, v247
	v_bfe_u32 v247, v196, 1, 3
	v_mul_u32_u24_e32 v248, 0x180, v196
	v_add_u32_e32 v248, 0xc000, v248
	v_or_b32_e32 v249, 0, v198
	v_xor_b32_e32 v249, v249, v247
	v_lshl_add_u32 v240, v249, 4, v248
	v_or_b32_e32 v249, 2, v198
	v_xor_b32_e32 v249, v249, v247
	v_lshl_add_u32 v241, v249, 4, v248
	v_or_b32_e32 v249, 4, v198
	v_xor_b32_e32 v249, v249, v247
	v_lshl_add_u32 v242, v249, 4, v248
	v_or_b32_e32 v249, 6, v198
	v_xor_b32_e32 v249, v249, v247
	v_lshl_add_u32 v243, v249, 4, v248
	v_and_b32_e32 v247, 3, v200
	v_lshlrev_b32_e32 v244, 3, v247
	v_bfe_u32 v247, v200, 2, 2
	v_lshl_or_b32 v244, v247, 6, v244
	v_bfe_u32 v247, v200, 4, 1
	v_lshl_or_b32 v244, v247, 5, v244
	v_lshl_or_b32 v244, v198, 8, v244
	v_mov_b32_e32 v0, 0
	v_mov_b32_e32 v1, 0
	v_mov_b32_e32 v2, 0
	v_mov_b32_e32 v3, 0
	v_mov_b32_e32 v4, 0
	v_mov_b32_e32 v5, 0
	v_mov_b32_e32 v6, 0
	v_mov_b32_e32 v7, 0
	v_mov_b32_e32 v8, 0
	v_mov_b32_e32 v9, 0
	v_mov_b32_e32 v10, 0
	v_mov_b32_e32 v11, 0
	v_mov_b32_e32 v12, 0
	v_mov_b32_e32 v13, 0
	v_mov_b32_e32 v14, 0
	v_mov_b32_e32 v15, 0
	v_mov_b32_e32 v16, 0
	v_mov_b32_e32 v17, 0
	v_mov_b32_e32 v18, 0
	v_mov_b32_e32 v19, 0
	v_mov_b32_e32 v20, 0
	v_mov_b32_e32 v21, 0
	v_mov_b32_e32 v22, 0
	v_mov_b32_e32 v23, 0
	v_mov_b32_e32 v24, 0
	v_mov_b32_e32 v25, 0
	v_mov_b32_e32 v26, 0
	v_mov_b32_e32 v27, 0
	v_mov_b32_e32 v28, 0
	v_mov_b32_e32 v29, 0
	v_mov_b32_e32 v30, 0
	v_mov_b32_e32 v31, 0
	v_mov_b32_e32 v32, 0
	v_mov_b32_e32 v33, 0
	v_mov_b32_e32 v34, 0
	v_mov_b32_e32 v35, 0
	v_mov_b32_e32 v36, 0
	v_mov_b32_e32 v37, 0
	v_mov_b32_e32 v38, 0
	v_mov_b32_e32 v39, 0
	v_mov_b32_e32 v40, 0
	v_mov_b32_e32 v41, 0
	v_mov_b32_e32 v42, 0
	v_mov_b32_e32 v43, 0
	v_mov_b32_e32 v44, 0
	v_mov_b32_e32 v45, 0
	v_mov_b32_e32 v46, 0
	v_mov_b32_e32 v47, 0
	v_mov_b32_e32 v48, 0
	v_mov_b32_e32 v49, 0
	v_mov_b32_e32 v50, 0
	v_mov_b32_e32 v51, 0
	v_mov_b32_e32 v52, 0
	v_mov_b32_e32 v53, 0
	v_mov_b32_e32 v54, 0
	v_mov_b32_e32 v55, 0
	v_mov_b32_e32 v56, 0
	v_mov_b32_e32 v57, 0
	v_mov_b32_e32 v58, 0
	v_mov_b32_e32 v59, 0
	v_mov_b32_e32 v60, 0
	v_mov_b32_e32 v61, 0
	v_mov_b32_e32 v62, 0
	v_mov_b32_e32 v63, 0
	v_mov_b32_e32 v245, 0
	v_mov_b32_e32 v246, 0
	s_add_i32 m0, s60, 0x0
	s_nop 0
	global_load_lds_dwordx4 v182, s[42:43]
	s_add_i32 m0, s60, 0x400
	s_nop 0
	global_load_lds_dwordx4 v183, s[42:43]
	s_add_i32 m0, s60, 0x800
	s_nop 0
	global_load_lds_dwordx4 v184, s[42:43]
	s_add_u32 s42, s42, 0x6000
	s_addc_u32 s43, s43, 0
	s_add_i32 m0, s60, 0x6000
	s_nop 0
	global_load_lds_dwordx4 v182, s[42:43]
	s_add_i32 m0, s60, 0x6400
	s_nop 0
	global_load_lds_dwordx4 v183, s[42:43]
	s_add_i32 m0, s60, 0x6800
	s_nop 0
	global_load_lds_dwordx4 v184, s[42:43]
	s_add_u32 s42, s42, 0x6000
	s_addc_u32 s43, s43, 0
	s_add_i32 m0, s61, 0x0
	s_nop 0
	global_load_lds_dwordx4 v185, s[46:47]
	s_add_i32 m0, s61, 0x400
	s_nop 0
	global_load_lds_dwordx4 v186, s[46:47]
	s_add_u32 s46, s46, 0x40000
	s_addc_u32 s47, s47, 0
	s_waitcnt vmcnt(5)
	s_barrier
	ds_read_b128 v[144:147], v240 offset:0
	ds_read_b128 v[148:151], v240 offset:12288
	ds_read_b128 v[152:155], v241 offset:0
	ds_read_b128 v[156:159], v241 offset:12288
	ds_read_b128 v[160:163], v242 offset:0
	ds_read_b128 v[164:167], v242 offset:12288
	ds_read_b128 v[168:171], v243 offset:0
	s_waitcnt lgkmcnt(6)
	v_mfma_f32_32x32x16_bf16 v[208:223], v[144:147], v[96:99], 0
	s_add_i32 m0, s60, 0xc000
	s_nop 0
	global_load_lds_dwordx4 v182, s[42:43]
	ds_read_b128 v[172:175], v243 offset:12288
	s_waitcnt lgkmcnt(6)
	v_mfma_f32_32x32x16_bf16 v[224:239], v[148:151], v[96:99], 0
	s_add_i32 m0, s60, 0xc400
	s_nop 0
	global_load_lds_dwordx4 v183, s[42:43]
	ds_read_b128 v[144:147], v240 offset:128
	s_waitcnt lgkmcnt(6)
	v_mfma_f32_32x32x16_bf16 v[208:223], v[152:155], v[100:103], v[208:223]
	s_add_i32 m0, s60, 0xc800
	s_nop 0
	global_load_lds_dwordx4 v184, s[42:43]
	ds_read_b128 v[148:151], v240 offset:12416
	s_waitcnt lgkmcnt(6)
	v_mfma_f32_32x32x16_bf16 v[224:239], v[156:159], v[100:103], v[224:239]
	s_add_i32 m0, s61, 0x4000
	s_nop 0
	global_load_lds_dwordx4 v185, s[46:47]
	ds_read_b128 v[152:155], v241 offset:128
	s_waitcnt lgkmcnt(6)
	v_mfma_f32_32x32x16_bf16 v[208:223], v[160:163], v[104:107], v[208:223]
	s_add_i32 m0, s61, 0x4400
	s_nop 0
	global_load_lds_dwordx4 v186, s[46:47]
	ds_read_b128 v[156:159], v241 offset:12416
	s_waitcnt lgkmcnt(6)
	v_mfma_f32_32x32x16_bf16 v[224:239], v[164:167], v[104:107], v[224:239]
	s_add_u32 s42, s42, 0x6000
	s_addc_u32 s43, s43, 0
	ds_read_b128 v[160:163], v242 offset:128
	s_waitcnt lgkmcnt(6)
	v_mfma_f32_32x32x16_bf16 v[208:223], v[168:171], v[108:111], v[208:223]
	s_add_u32 s46, s46, 0x40000
	s_addc_u32 s47, s47, 0
	ds_read_b128 v[164:167], v242 offset:12416
	s_waitcnt lgkmcnt(6)
	v_mfma_f32_32x32x16_bf16 v[224:239], v[172:175], v[108:111], v[224:239]
	ds_read_b128 v[168:171], v243 offset:128
	s_waitcnt lgkmcnt(6)
	v_mfma_f32_32x32x16_bf16 v[208:223], v[144:147], v[112:115], v[208:223]
	ds_read_b128 v[172:175], v243 offset:12416
	s_waitcnt lgkmcnt(6)
	v_mfma_f32_32x32x16_bf16 v[224:239], v[148:151], v[112:115], v[224:239]
	ds_read_b128 v[144:147], v240 offset:256
	s_waitcnt lgkmcnt(6)
	v_mfma_f32_32x32x16_bf16 v[208:223], v[152:155], v[116:119], v[208:223]
	ds_read_b128 v[148:151], v240 offset:12544
	s_waitcnt lgkmcnt(6)
	v_mfma_f32_32x32x16_bf16 v[224:239], v[156:159], v[116:119], v[224:239]
	ds_read_b128 v[152:155], v241 offset:256
	s_waitcnt lgkmcnt(6)
	v_mfma_f32_32x32x16_bf16 v[208:223], v[160:163], v[120:123], v[208:223]
	ds_read_b128 v[156:159], v241 offset:12544
	s_waitcnt lgkmcnt(6)
	v_mfma_f32_32x32x16_bf16 v[224:239], v[164:167], v[120:123], v[224:239]
	ds_read_b128 v[160:163], v242 offset:256
	s_waitcnt lgkmcnt(6)
	v_mfma_f32_32x32x16_bf16 v[208:223], v[168:171], v[124:127], v[208:223]
	ds_read_b128 v[164:167], v242 offset:12544
	s_waitcnt lgkmcnt(6)
	v_mfma_f32_32x32x16_bf16 v[224:239], v[172:175], v[124:127], v[224:239]
	ds_read_b128 v[168:171], v243 offset:256
	s_waitcnt lgkmcnt(6)
	v_mfma_f32_32x32x16_bf16 v[208:223], v[144:147], v[128:131], v[208:223]
	ds_read_b128 v[172:175], v243 offset:12544
	s_waitcnt lgkmcnt(6)
	v_mfma_f32_32x32x16_bf16 v[224:239], v[148:151], v[128:131], v[224:239]
	v_add_u32_e32 v240, 0x6000, v240
	s_waitcnt lgkmcnt(5)
	v_mfma_f32_32x32x16_bf16 v[208:223], v[152:155], v[132:135], v[208:223]
	v_add_u32_e32 v241, 0x6000, v241
	s_waitcnt lgkmcnt(4)
	v_mfma_f32_32x32x16_bf16 v[224:239], v[156:159], v[132:135], v[224:239]
	v_add_u32_e32 v242, 0x6000, v242
	s_waitcnt lgkmcnt(3)
	v_mfma_f32_32x32x16_bf16 v[208:223], v[160:163], v[136:139], v[208:223]
	v_add_u32_e32 v243, 0x6000, v243
	s_waitcnt lgkmcnt(2)
	v_mfma_f32_32x32x16_bf16 v[224:239], v[164:167], v[136:139], v[224:239]
	s_waitcnt lgkmcnt(1)
	v_mfma_f32_32x32x16_bf16 v[208:223], v[168:171], v[140:143], v[208:223]
	s_waitcnt lgkmcnt(0)
	v_mfma_f32_32x32x16_bf16 v[224:239], v[172:175], v[140:143], v[224:239]
	s_nop 7
	s_nop 7
	v_exp_f32_e32 v208, v208
	v_exp_f32_e32 v209, v209
	v_exp_f32_e32 v210, v210
	v_exp_f32_e32 v211, v211
	v_exp_f32_e32 v212, v212
	v_exp_f32_e32 v213, v213
	v_exp_f32_e32 v214, v214
	v_exp_f32_e32 v215, v215
	v_exp_f32_e32 v216, v216
	v_exp_f32_e32 v217, v217
	v_exp_f32_e32 v218, v218
	v_exp_f32_e32 v219, v219
	v_exp_f32_e32 v220, v220
	v_exp_f32_e32 v221, v221
	v_exp_f32_e32 v222, v222
	v_exp_f32_e32 v223, v223
	v_exp_f32_e32 v224, v224
	v_exp_f32_e32 v225, v225
	v_exp_f32_e32 v226, v226
	v_exp_f32_e32 v227, v227
	v_exp_f32_e32 v228, v228
	v_exp_f32_e32 v229, v229
	v_exp_f32_e32 v230, v230
	v_exp_f32_e32 v231, v231
	v_exp_f32_e32 v232, v232
	v_exp_f32_e32 v233, v233
	v_exp_f32_e32 v234, v234
	v_exp_f32_e32 v235, v235
	v_exp_f32_e32 v236, v236
	v_exp_f32_e32 v237, v237
	v_exp_f32_e32 v238, v238
	v_exp_f32_e32 v239, v239
	s_mov_b32 s78, 21
.Lattn_loop:
	s_waitcnt vmcnt(5)
	s_barrier
	ds_read_b128 v[144:147], v240 offset:0
	ds_read_b128 v[148:151], v240 offset:12288
	ds_read_b128 v[152:155], v241 offset:0
	ds_read_b128 v[156:159], v241 offset:12288
	ds_read_b128 v[160:163], v242 offset:0
	ds_read_b128 v[164:167], v242 offset:12288
	v_add_f32_e32 v245, v208, v245
	v_add_f32_e32 v246, v209, v246
	v_add_f32_e32 v245, v210, v245
	v_add_f32_e32 v246, v211, v246
	v_add_f32_e32 v245, v212, v245
	v_add_f32_e32 v246, v213, v246
	v_add_f32_e32 v245, v214, v245
	v_add_f32_e32 v246, v215, v246
	ds_read_b128 v[168:171], v243 offset:0
	s_waitcnt lgkmcnt(6)
	v_mfma_f32_32x32x16_bf16 v[64:79], v[144:147], v[96:99], 0
	v_add_f32_e32 v245, v216, v245
	v_add_f32_e32 v246, v217, v246
	ds_read_b128 v[172:175], v243 offset:12288
	s_waitcnt lgkmcnt(6)
	v_mfma_f32_32x32x16_bf16 v[80:95], v[148:151], v[96:99], 0
	v_add_f32_e32 v245, v218, v245
	v_add_f32_e32 v246, v219, v246
	ds_read_b128 v[144:147], v240 offset:128
	s_waitcnt lgkmcnt(6)
	v_mfma_f32_32x32x16_bf16 v[64:79], v[152:155], v[100:103], v[64:79]
	v_add_f32_e32 v245, v220, v245
	s_add_i32 m0, s60, 0x0
	s_nop 0
	global_load_lds_dwordx4 v182, s[42:43]
	ds_read_b128 v[148:151], v240 offset:12416
	s_waitcnt lgkmcnt(6)
	v_mfma_f32_32x32x16_bf16 v[80:95], v[156:159], v[100:103], v[80:95]
	v_add_f32_e32 v246, v221, v246
	v_add_f32_e32 v245, v222, v245
	ds_read_b128 v[152:155], v241 offset:128
	s_waitcnt lgkmcnt(6)
	v_mfma_f32_32x32x16_bf16 v[64:79], v[160:163], v[104:107], v[64:79]
	v_add_f32_e32 v246, v223, v246
	v_add_f32_e32 v245, v224, v245
	ds_read_b128 v[156:159], v241 offset:12416
	s_waitcnt lgkmcnt(6)
	v_mfma_f32_32x32x16_bf16 v[80:95], v[164:167], v[104:107], v[80:95]
	v_add_f32_e32 v246, v225, v246
	s_add_i32 m0, s60, 0x400
	s_nop 0
	global_load_lds_dwordx4 v183, s[42:43]
	ds_read_b128 v[160:163], v242 offset:128
	s_waitcnt lgkmcnt(6)
	v_mfma_f32_32x32x16_bf16 v[64:79], v[168:171], v[108:111], v[64:79]
	v_add_f32_e32 v245, v226, v245
	v_add_f32_e32 v246, v227, v246
	ds_read_b128 v[164:167], v242 offset:12416
	s_waitcnt lgkmcnt(6)
	v_mfma_f32_32x32x16_bf16 v[80:95], v[172:175], v[108:111], v[80:95]
	v_add_f32_e32 v245, v228, v245
	v_add_f32_e32 v246, v229, v246
	ds_read_b128 v[168:171], v243 offset:128
	s_waitcnt lgkmcnt(6)
	v_mfma_f32_32x32x16_bf16 v[64:79], v[144:147], v[112:115], v[64:79]
	v_add_f32_e32 v245, v230, v245
	s_add_i32 m0, s60, 0x800
	s_nop 0
	global_load_lds_dwordx4 v184, s[42:43]
	ds_read_b128 v[172:175], v243 offset:12416
	s_waitcnt lgkmcnt(6)
	v_mfma_f32_32x32x16_bf16 v[80:95], v[148:151], v[112:115], v[80:95]
	v_add_f32_e32 v246, v231, v246
	v_add_f32_e32 v245, v232, v245
	ds_read_b128 v[144:147], v240 offset:256
	s_waitcnt lgkmcnt(6)
	v_mfma_f32_32x32x16_bf16 v[64:79], v[152:155], v[116:119], v[64:79]
	v_add_f32_e32 v246, v233, v246
	v_add_f32_e32 v245, v234, v245
	ds_read_b128 v[148:151], v240 offset:12544
	s_waitcnt lgkmcnt(6)
	v_mfma_f32_32x32x16_bf16 v[80:95], v[156:159], v[116:119], v[80:95]
	v_add_f32_e32 v246, v235, v246
	s_add_i32 m0, s61, 0x8000
	s_nop 0
	global_load_lds_dwordx4 v185, s[46:47]
	ds_read_b128 v[152:155], v241 offset:256
	s_waitcnt lgkmcnt(6)
	v_mfma_f32_32x32x16_bf16 v[64:79], v[160:163], v[120:123], v[64:79]
	v_add_f32_e32 v245, v236, v245
	v_add_f32_e32 v246, v237, v246
	ds_read_b128 v[156:159], v241 offset:12544
	s_waitcnt lgkmcnt(6)
	v_mfma_f32_32x32x16_bf16 v[80:95], v[164:167], v[120:123], v[80:95]
	v_add_f32_e32 v245, v238, v245
	v_add_f32_e32 v246, v239, v246
	ds_read_b128 v[160:163], v242 offset:256
	s_waitcnt lgkmcnt(6)
	v_mfma_f32_32x32x16_bf16 v[64:79], v[168:171], v[124:127], v[64:79]
	v_cvt_pk_bf16_f32 v208, v208, v209
	s_add_i32 m0, s61, 0x8400
	s_nop 0
	global_load_lds_dwordx4 v186, s[46:47]
	ds_read_b128 v[164:167], v242 offset:12544
	s_waitcnt lgkmcnt(6)
	v_mfma_f32_32x32x16_bf16 v[80:95], v[172:175], v[124:127], v[80:95]
	v_cvt_pk_bf16_f32 v209, v210, v211
	v_cvt_pk_bf16_f32 v210, v212, v213
	ds_read_b128 v[168:171], v243 offset:256
	s_waitcnt lgkmcnt(6)
	v_mfma_f32_32x32x16_bf16 v[64:79], v[144:147], v[128:131], v[64:79]
	v_cvt_pk_bf16_f32 v211, v214, v215
	v_cvt_pk_bf16_f32 v212, v216, v217
	ds_read_b128 v[172:175], v243 offset:12544
	s_waitcnt lgkmcnt(6)
	v_mfma_f32_32x32x16_bf16 v[80:95], v[148:151], v[128:131], v[80:95]
	v_cvt_pk_bf16_f32 v213, v218, v219
	s_add_u32 s42, s42, 0x6000
	s_addc_u32 s43, s43, 0
	v_add_u32_e32 v240, 0x6000, v240
	ds_read_b64_tr_b16 v[144:145], v244 offset:0
	ds_read_b64_tr_b16 v[146:147], v244 offset:2048
	s_waitcnt lgkmcnt(7)
	v_mfma_f32_32x32x16_bf16 v[64:79], v[152:155], v[132:135], v[64:79]
	v_cvt_pk_bf16_f32 v214, v220, v221
	v_cvt_pk_bf16_f32 v215, v222, v223
	v_add_u32_e32 v241, 0x6000, v241
	ds_read_b64_tr_b16 v[148:149], v244 offset:4096
	ds_read_b64_tr_b16 v[150:151], v244 offset:6144
	s_waitcnt lgkmcnt(8)
	v_mfma_f32_32x32x16_bf16 v[80:95], v[156:159], v[132:135], v[80:95]
	v_cvt_pk_bf16_f32 v224, v224, v225
	v_cvt_pk_bf16_f32 v225, v226, v227
	v_add_u32_e32 v242, 0x6000, v242
	ds_read_b64_tr_b16 v[152:153], v244 offset:8192
	ds_read_b64_tr_b16 v[154:155], v244 offset:10240
	s_waitcnt lgkmcnt(9)
	v_mfma_f32_32x32x16_bf16 v[64:79], v[160:163], v[136:139], v[64:79]
	v_cvt_pk_bf16_f32 v226, v228, v229
	s_add_u32 s46, s46, 0x40000
	s_addc_u32 s47, s47, 0
	v_add_u32_e32 v243, 0x6000, v243
	ds_read_b64_tr_b16 v[156:157], v244 offset:12288
	ds_read_b64_tr_b16 v[158:159], v244 offset:14336
	s_waitcnt lgkmcnt(10)
	v_mfma_f32_32x32x16_bf16 v[80:95], v[164:167], v[136:139], v[80:95]
	v_cvt_pk_bf16_f32 v227, v230, v231
	v_cvt_pk_bf16_f32 v228, v232, v233
	ds_read_b64_tr_b16 v[160:161], v244 offset:512
	ds_read_b64_tr_b16 v[162:163], v244 offset:2560
	s_waitcnt lgkmcnt(11)
	v_mfma_f32_32x32x16_bf16 v[64:79], v[168:171], v[140:143], v[64:79]
	v_cvt_pk_bf16_f32 v229, v234, v235
	v_cvt_pk_bf16_f32 v230, v236, v237
	ds_read_b64_tr_b16 v[164:165], v244 offset:4608
	ds_read_b64_tr_b16 v[166:167], v244 offset:6656
	s_waitcnt lgkmcnt(12)
	v_mfma_f32_32x32x16_bf16 v[80:95], v[172:175], v[140:143], v[80:95]
	v_cvt_pk_bf16_f32 v231, v238, v239
	s_waitcnt lgkmcnt(10)
	v_mfma_f32_32x32x16_bf16 v[48:63], v[208:211], v[144:147], v[48:63]
	s_waitcnt lgkmcnt(8)
	v_mfma_f32_32x32x16_bf16 v[48:63], v[212:215], v[148:151], v[48:63]
	ds_read_b64_tr_b16 v[168:169], v244 offset:8704
	ds_read_b64_tr_b16 v[170:171], v244 offset:10752
	s_waitcnt lgkmcnt(8)
	v_mfma_f32_32x32x16_bf16 v[48:63], v[224:227], v[152:155], v[48:63]
	v_exp_f32_e32 v64, v64
	v_exp_f32_e32 v65, v65
	v_exp_f32_e32 v66, v66
	ds_read_b64_tr_b16 v[172:173], v244 offset:12800
	ds_read_b64_tr_b16 v[174:175], v244 offset:14848
	s_waitcnt lgkmcnt(8)
	v_mfma_f32_32x32x16_bf16 v[48:63], v[228:231], v[156:159], v[48:63]
	v_exp_f32_e32 v67, v67
	v_exp_f32_e32 v68, v68
	v_exp_f32_e32 v69, v69
	ds_read_b64_tr_b16 v[144:145], v244 offset:1024
	ds_read_b64_tr_b16 v[146:147], v244 offset:3072
	s_waitcnt lgkmcnt(8)
	v_mfma_f32_32x32x16_bf16 v[32:47], v[208:211], v[160:163], v[32:47]
	v_exp_f32_e32 v70, v70
	v_exp_f32_e32 v71, v71
	v_exp_f32_e32 v72, v72
	ds_read_b64_tr_b16 v[148:149], v244 offset:5120
	ds_read_b64_tr_b16 v[150:151], v244 offset:7168
	s_waitcnt lgkmcnt(8)
	v_mfma_f32_32x32x16_bf16 v[32:47], v[212:215], v[164:167], v[32:47]
	v_exp_f32_e32 v73, v73
	v_exp_f32_e32 v74, v74
	v_exp_f32_e32 v75, v75
	ds_read_b64_tr_b16 v[152:153], v244 offset:9216
	ds_read_b64_tr_b16 v[154:155], v244 offset:11264
	s_waitcnt lgkmcnt(8)
	v_mfma_f32_32x32x16_bf16 v[32:47], v[224:227], v[168:171], v[32:47]
	v_exp_f32_e32 v76, v76
	v_exp_f32_e32 v77, v77
	ds_read_b64_tr_b16 v[156:157], v244 offset:13312
	ds_read_b64_tr_b16 v[158:159], v244 offset:15360
	s_waitcnt lgkmcnt(8)
	v_mfma_f32_32x32x16_bf16 v[32:47], v[228:231], v[172:175], v[32:47]
	v_exp_f32_e32 v78, v78
	v_exp_f32_e32 v79, v79
	ds_read_b64_tr_b16 v[160:161], v244 offset:1536
	ds_read_b64_tr_b16 v[162:163], v244 offset:3584
	s_waitcnt lgkmcnt(8)
	v_mfma_f32_32x32x16_bf16 v[16:31], v[208:211], v[144:147], v[16:31]
	v_exp_f32_e32 v80, v80
	v_exp_f32_e32 v81, v81
	ds_read_b64_tr_b16 v[164:165], v244 offset:5632
	ds_read_b64_tr_b16 v[166:167], v244 offset:7680
	s_waitcnt lgkmcnt(8)
	v_mfma_f32_32x32x16_bf16 v[16:31], v[212:215], v[148:151], v[16:31]
	v_exp_f32_e32 v82, v82
	v_exp_f32_e32 v83, v83
	ds_read_b64_tr_b16 v[168:169], v244 offset:9728
	ds_read_b64_tr_b16 v[170:171], v244 offset:11776
	s_waitcnt lgkmcnt(8)
	v_mfma_f32_32x32x16_bf16 v[16:31], v[224:227], v[152:155], v[16:31]
	v_exp_f32_e32 v84, v84
	v_exp_f32_e32 v85, v85
	ds_read_b64_tr_b16 v[172:173], v244 offset:13824
	ds_read_b64_tr_b16 v[174:175], v244 offset:15872
	s_waitcnt lgkmcnt(8)
	v_mfma_f32_32x32x16_bf16 v[16:31], v[228:231], v[156:159], v[16:31]
	v_exp_f32_e32 v86, v86
	v_exp_f32_e32 v87, v87
	v_add_u32_e32 v244, 0x4000, v244
	s_waitcnt lgkmcnt(6)
	v_mfma_f32_32x32x16_bf16 v[0:15], v[208:211], v[160:163], v[0:15]
	v_exp_f32_e32 v88, v88
	v_exp_f32_e32 v89, v89
	s_waitcnt lgkmcnt(4)
	v_mfma_f32_32x32x16_bf16 v[0:15], v[212:215], v[164:167], v[0:15]
	v_exp_f32_e32 v90, v90
	v_exp_f32_e32 v91, v91
	s_waitcnt lgkmcnt(2)
	v_mfma_f32_32x32x16_bf16 v[0:15], v[224:227], v[168:171], v[0:15]
	v_exp_f32_e32 v92, v92
	v_exp_f32_e32 v93, v93
	s_waitcnt lgkmcnt(0)
	v_mfma_f32_32x32x16_bf16 v[0:15], v[228:231], v[172:175], v[0:15]
	v_exp_f32_e32 v94, v94
	v_exp_f32_e32 v95, v95
	s_waitcnt vmcnt(5)
	s_barrier
	ds_read_b128 v[144:147], v240 offset:0
	ds_read_b128 v[148:151], v240 offset:12288
	ds_read_b128 v[152:155], v241 offset:0
	ds_read_b128 v[156:159], v241 offset:12288
	ds_read_b128 v[160:163], v242 offset:0
	ds_read_b128 v[164:167], v242 offset:12288
	v_add_f32_e32 v245, v64, v245
	v_add_f32_e32 v246, v65, v246
	v_add_f32_e32 v245, v66, v245
	v_add_f32_e32 v246, v67, v246
	v_add_f32_e32 v245, v68, v245
	v_add_f32_e32 v246, v69, v246
	v_add_f32_e32 v245, v70, v245
	v_add_f32_e32 v246, v71, v246
	ds_read_b128 v[168:171], v243 offset:0
	s_waitcnt lgkmcnt(6)
	v_mfma_f32_32x32x16_bf16 v[208:223], v[144:147], v[96:99], 0
	v_add_f32_e32 v245, v72, v245
	v_add_f32_e32 v246, v73, v246
	ds_read_b128 v[172:175], v243 offset:12288
	s_waitcnt lgkmcnt(6)
	v_mfma_f32_32x32x16_bf16 v[224:239], v[148:151], v[96:99], 0
	v_add_f32_e32 v245, v74, v245
	v_add_f32_e32 v246, v75, v246
	ds_read_b128 v[144:147], v240 offset:128
	s_waitcnt lgkmcnt(6)
	v_mfma_f32_32x32x16_bf16 v[208:223], v[152:155], v[100:103], v[208:223]
	v_add_f32_e32 v245, v76, v245
	s_add_i32 m0, s60, 0x6000
	s_nop 0
	global_load_lds_dwordx4 v182, s[42:43]
	ds_read_b128 v[148:151], v240 offset:12416
	s_waitcnt lgkmcnt(6)
	v_mfma_f32_32x32x16_bf16 v[224:239], v[156:159], v[100:103], v[224:239]
	v_add_f32_e32 v246, v77, v246
	v_add_f32_e32 v245, v78, v245
	ds_read_b128 v[152:155], v241 offset:128
	s_waitcnt lgkmcnt(6)
	v_mfma_f32_32x32x16_bf16 v[208:223], v[160:163], v[104:107], v[208:223]
	v_add_f32_e32 v246, v79, v246
	v_add_f32_e32 v245, v80, v245
	ds_read_b128 v[156:159], v241 offset:12416
	s_waitcnt lgkmcnt(6)
	v_mfma_f32_32x32x16_bf16 v[224:239], v[164:167], v[104:107], v[224:239]
	v_add_f32_e32 v246, v81, v246
	s_add_i32 m0, s60, 0x6400
	s_nop 0
	global_load_lds_dwordx4 v183, s[42:43]
	ds_read_b128 v[160:163], v242 offset:128
	s_waitcnt lgkmcnt(6)
	v_mfma_f32_32x32x16_bf16 v[208:223], v[168:171], v[108:111], v[208:223]
	v_add_f32_e32 v245, v82, v245
	v_add_f32_e32 v246, v83, v246
	ds_read_b128 v[164:167], v242 offset:12416
	s_waitcnt lgkmcnt(6)
	v_mfma_f32_32x32x16_bf16 v[224:239], v[172:175], v[108:111], v[224:239]
	v_add_f32_e32 v245, v84, v245
	v_add_f32_e32 v246, v85, v246
	ds_read_b128 v[168:171], v243 offset:128
	s_waitcnt lgkmcnt(6)
	v_mfma_f32_32x32x16_bf16 v[208:223], v[144:147], v[112:115], v[208:223]
	v_add_f32_e32 v245, v86, v245
	s_add_i32 m0, s60, 0x6800
	s_nop 0
	global_load_lds_dwordx4 v184, s[42:43]
	ds_read_b128 v[172:175], v243 offset:12416
	s_waitcnt lgkmcnt(6)
	v_mfma_f32_32x32x16_bf16 v[224:239], v[148:151], v[112:115], v[224:239]
	v_add_f32_e32 v246, v87, v246
	v_add_f32_e32 v245, v88, v245
	ds_read_b128 v[144:147], v240 offset:256
	s_waitcnt lgkmcnt(6)
	v_mfma_f32_32x32x16_bf16 v[208:223], v[152:155], v[116:119], v[208:223]
	v_add_f32_e32 v246, v89, v246
	v_add_f32_e32 v245, v90, v245
	ds_read_b128 v[148:151], v240 offset:12544
	s_waitcnt lgkmcnt(6)
	v_mfma_f32_32x32x16_bf16 v[224:239], v[156:159], v[116:119], v[224:239]
	v_add_f32_e32 v246, v91, v246
	s_add_i32 m0, s61, 0x0
	s_nop 0
	global_load_lds_dwordx4 v185, s[46:47]
	ds_read_b128 v[152:155], v241 offset:256
	s_waitcnt lgkmcnt(6)
	v_mfma_f32_32x32x16_bf16 v[208:223], v[160:163], v[120:123], v[208:223]
	v_add_f32_e32 v245, v92, v245
	v_add_f32_e32 v246, v93, v246
	ds_read_b128 v[156:159], v241 offset:12544
	s_waitcnt lgkmcnt(6)
	v_mfma_f32_32x32x16_bf16 v[224:239], v[164:167], v[120:123], v[224:239]
	v_add_f32_e32 v245, v94, v245
	v_add_f32_e32 v246, v95, v246
	ds_read_b128 v[160:163], v242 offset:256
	s_waitcnt lgkmcnt(6)
	v_mfma_f32_32x32x16_bf16 v[208:223], v[168:171], v[124:127], v[208:223]
	v_cvt_pk_bf16_f32 v64, v64, v65
	s_add_i32 m0, s61, 0x400
	s_nop 0
	global_load_lds_dwordx4 v186, s[46:47]
	ds_read_b128 v[164:167], v242 offset:12544
	s_waitcnt lgkmcnt(6)
	v_mfma_f32_32x32x16_bf16 v[224:239], v[172:175], v[124:127], v[224:239]
	v_cvt_pk_bf16_f32 v65, v66, v67
	v_cvt_pk_bf16_f32 v66, v68, v69
	ds_read_b128 v[168:171], v243 offset:256
	s_waitcnt lgkmcnt(6)
	v_mfma_f32_32x32x16_bf16 v[208:223], v[144:147], v[128:131], v[208:223]
	v_cvt_pk_bf16_f32 v67, v70, v71
	v_cvt_pk_bf16_f32 v68, v72, v73
	ds_read_b128 v[172:175], v243 offset:12544
	s_waitcnt lgkmcnt(6)
	v_mfma_f32_32x32x16_bf16 v[224:239], v[148:151], v[128:131], v[224:239]
	v_cvt_pk_bf16_f32 v69, v74, v75
	s_add_u32 s42, s42, 0x6000
	s_addc_u32 s43, s43, 0
	v_add_u32_e32 v240, 0xffff4000, v240
	ds_read_b64_tr_b16 v[144:145], v244 offset:0
	ds_read_b64_tr_b16 v[146:147], v244 offset:2048
	s_waitcnt lgkmcnt(7)
	v_mfma_f32_32x32x16_bf16 v[208:223], v[152:155], v[132:135], v[208:223]
	v_cvt_pk_bf16_f32 v70, v76, v77
	v_cvt_pk_bf16_f32 v71, v78, v79
	v_add_u32_e32 v241, 0xffff4000, v241
	ds_read_b64_tr_b16 v[148:149], v244 offset:4096
	ds_read_b64_tr_b16 v[150:151], v244 offset:6144
	s_waitcnt lgkmcnt(8)
	v_mfma_f32_32x32x16_bf16 v[224:239], v[156:159], v[132:135], v[224:239]
	v_cvt_pk_bf16_f32 v80, v80, v81
	v_cvt_pk_bf16_f32 v81, v82, v83
	v_add_u32_e32 v242, 0xffff4000, v242
	ds_read_b64_tr_b16 v[152:153], v244 offset:8192
	ds_read_b64_tr_b16 v[154:155], v244 offset:10240
	s_waitcnt lgkmcnt(9)
	v_mfma_f32_32x32x16_bf16 v[208:223], v[160:163], v[136:139], v[208:223]
	v_cvt_pk_bf16_f32 v82, v84, v85
	s_add_u32 s46, s46, 0x40000
	s_addc_u32 s47, s47, 0
	v_add_u32_e32 v243, 0xffff4000, v243
	ds_read_b64_tr_b16 v[156:157], v244 offset:12288
	ds_read_b64_tr_b16 v[158:159], v244 offset:14336
	s_waitcnt lgkmcnt(10)
	v_mfma_f32_32x32x16_bf16 v[224:239], v[164:167], v[136:139], v[224:239]
	v_cvt_pk_bf16_f32 v83, v86, v87
	v_cvt_pk_bf16_f32 v84, v88, v89
	ds_read_b64_tr_b16 v[160:161], v244 offset:512
	ds_read_b64_tr_b16 v[162:163], v244 offset:2560
	s_waitcnt lgkmcnt(11)
	v_mfma_f32_32x32x16_bf16 v[208:223], v[168:171], v[140:143], v[208:223]
	v_cvt_pk_bf16_f32 v85, v90, v91
	v_cvt_pk_bf16_f32 v86, v92, v93
	ds_read_b64_tr_b16 v[164:165], v244 offset:4608
	ds_read_b64_tr_b16 v[166:167], v244 offset:6656
	s_waitcnt lgkmcnt(12)
	v_mfma_f32_32x32x16_bf16 v[224:239], v[172:175], v[140:143], v[224:239]
	v_cvt_pk_bf16_f32 v87, v94, v95
	s_waitcnt lgkmcnt(10)
	v_mfma_f32_32x32x16_bf16 v[48:63], v[64:67], v[144:147], v[48:63]
	s_waitcnt lgkmcnt(8)
	v_mfma_f32_32x32x16_bf16 v[48:63], v[68:71], v[148:151], v[48:63]
	ds_read_b64_tr_b16 v[168:169], v244 offset:8704
	ds_read_b64_tr_b16 v[170:171], v244 offset:10752
	s_waitcnt lgkmcnt(8)
	v_mfma_f32_32x32x16_bf16 v[48:63], v[80:83], v[152:155], v[48:63]
	v_exp_f32_e32 v208, v208
	v_exp_f32_e32 v209, v209
	v_exp_f32_e32 v210, v210
	ds_read_b64_tr_b16 v[172:173], v244 offset:12800
	ds_read_b64_tr_b16 v[174:175], v244 offset:14848
	s_waitcnt lgkmcnt(8)
	v_mfma_f32_32x32x16_bf16 v[48:63], v[84:87], v[156:159], v[48:63]
	v_exp_f32_e32 v211, v211
	v_exp_f32_e32 v212, v212
	v_exp_f32_e32 v213, v213
	ds_read_b64_tr_b16 v[144:145], v244 offset:1024
	ds_read_b64_tr_b16 v[146:147], v244 offset:3072
	s_waitcnt lgkmcnt(8)
	v_mfma_f32_32x32x16_bf16 v[32:47], v[64:67], v[160:163], v[32:47]
	v_exp_f32_e32 v214, v214
	v_exp_f32_e32 v215, v215
	v_exp_f32_e32 v216, v216
	ds_read_b64_tr_b16 v[148:149], v244 offset:5120
	ds_read_b64_tr_b16 v[150:151], v244 offset:7168
	s_waitcnt lgkmcnt(8)
	v_mfma_f32_32x32x16_bf16 v[32:47], v[68:71], v[164:167], v[32:47]
	v_exp_f32_e32 v217, v217
	v_exp_f32_e32 v218, v218
	v_exp_f32_e32 v219, v219
	ds_read_b64_tr_b16 v[152:153], v244 offset:9216
	ds_read_b64_tr_b16 v[154:155], v244 offset:11264
	s_waitcnt lgkmcnt(8)
	v_mfma_f32_32x32x16_bf16 v[32:47], v[80:83], v[168:171], v[32:47]
	v_exp_f32_e32 v220, v220
	v_exp_f32_e32 v221, v221
	ds_read_b64_tr_b16 v[156:157], v244 offset:13312
	ds_read_b64_tr_b16 v[158:159], v244 offset:15360
	s_waitcnt lgkmcnt(8)
	v_mfma_f32_32x32x16_bf16 v[32:47], v[84:87], v[172:175], v[32:47]
	v_exp_f32_e32 v222, v222
	v_exp_f32_e32 v223, v223
	ds_read_b64_tr_b16 v[160:161], v244 offset:1536
	ds_read_b64_tr_b16 v[162:163], v244 offset:3584
	s_waitcnt lgkmcnt(8)
	v_mfma_f32_32x32x16_bf16 v[16:31], v[64:67], v[144:147], v[16:31]
	v_exp_f32_e32 v224, v224
	v_exp_f32_e32 v225, v225
	ds_read_b64_tr_b16 v[164:165], v244 offset:5632
	ds_read_b64_tr_b16 v[166:167], v244 offset:7680
	s_waitcnt lgkmcnt(8)
	v_mfma_f32_32x32x16_bf16 v[16:31], v[68:71], v[148:151], v[16:31]
	v_exp_f32_e32 v226, v226
	v_exp_f32_e32 v227, v227
	ds_read_b64_tr_b16 v[168:169], v244 offset:9728
	ds_read_b64_tr_b16 v[170:171], v244 offset:11776
	s_waitcnt lgkmcnt(8)
	v_mfma_f32_32x32x16_bf16 v[16:31], v[80:83], v[152:155], v[16:31]
	v_exp_f32_e32 v228, v228
	v_exp_f32_e32 v229, v229
	ds_read_b64_tr_b16 v[172:173], v244 offset:13824
	ds_read_b64_tr_b16 v[174:175], v244 offset:15872
	s_waitcnt lgkmcnt(8)
	v_mfma_f32_32x32x16_bf16 v[16:31], v[84:87], v[156:159], v[16:31]
	v_exp_f32_e32 v230, v230
	v_exp_f32_e32 v231, v231
	v_add_u32_e32 v244, 0x4000, v244
	s_waitcnt lgkmcnt(6)
	v_mfma_f32_32x32x16_bf16 v[0:15], v[64:67], v[160:163], v[0:15]
	v_exp_f32_e32 v232, v232
	v_exp_f32_e32 v233, v233
	s_waitcnt lgkmcnt(4)
	v_mfma_f32_32x32x16_bf16 v[0:15], v[68:71], v[164:167], v[0:15]
	v_exp_f32_e32 v234, v234
	v_exp_f32_e32 v235, v235
	s_waitcnt lgkmcnt(2)
	v_mfma_f32_32x32x16_bf16 v[0:15], v[80:83], v[168:171], v[0:15]
	v_exp_f32_e32 v236, v236
	v_exp_f32_e32 v237, v237
	s_waitcnt lgkmcnt(0)
	v_mfma_f32_32x32x16_bf16 v[0:15], v[84:87], v[172:175], v[0:15]
	v_exp_f32_e32 v238, v238
	v_exp_f32_e32 v239, v239
	s_waitcnt vmcnt(5)
	s_barrier
	ds_read_b128 v[144:147], v240 offset:0
	ds_read_b128 v[148:151], v240 offset:12288
	ds_read_b128 v[152:155], v241 offset:0
	ds_read_b128 v[156:159], v241 offset:12288
	ds_read_b128 v[160:163], v242 offset:0
	ds_read_b128 v[164:167], v242 offset:12288
	v_add_f32_e32 v245, v208, v245
	v_add_f32_e32 v246, v209, v246
	v_add_f32_e32 v245, v210, v245
	v_add_f32_e32 v246, v211, v246
	v_add_f32_e32 v245, v212, v245
	v_add_f32_e32 v246, v213, v246
	v_add_f32_e32 v245, v214, v245
	v_add_f32_e32 v246, v215, v246
	ds_read_b128 v[168:171], v243 offset:0
	s_waitcnt lgkmcnt(6)
	v_mfma_f32_32x32x16_bf16 v[64:79], v[144:147], v[96:99], 0
	v_add_f32_e32 v245, v216, v245
	v_add_f32_e32 v246, v217, v246
	ds_read_b128 v[172:175], v243 offset:12288
	s_waitcnt lgkmcnt(6)
	v_mfma_f32_32x32x16_bf16 v[80:95], v[148:151], v[96:99], 0
	v_add_f32_e32 v245, v218, v245
	v_add_f32_e32 v246, v219, v246
	ds_read_b128 v[144:147], v240 offset:128
	s_waitcnt lgkmcnt(6)
	v_mfma_f32_32x32x16_bf16 v[64:79], v[152:155], v[100:103], v[64:79]
	v_add_f32_e32 v245, v220, v245
	s_add_i32 m0, s60, 0xc000
	s_nop 0
	global_load_lds_dwordx4 v182, s[42:43]
	ds_read_b128 v[148:151], v240 offset:12416
	s_waitcnt lgkmcnt(6)
	v_mfma_f32_32x32x16_bf16 v[80:95], v[156:159], v[100:103], v[80:95]
	v_add_f32_e32 v246, v221, v246
	v_add_f32_e32 v245, v222, v245
	ds_read_b128 v[152:155], v241 offset:128
	s_waitcnt lgkmcnt(6)
	v_mfma_f32_32x32x16_bf16 v[64:79], v[160:163], v[104:107], v[64:79]
	v_add_f32_e32 v246, v223, v246
	v_add_f32_e32 v245, v224, v245
	ds_read_b128 v[156:159], v241 offset:12416
	s_waitcnt lgkmcnt(6)
	v_mfma_f32_32x32x16_bf16 v[80:95], v[164:167], v[104:107], v[80:95]
	v_add_f32_e32 v246, v225, v246
	s_add_i32 m0, s60, 0xc400
	s_nop 0
	global_load_lds_dwordx4 v183, s[42:43]
	ds_read_b128 v[160:163], v242 offset:128
	s_waitcnt lgkmcnt(6)
	v_mfma_f32_32x32x16_bf16 v[64:79], v[168:171], v[108:111], v[64:79]
	v_add_f32_e32 v245, v226, v245
	v_add_f32_e32 v246, v227, v246
	ds_read_b128 v[164:167], v242 offset:12416
	s_waitcnt lgkmcnt(6)
	v_mfma_f32_32x32x16_bf16 v[80:95], v[172:175], v[108:111], v[80:95]
	v_add_f32_e32 v245, v228, v245
	v_add_f32_e32 v246, v229, v246
	ds_read_b128 v[168:171], v243 offset:128
	s_waitcnt lgkmcnt(6)
	v_mfma_f32_32x32x16_bf16 v[64:79], v[144:147], v[112:115], v[64:79]
	v_add_f32_e32 v245, v230, v245
	s_add_i32 m0, s60, 0xc800
	s_nop 0
	global_load_lds_dwordx4 v184, s[42:43]
	ds_read_b128 v[172:175], v243 offset:12416
	s_waitcnt lgkmcnt(6)
	v_mfma_f32_32x32x16_bf16 v[80:95], v[148:151], v[112:115], v[80:95]
	v_add_f32_e32 v246, v231, v246
	v_add_f32_e32 v245, v232, v245
	ds_read_b128 v[144:147], v240 offset:256
	s_waitcnt lgkmcnt(6)
	v_mfma_f32_32x32x16_bf16 v[64:79], v[152:155], v[116:119], v[64:79]
	v_add_f32_e32 v246, v233, v246
	v_add_f32_e32 v245, v234, v245
	ds_read_b128 v[148:151], v240 offset:12544
	s_waitcnt lgkmcnt(6)
	v_mfma_f32_32x32x16_bf16 v[80:95], v[156:159], v[116:119], v[80:95]
	v_add_f32_e32 v246, v235, v246
	s_add_i32 m0, s61, 0x4000
	s_nop 0
	global_load_lds_dwordx4 v185, s[46:47]
	ds_read_b128 v[152:155], v241 offset:256
	s_waitcnt lgkmcnt(6)
	v_mfma_f32_32x32x16_bf16 v[64:79], v[160:163], v[120:123], v[64:79]
	v_add_f32_e32 v245, v236, v245
	v_add_f32_e32 v246, v237, v246
	ds_read_b128 v[156:159], v241 offset:12544
	s_waitcnt lgkmcnt(6)
	v_mfma_f32_32x32x16_bf16 v[80:95], v[164:167], v[120:123], v[80:95]
	v_add_f32_e32 v245, v238, v245
	v_add_f32_e32 v246, v239, v246
	ds_read_b128 v[160:163], v242 offset:256
	s_waitcnt lgkmcnt(6)
	v_mfma_f32_32x32x16_bf16 v[64:79], v[168:171], v[124:127], v[64:79]
	v_cvt_pk_bf16_f32 v208, v208, v209
	s_add_i32 m0, s61, 0x4400
	s_nop 0
	global_load_lds_dwordx4 v186, s[46:47]
	ds_read_b128 v[164:167], v242 offset:12544
	s_waitcnt lgkmcnt(6)
	v_mfma_f32_32x32x16_bf16 v[80:95], v[172:175], v[124:127], v[80:95]
	v_cvt_pk_bf16_f32 v209, v210, v211
	v_cvt_pk_bf16_f32 v210, v212, v213
	ds_read_b128 v[168:171], v243 offset:256
	s_waitcnt lgkmcnt(6)
	v_mfma_f32_32x32x16_bf16 v[64:79], v[144:147], v[128:131], v[64:79]
	v_cvt_pk_bf16_f32 v211, v214, v215
	v_cvt_pk_bf16_f32 v212, v216, v217
	ds_read_b128 v[172:175], v243 offset:12544
	s_waitcnt lgkmcnt(6)
	v_mfma_f32_32x32x16_bf16 v[80:95], v[148:151], v[128:131], v[80:95]
	v_cvt_pk_bf16_f32 v213, v218, v219
	s_add_u32 s42, s42, 0x6000
	s_addc_u32 s43, s43, 0
	v_add_u32_e32 v240, 0x6000, v240
	ds_read_b64_tr_b16 v[144:145], v244 offset:0
	ds_read_b64_tr_b16 v[146:147], v244 offset:2048
	s_waitcnt lgkmcnt(7)
	v_mfma_f32_32x32x16_bf16 v[64:79], v[152:155], v[132:135], v[64:79]
	v_cvt_pk_bf16_f32 v214, v220, v221
	v_cvt_pk_bf16_f32 v215, v222, v223
	v_add_u32_e32 v241, 0x6000, v241
	ds_read_b64_tr_b16 v[148:149], v244 offset:4096
	ds_read_b64_tr_b16 v[150:151], v244 offset:6144
	s_waitcnt lgkmcnt(8)
	v_mfma_f32_32x32x16_bf16 v[80:95], v[156:159], v[132:135], v[80:95]
	v_cvt_pk_bf16_f32 v224, v224, v225
	v_cvt_pk_bf16_f32 v225, v226, v227
	v_add_u32_e32 v242, 0x6000, v242
	ds_read_b64_tr_b16 v[152:153], v244 offset:8192
	ds_read_b64_tr_b16 v[154:155], v244 offset:10240
	s_waitcnt lgkmcnt(9)
	v_mfma_f32_32x32x16_bf16 v[64:79], v[160:163], v[136:139], v[64:79]
	v_cvt_pk_bf16_f32 v226, v228, v229
	s_add_u32 s46, s46, 0x40000
	s_addc_u32 s47, s47, 0
	v_add_u32_e32 v243, 0x6000, v243
	ds_read_b64_tr_b16 v[156:157], v244 offset:12288
	ds_read_b64_tr_b16 v[158:159], v244 offset:14336
	s_waitcnt lgkmcnt(10)
	v_mfma_f32_32x32x16_bf16 v[80:95], v[164:167], v[136:139], v[80:95]
	v_cvt_pk_bf16_f32 v227, v230, v231
	v_cvt_pk_bf16_f32 v228, v232, v233
	ds_read_b64_tr_b16 v[160:161], v244 offset:512
	ds_read_b64_tr_b16 v[162:163], v244 offset:2560
	s_waitcnt lgkmcnt(11)
	v_mfma_f32_32x32x16_bf16 v[64:79], v[168:171], v[140:143], v[64:79]
	v_cvt_pk_bf16_f32 v229, v234, v235
	v_cvt_pk_bf16_f32 v230, v236, v237
	ds_read_b64_tr_b16 v[164:165], v244 offset:4608
	ds_read_b64_tr_b16 v[166:167], v244 offset:6656
	s_waitcnt lgkmcnt(12)
	v_mfma_f32_32x32x16_bf16 v[80:95], v[172:175], v[140:143], v[80:95]
	v_cvt_pk_bf16_f32 v231, v238, v239
	s_waitcnt lgkmcnt(10)
	v_mfma_f32_32x32x16_bf16 v[48:63], v[208:211], v[144:147], v[48:63]
	s_waitcnt lgkmcnt(8)
	v_mfma_f32_32x32x16_bf16 v[48:63], v[212:215], v[148:151], v[48:63]
	ds_read_b64_tr_b16 v[168:169], v244 offset:8704
	ds_read_b64_tr_b16 v[170:171], v244 offset:10752
	s_waitcnt lgkmcnt(8)
	v_mfma_f32_32x32x16_bf16 v[48:63], v[224:227], v[152:155], v[48:63]
	v_exp_f32_e32 v64, v64
	v_exp_f32_e32 v65, v65
	v_exp_f32_e32 v66, v66
	ds_read_b64_tr_b16 v[172:173], v244 offset:12800
	ds_read_b64_tr_b16 v[174:175], v244 offset:14848
	s_waitcnt lgkmcnt(8)
	v_mfma_f32_32x32x16_bf16 v[48:63], v[228:231], v[156:159], v[48:63]
	v_exp_f32_e32 v67, v67
	v_exp_f32_e32 v68, v68
	v_exp_f32_e32 v69, v69
	ds_read_b64_tr_b16 v[144:145], v244 offset:1024
	ds_read_b64_tr_b16 v[146:147], v244 offset:3072
	s_waitcnt lgkmcnt(8)
	v_mfma_f32_32x32x16_bf16 v[32:47], v[208:211], v[160:163], v[32:47]
	v_exp_f32_e32 v70, v70
	v_exp_f32_e32 v71, v71
	v_exp_f32_e32 v72, v72
	ds_read_b64_tr_b16 v[148:149], v244 offset:5120
	ds_read_b64_tr_b16 v[150:151], v244 offset:7168
	s_waitcnt lgkmcnt(8)
	v_mfma_f32_32x32x16_bf16 v[32:47], v[212:215], v[164:167], v[32:47]
	v_exp_f32_e32 v73, v73
	v_exp_f32_e32 v74, v74
	v_exp_f32_e32 v75, v75
	ds_read_b64_tr_b16 v[152:153], v244 offset:9216
	ds_read_b64_tr_b16 v[154:155], v244 offset:11264
	s_waitcnt lgkmcnt(8)
	v_mfma_f32_32x32x16_bf16 v[32:47], v[224:227], v[168:171], v[32:47]
	v_exp_f32_e32 v76, v76
	v_exp_f32_e32 v77, v77
	ds_read_b64_tr_b16 v[156:157], v244 offset:13312
	ds_read_b64_tr_b16 v[158:159], v244 offset:15360
	s_waitcnt lgkmcnt(8)
	v_mfma_f32_32x32x16_bf16 v[32:47], v[228:231], v[172:175], v[32:47]
	v_exp_f32_e32 v78, v78
	v_exp_f32_e32 v79, v79
	ds_read_b64_tr_b16 v[160:161], v244 offset:1536
	ds_read_b64_tr_b16 v[162:163], v244 offset:3584
	s_waitcnt lgkmcnt(8)
	v_mfma_f32_32x32x16_bf16 v[16:31], v[208:211], v[144:147], v[16:31]
	v_exp_f32_e32 v80, v80
	v_exp_f32_e32 v81, v81
	ds_read_b64_tr_b16 v[164:165], v244 offset:5632
	ds_read_b64_tr_b16 v[166:167], v244 offset:7680
	s_waitcnt lgkmcnt(8)
	v_mfma_f32_32x32x16_bf16 v[16:31], v[212:215], v[148:151], v[16:31]
	v_exp_f32_e32 v82, v82
	v_exp_f32_e32 v83, v83
	ds_read_b64_tr_b16 v[168:169], v244 offset:9728
	ds_read_b64_tr_b16 v[170:171], v244 offset:11776
	s_waitcnt lgkmcnt(8)
	v_mfma_f32_32x32x16_bf16 v[16:31], v[224:227], v[152:155], v[16:31]
	v_exp_f32_e32 v84, v84
	v_exp_f32_e32 v85, v85
	ds_read_b64_tr_b16 v[172:173], v244 offset:13824
	ds_read_b64_tr_b16 v[174:175], v244 offset:15872
	s_waitcnt lgkmcnt(8)
	v_mfma_f32_32x32x16_bf16 v[16:31], v[228:231], v[156:159], v[16:31]
	v_exp_f32_e32 v86, v86
	v_exp_f32_e32 v87, v87
	v_add_u32_e32 v244, 0xffff8000, v244
	s_waitcnt lgkmcnt(6)
	v_mfma_f32_32x32x16_bf16 v[0:15], v[208:211], v[160:163], v[0:15]
	v_exp_f32_e32 v88, v88
	v_exp_f32_e32 v89, v89
	s_waitcnt lgkmcnt(4)
	v_mfma_f32_32x32x16_bf16 v[0:15], v[212:215], v[164:167], v[0:15]
	v_exp_f32_e32 v90, v90
	v_exp_f32_e32 v91, v91
	s_waitcnt lgkmcnt(2)
	v_mfma_f32_32x32x16_bf16 v[0:15], v[224:227], v[168:171], v[0:15]
	v_exp_f32_e32 v92, v92
	v_exp_f32_e32 v93, v93
	s_waitcnt lgkmcnt(0)
	v_mfma_f32_32x32x16_bf16 v[0:15], v[228:231], v[172:175], v[0:15]
	v_exp_f32_e32 v94, v94
	v_exp_f32_e32 v95, v95
	s_waitcnt vmcnt(5)
	s_barrier
	ds_read_b128 v[144:147], v240 offset:0
	ds_read_b128 v[148:151], v240 offset:12288
	ds_read_b128 v[152:155], v241 offset:0
	ds_read_b128 v[156:159], v241 offset:12288
	ds_read_b128 v[160:163], v242 offset:0
	ds_read_b128 v[164:167], v242 offset:12288
	v_add_f32_e32 v245, v64, v245
	v_add_f32_e32 v246, v65, v246
	v_add_f32_e32 v245, v66, v245
	v_add_f32_e32 v246, v67, v246
	v_add_f32_e32 v245, v68, v245
	v_add_f32_e32 v246, v69, v246
	v_add_f32_e32 v245, v70, v245
	v_add_f32_e32 v246, v71, v246
	ds_read_b128 v[168:171], v243 offset:0
	s_waitcnt lgkmcnt(6)
	v_mfma_f32_32x32x16_bf16 v[208:223], v[144:147], v[96:99], 0
	v_add_f32_e32 v245, v72, v245
	v_add_f32_e32 v246, v73, v246
	ds_read_b128 v[172:175], v243 offset:12288
	s_waitcnt lgkmcnt(6)
	v_mfma_f32_32x32x16_bf16 v[224:239], v[148:151], v[96:99], 0
	v_add_f32_e32 v245, v74, v245
	v_add_f32_e32 v246, v75, v246
	ds_read_b128 v[144:147], v240 offset:128
	s_waitcnt lgkmcnt(6)
	v_mfma_f32_32x32x16_bf16 v[208:223], v[152:155], v[100:103], v[208:223]
	v_add_f32_e32 v245, v76, v245
	s_add_i32 m0, s60, 0x0
	s_nop 0
	global_load_lds_dwordx4 v182, s[42:43]
	ds_read_b128 v[148:151], v240 offset:12416
	s_waitcnt lgkmcnt(6)
	v_mfma_f32_32x32x16_bf16 v[224:239], v[156:159], v[100:103], v[224:239]
	v_add_f32_e32 v246, v77, v246
	v_add_f32_e32 v245, v78, v245
	ds_read_b128 v[152:155], v241 offset:128
	s_waitcnt lgkmcnt(6)
	v_mfma_f32_32x32x16_bf16 v[208:223], v[160:163], v[104:107], v[208:223]
	v_add_f32_e32 v246, v79, v246
	v_add_f32_e32 v245, v80, v245
	ds_read_b128 v[156:159], v241 offset:12416
	s_waitcnt lgkmcnt(6)
	v_mfma_f32_32x32x16_bf16 v[224:239], v[164:167], v[104:107], v[224:239]
	v_add_f32_e32 v246, v81, v246
	s_add_i32 m0, s60, 0x400
	s_nop 0
	global_load_lds_dwordx4 v183, s[42:43]
	ds_read_b128 v[160:163], v242 offset:128
	s_waitcnt lgkmcnt(6)
	v_mfma_f32_32x32x16_bf16 v[208:223], v[168:171], v[108:111], v[208:223]
	v_add_f32_e32 v245, v82, v245
	v_add_f32_e32 v246, v83, v246
	ds_read_b128 v[164:167], v242 offset:12416
	s_waitcnt lgkmcnt(6)
	v_mfma_f32_32x32x16_bf16 v[224:239], v[172:175], v[108:111], v[224:239]
	v_add_f32_e32 v245, v84, v245
	v_add_f32_e32 v246, v85, v246
	ds_read_b128 v[168:171], v243 offset:128
	s_waitcnt lgkmcnt(6)
	v_mfma_f32_32x32x16_bf16 v[208:223], v[144:147], v[112:115], v[208:223]
	v_add_f32_e32 v245, v86, v245
	s_add_i32 m0, s60, 0x800
	s_nop 0
	global_load_lds_dwordx4 v184, s[42:43]
	ds_read_b128 v[172:175], v243 offset:12416
	s_waitcnt lgkmcnt(6)
	v_mfma_f32_32x32x16_bf16 v[224:239], v[148:151], v[112:115], v[224:239]
	v_add_f32_e32 v246, v87, v246
	v_add_f32_e32 v245, v88, v245
	ds_read_b128 v[144:147], v240 offset:256
	s_waitcnt lgkmcnt(6)
	v_mfma_f32_32x32x16_bf16 v[208:223], v[152:155], v[116:119], v[208:223]
	v_add_f32_e32 v246, v89, v246
	v_add_f32_e32 v245, v90, v245
	ds_read_b128 v[148:151], v240 offset:12544
	s_waitcnt lgkmcnt(6)
	v_mfma_f32_32x32x16_bf16 v[224:239], v[156:159], v[116:119], v[224:239]
	v_add_f32_e32 v246, v91, v246
	s_add_i32 m0, s61, 0x8000
	s_nop 0
	global_load_lds_dwordx4 v185, s[46:47]
	ds_read_b128 v[152:155], v241 offset:256
	s_waitcnt lgkmcnt(6)
	v_mfma_f32_32x32x16_bf16 v[208:223], v[160:163], v[120:123], v[208:223]
	v_add_f32_e32 v245, v92, v245
	v_add_f32_e32 v246, v93, v246
	ds_read_b128 v[156:159], v241 offset:12544
	s_waitcnt lgkmcnt(6)
	v_mfma_f32_32x32x16_bf16 v[224:239], v[164:167], v[120:123], v[224:239]
	v_add_f32_e32 v245, v94, v245
	v_add_f32_e32 v246, v95, v246
	ds_read_b128 v[160:163], v242 offset:256
	s_waitcnt lgkmcnt(6)
	v_mfma_f32_32x32x16_bf16 v[208:223], v[168:171], v[124:127], v[208:223]
	v_cvt_pk_bf16_f32 v64, v64, v65
	s_add_i32 m0, s61, 0x8400
	s_nop 0
	global_load_lds_dwordx4 v186, s[46:47]
	ds_read_b128 v[164:167], v242 offset:12544
	s_waitcnt lgkmcnt(6)
	v_mfma_f32_32x32x16_bf16 v[224:239], v[172:175], v[124:127], v[224:239]
	v_cvt_pk_bf16_f32 v65, v66, v67
	v_cvt_pk_bf16_f32 v66, v68, v69
	ds_read_b128 v[168:171], v243 offset:256
	s_waitcnt lgkmcnt(6)
	v_mfma_f32_32x32x16_bf16 v[208:223], v[144:147], v[128:131], v[208:223]
	v_cvt_pk_bf16_f32 v67, v70, v71
	v_cvt_pk_bf16_f32 v68, v72, v73
	ds_read_b128 v[172:175], v243 offset:12544
	s_waitcnt lgkmcnt(6)
	v_mfma_f32_32x32x16_bf16 v[224:239], v[148:151], v[128:131], v[224:239]
	v_cvt_pk_bf16_f32 v69, v74, v75
	s_add_u32 s42, s42, 0x6000
	s_addc_u32 s43, s43, 0
	v_add_u32_e32 v240, 0x6000, v240
	ds_read_b64_tr_b16 v[144:145], v244 offset:0
	ds_read_b64_tr_b16 v[146:147], v244 offset:2048
	s_waitcnt lgkmcnt(7)
	v_mfma_f32_32x32x16_bf16 v[208:223], v[152:155], v[132:135], v[208:223]
	v_cvt_pk_bf16_f32 v70, v76, v77
	v_cvt_pk_bf16_f32 v71, v78, v79
	v_add_u32_e32 v241, 0x6000, v241
	ds_read_b64_tr_b16 v[148:149], v244 offset:4096
	ds_read_b64_tr_b16 v[150:151], v244 offset:6144
	s_waitcnt lgkmcnt(8)
	v_mfma_f32_32x32x16_bf16 v[224:239], v[156:159], v[132:135], v[224:239]
	v_cvt_pk_bf16_f32 v80, v80, v81
	v_cvt_pk_bf16_f32 v81, v82, v83
	v_add_u32_e32 v242, 0x6000, v242
	ds_read_b64_tr_b16 v[152:153], v244 offset:8192
	ds_read_b64_tr_b16 v[154:155], v244 offset:10240
	s_waitcnt lgkmcnt(9)
	v_mfma_f32_32x32x16_bf16 v[208:223], v[160:163], v[136:139], v[208:223]
	v_cvt_pk_bf16_f32 v82, v84, v85
	s_add_u32 s46, s46, 0x40000
	s_addc_u32 s47, s47, 0
	v_add_u32_e32 v243, 0x6000, v243
	ds_read_b64_tr_b16 v[156:157], v244 offset:12288
	ds_read_b64_tr_b16 v[158:159], v244 offset:14336
	s_waitcnt lgkmcnt(10)
	v_mfma_f32_32x32x16_bf16 v[224:239], v[164:167], v[136:139], v[224:239]
	v_cvt_pk_bf16_f32 v83, v86, v87
	v_cvt_pk_bf16_f32 v84, v88, v89
	ds_read_b64_tr_b16 v[160:161], v244 offset:512
	ds_read_b64_tr_b16 v[162:163], v244 offset:2560
	s_waitcnt lgkmcnt(11)
	v_mfma_f32_32x32x16_bf16 v[208:223], v[168:171], v[140:143], v[208:223]
	v_cvt_pk_bf16_f32 v85, v90, v91
	v_cvt_pk_bf16_f32 v86, v92, v93
	ds_read_b64_tr_b16 v[164:165], v244 offset:4608
	ds_read_b64_tr_b16 v[166:167], v244 offset:6656
	s_waitcnt lgkmcnt(12)
	v_mfma_f32_32x32x16_bf16 v[224:239], v[172:175], v[140:143], v[224:239]
	v_cvt_pk_bf16_f32 v87, v94, v95
	s_waitcnt lgkmcnt(10)
	v_mfma_f32_32x32x16_bf16 v[48:63], v[64:67], v[144:147], v[48:63]
	s_waitcnt lgkmcnt(8)
	v_mfma_f32_32x32x16_bf16 v[48:63], v[68:71], v[148:151], v[48:63]
	ds_read_b64_tr_b16 v[168:169], v244 offset:8704
	ds_read_b64_tr_b16 v[170:171], v244 offset:10752
	s_waitcnt lgkmcnt(8)
	v_mfma_f32_32x32x16_bf16 v[48:63], v[80:83], v[152:155], v[48:63]
	v_exp_f32_e32 v208, v208
	v_exp_f32_e32 v209, v209
	v_exp_f32_e32 v210, v210
	ds_read_b64_tr_b16 v[172:173], v244 offset:12800
	ds_read_b64_tr_b16 v[174:175], v244 offset:14848
	s_waitcnt lgkmcnt(8)
	v_mfma_f32_32x32x16_bf16 v[48:63], v[84:87], v[156:159], v[48:63]
	v_exp_f32_e32 v211, v211
	v_exp_f32_e32 v212, v212
	v_exp_f32_e32 v213, v213
	ds_read_b64_tr_b16 v[144:145], v244 offset:1024
	ds_read_b64_tr_b16 v[146:147], v244 offset:3072
	s_waitcnt lgkmcnt(8)
	v_mfma_f32_32x32x16_bf16 v[32:47], v[64:67], v[160:163], v[32:47]
	v_exp_f32_e32 v214, v214
	v_exp_f32_e32 v215, v215
	v_exp_f32_e32 v216, v216
	ds_read_b64_tr_b16 v[148:149], v244 offset:5120
	ds_read_b64_tr_b16 v[150:151], v244 offset:7168
	s_waitcnt lgkmcnt(8)
	v_mfma_f32_32x32x16_bf16 v[32:47], v[68:71], v[164:167], v[32:47]
	v_exp_f32_e32 v217, v217
	v_exp_f32_e32 v218, v218
	v_exp_f32_e32 v219, v219
	ds_read_b64_tr_b16 v[152:153], v244 offset:9216
	ds_read_b64_tr_b16 v[154:155], v244 offset:11264
	s_waitcnt lgkmcnt(8)
	v_mfma_f32_32x32x16_bf16 v[32:47], v[80:83], v[168:171], v[32:47]
	v_exp_f32_e32 v220, v220
	v_exp_f32_e32 v221, v221
	ds_read_b64_tr_b16 v[156:157], v244 offset:13312
	ds_read_b64_tr_b16 v[158:159], v244 offset:15360
	s_waitcnt lgkmcnt(8)
	v_mfma_f32_32x32x16_bf16 v[32:47], v[84:87], v[172:175], v[32:47]
	v_exp_f32_e32 v222, v222
	v_exp_f32_e32 v223, v223
	ds_read_b64_tr_b16 v[160:161], v244 offset:1536
	ds_read_b64_tr_b16 v[162:163], v244 offset:3584
	s_waitcnt lgkmcnt(8)
	v_mfma_f32_32x32x16_bf16 v[16:31], v[64:67], v[144:147], v[16:31]
	v_exp_f32_e32 v224, v224
	v_exp_f32_e32 v225, v225
	ds_read_b64_tr_b16 v[164:165], v244 offset:5632
	ds_read_b64_tr_b16 v[166:167], v244 offset:7680
	s_waitcnt lgkmcnt(8)
	v_mfma_f32_32x32x16_bf16 v[16:31], v[68:71], v[148:151], v[16:31]
	v_exp_f32_e32 v226, v226
	v_exp_f32_e32 v227, v227
	ds_read_b64_tr_b16 v[168:169], v244 offset:9728
	ds_read_b64_tr_b16 v[170:171], v244 offset:11776
	s_waitcnt lgkmcnt(8)
	v_mfma_f32_32x32x16_bf16 v[16:31], v[80:83], v[152:155], v[16:31]
	v_exp_f32_e32 v228, v228
	v_exp_f32_e32 v229, v229
	ds_read_b64_tr_b16 v[172:173], v244 offset:13824
	ds_read_b64_tr_b16 v[174:175], v244 offset:15872
	s_waitcnt lgkmcnt(8)
	v_mfma_f32_32x32x16_bf16 v[16:31], v[84:87], v[156:159], v[16:31]
	v_exp_f32_e32 v230, v230
	v_exp_f32_e32 v231, v231
	v_add_u32_e32 v244, 0x4000, v244
	s_waitcnt lgkmcnt(6)
	v_mfma_f32_32x32x16_bf16 v[0:15], v[64:67], v[160:163], v[0:15]
	v_exp_f32_e32 v232, v232
	v_exp_f32_e32 v233, v233
	s_waitcnt lgkmcnt(4)
	v_mfma_f32_32x32x16_bf16 v[0:15], v[68:71], v[164:167], v[0:15]
	v_exp_f32_e32 v234, v234
	v_exp_f32_e32 v235, v235
	s_waitcnt lgkmcnt(2)
	v_mfma_f32_32x32x16_bf16 v[0:15], v[80:83], v[168:171], v[0:15]
	v_exp_f32_e32 v236, v236
	v_exp_f32_e32 v237, v237
	s_waitcnt lgkmcnt(0)
	v_mfma_f32_32x32x16_bf16 v[0:15], v[84:87], v[172:175], v[0:15]
	v_exp_f32_e32 v238, v238
	v_exp_f32_e32 v239, v239
	s_waitcnt vmcnt(5)
	s_barrier
	ds_read_b128 v[144:147], v240 offset:0
	ds_read_b128 v[148:151], v240 offset:12288
	ds_read_b128 v[152:155], v241 offset:0
	ds_read_b128 v[156:159], v241 offset:12288
	ds_read_b128 v[160:163], v242 offset:0
	ds_read_b128 v[164:167], v242 offset:12288
	v_add_f32_e32 v245, v208, v245
	v_add_f32_e32 v246, v209, v246
	v_add_f32_e32 v245, v210, v245
	v_add_f32_e32 v246, v211, v246
	v_add_f32_e32 v245, v212, v245
	v_add_f32_e32 v246, v213, v246
	v_add_f32_e32 v245, v214, v245
	v_add_f32_e32 v246, v215, v246
	ds_read_b128 v[168:171], v243 offset:0
	s_waitcnt lgkmcnt(6)
	v_mfma_f32_32x32x16_bf16 v[64:79], v[144:147], v[96:99], 0
	v_add_f32_e32 v245, v216, v245
	v_add_f32_e32 v246, v217, v246
	ds_read_b128 v[172:175], v243 offset:12288
	s_waitcnt lgkmcnt(6)
	v_mfma_f32_32x32x16_bf16 v[80:95], v[148:151], v[96:99], 0
	v_add_f32_e32 v245, v218, v245
	v_add_f32_e32 v246, v219, v246
	ds_read_b128 v[144:147], v240 offset:128
	s_waitcnt lgkmcnt(6)
	v_mfma_f32_32x32x16_bf16 v[64:79], v[152:155], v[100:103], v[64:79]
	v_add_f32_e32 v245, v220, v245
	s_add_i32 m0, s60, 0x6000
	s_nop 0
	global_load_lds_dwordx4 v182, s[42:43]
	ds_read_b128 v[148:151], v240 offset:12416
	s_waitcnt lgkmcnt(6)
	v_mfma_f32_32x32x16_bf16 v[80:95], v[156:159], v[100:103], v[80:95]
	v_add_f32_e32 v246, v221, v246
	v_add_f32_e32 v245, v222, v245
	ds_read_b128 v[152:155], v241 offset:128
	s_waitcnt lgkmcnt(6)
	v_mfma_f32_32x32x16_bf16 v[64:79], v[160:163], v[104:107], v[64:79]
	v_add_f32_e32 v246, v223, v246
	v_add_f32_e32 v245, v224, v245
	ds_read_b128 v[156:159], v241 offset:12416
	s_waitcnt lgkmcnt(6)
	v_mfma_f32_32x32x16_bf16 v[80:95], v[164:167], v[104:107], v[80:95]
	v_add_f32_e32 v246, v225, v246
	s_add_i32 m0, s60, 0x6400
	s_nop 0
	global_load_lds_dwordx4 v183, s[42:43]
	ds_read_b128 v[160:163], v242 offset:128
	s_waitcnt lgkmcnt(6)
	v_mfma_f32_32x32x16_bf16 v[64:79], v[168:171], v[108:111], v[64:79]
	v_add_f32_e32 v245, v226, v245
	v_add_f32_e32 v246, v227, v246
	ds_read_b128 v[164:167], v242 offset:12416
	s_waitcnt lgkmcnt(6)
	v_mfma_f32_32x32x16_bf16 v[80:95], v[172:175], v[108:111], v[80:95]
	v_add_f32_e32 v245, v228, v245
	v_add_f32_e32 v246, v229, v246
	ds_read_b128 v[168:171], v243 offset:128
	s_waitcnt lgkmcnt(6)
	v_mfma_f32_32x32x16_bf16 v[64:79], v[144:147], v[112:115], v[64:79]
	v_add_f32_e32 v245, v230, v245
	s_add_i32 m0, s60, 0x6800
	s_nop 0
	global_load_lds_dwordx4 v184, s[42:43]
	ds_read_b128 v[172:175], v243 offset:12416
	s_waitcnt lgkmcnt(6)
	v_mfma_f32_32x32x16_bf16 v[80:95], v[148:151], v[112:115], v[80:95]
	v_add_f32_e32 v246, v231, v246
	v_add_f32_e32 v245, v232, v245
	ds_read_b128 v[144:147], v240 offset:256
	s_waitcnt lgkmcnt(6)
	v_mfma_f32_32x32x16_bf16 v[64:79], v[152:155], v[116:119], v[64:79]
	v_add_f32_e32 v246, v233, v246
	v_add_f32_e32 v245, v234, v245
	ds_read_b128 v[148:151], v240 offset:12544
	s_waitcnt lgkmcnt(6)
	v_mfma_f32_32x32x16_bf16 v[80:95], v[156:159], v[116:119], v[80:95]
	v_add_f32_e32 v246, v235, v246
	s_add_i32 m0, s61, 0x0
	s_nop 0
	global_load_lds_dwordx4 v185, s[46:47]
	ds_read_b128 v[152:155], v241 offset:256
	s_waitcnt lgkmcnt(6)
	v_mfma_f32_32x32x16_bf16 v[64:79], v[160:163], v[120:123], v[64:79]
	v_add_f32_e32 v245, v236, v245
	v_add_f32_e32 v246, v237, v246
	ds_read_b128 v[156:159], v241 offset:12544
	s_waitcnt lgkmcnt(6)
	v_mfma_f32_32x32x16_bf16 v[80:95], v[164:167], v[120:123], v[80:95]
	v_add_f32_e32 v245, v238, v245
	v_add_f32_e32 v246, v239, v246
	ds_read_b128 v[160:163], v242 offset:256
	s_waitcnt lgkmcnt(6)
	v_mfma_f32_32x32x16_bf16 v[64:79], v[168:171], v[124:127], v[64:79]
	v_cvt_pk_bf16_f32 v208, v208, v209
	s_add_i32 m0, s61, 0x400
	s_nop 0
	global_load_lds_dwordx4 v186, s[46:47]
	ds_read_b128 v[164:167], v242 offset:12544
	s_waitcnt lgkmcnt(6)
	v_mfma_f32_32x32x16_bf16 v[80:95], v[172:175], v[124:127], v[80:95]
	v_cvt_pk_bf16_f32 v209, v210, v211
	v_cvt_pk_bf16_f32 v210, v212, v213
	ds_read_b128 v[168:171], v243 offset:256
	s_waitcnt lgkmcnt(6)
	v_mfma_f32_32x32x16_bf16 v[64:79], v[144:147], v[128:131], v[64:79]
	v_cvt_pk_bf16_f32 v211, v214, v215
	v_cvt_pk_bf16_f32 v212, v216, v217
	ds_read_b128 v[172:175], v243 offset:12544
	s_waitcnt lgkmcnt(6)
	v_mfma_f32_32x32x16_bf16 v[80:95], v[148:151], v[128:131], v[80:95]
	v_cvt_pk_bf16_f32 v213, v218, v219
	s_add_u32 s42, s42, 0x6000
	s_addc_u32 s43, s43, 0
	v_add_u32_e32 v240, 0xffff4000, v240
	ds_read_b64_tr_b16 v[144:145], v244 offset:0
	ds_read_b64_tr_b16 v[146:147], v244 offset:2048
	s_waitcnt lgkmcnt(7)
	v_mfma_f32_32x32x16_bf16 v[64:79], v[152:155], v[132:135], v[64:79]
	v_cvt_pk_bf16_f32 v214, v220, v221
	v_cvt_pk_bf16_f32 v215, v222, v223
	v_add_u32_e32 v241, 0xffff4000, v241
	ds_read_b64_tr_b16 v[148:149], v244 offset:4096
	ds_read_b64_tr_b16 v[150:151], v244 offset:6144
	s_waitcnt lgkmcnt(8)
	v_mfma_f32_32x32x16_bf16 v[80:95], v[156:159], v[132:135], v[80:95]
	v_cvt_pk_bf16_f32 v224, v224, v225
	v_cvt_pk_bf16_f32 v225, v226, v227
	v_add_u32_e32 v242, 0xffff4000, v242
	ds_read_b64_tr_b16 v[152:153], v244 offset:8192
	ds_read_b64_tr_b16 v[154:155], v244 offset:10240
	s_waitcnt lgkmcnt(9)
	v_mfma_f32_32x32x16_bf16 v[64:79], v[160:163], v[136:139], v[64:79]
	v_cvt_pk_bf16_f32 v226, v228, v229
	s_add_u32 s46, s46, 0x40000
	s_addc_u32 s47, s47, 0
	v_add_u32_e32 v243, 0xffff4000, v243
	ds_read_b64_tr_b16 v[156:157], v244 offset:12288
	ds_read_b64_tr_b16 v[158:159], v244 offset:14336
	s_waitcnt lgkmcnt(10)
	v_mfma_f32_32x32x16_bf16 v[80:95], v[164:167], v[136:139], v[80:95]
	v_cvt_pk_bf16_f32 v227, v230, v231
	v_cvt_pk_bf16_f32 v228, v232, v233
	ds_read_b64_tr_b16 v[160:161], v244 offset:512
	ds_read_b64_tr_b16 v[162:163], v244 offset:2560
	s_waitcnt lgkmcnt(11)
	v_mfma_f32_32x32x16_bf16 v[64:79], v[168:171], v[140:143], v[64:79]
	v_cvt_pk_bf16_f32 v229, v234, v235
	v_cvt_pk_bf16_f32 v230, v236, v237
	ds_read_b64_tr_b16 v[164:165], v244 offset:4608
	ds_read_b64_tr_b16 v[166:167], v244 offset:6656
	s_waitcnt lgkmcnt(12)
	v_mfma_f32_32x32x16_bf16 v[80:95], v[172:175], v[140:143], v[80:95]
	v_cvt_pk_bf16_f32 v231, v238, v239
	s_waitcnt lgkmcnt(10)
	v_mfma_f32_32x32x16_bf16 v[48:63], v[208:211], v[144:147], v[48:63]
	s_waitcnt lgkmcnt(8)
	v_mfma_f32_32x32x16_bf16 v[48:63], v[212:215], v[148:151], v[48:63]
	ds_read_b64_tr_b16 v[168:169], v244 offset:8704
	ds_read_b64_tr_b16 v[170:171], v244 offset:10752
	s_waitcnt lgkmcnt(8)
	v_mfma_f32_32x32x16_bf16 v[48:63], v[224:227], v[152:155], v[48:63]
	v_exp_f32_e32 v64, v64
	v_exp_f32_e32 v65, v65
	v_exp_f32_e32 v66, v66
	ds_read_b64_tr_b16 v[172:173], v244 offset:12800
	ds_read_b64_tr_b16 v[174:175], v244 offset:14848
	s_waitcnt lgkmcnt(8)
	v_mfma_f32_32x32x16_bf16 v[48:63], v[228:231], v[156:159], v[48:63]
	v_exp_f32_e32 v67, v67
	v_exp_f32_e32 v68, v68
	v_exp_f32_e32 v69, v69
	ds_read_b64_tr_b16 v[144:145], v244 offset:1024
	ds_read_b64_tr_b16 v[146:147], v244 offset:3072
	s_waitcnt lgkmcnt(8)
	v_mfma_f32_32x32x16_bf16 v[32:47], v[208:211], v[160:163], v[32:47]
	v_exp_f32_e32 v70, v70
	v_exp_f32_e32 v71, v71
	v_exp_f32_e32 v72, v72
	ds_read_b64_tr_b16 v[148:149], v244 offset:5120
	ds_read_b64_tr_b16 v[150:151], v244 offset:7168
	s_waitcnt lgkmcnt(8)
	v_mfma_f32_32x32x16_bf16 v[32:47], v[212:215], v[164:167], v[32:47]
	v_exp_f32_e32 v73, v73
	v_exp_f32_e32 v74, v74
	v_exp_f32_e32 v75, v75
	ds_read_b64_tr_b16 v[152:153], v244 offset:9216
	ds_read_b64_tr_b16 v[154:155], v244 offset:11264
	s_waitcnt lgkmcnt(8)
	v_mfma_f32_32x32x16_bf16 v[32:47], v[224:227], v[168:171], v[32:47]
	v_exp_f32_e32 v76, v76
	v_exp_f32_e32 v77, v77
	ds_read_b64_tr_b16 v[156:157], v244 offset:13312
	ds_read_b64_tr_b16 v[158:159], v244 offset:15360
	s_waitcnt lgkmcnt(8)
	v_mfma_f32_32x32x16_bf16 v[32:47], v[228:231], v[172:175], v[32:47]
	v_exp_f32_e32 v78, v78
	v_exp_f32_e32 v79, v79
	ds_read_b64_tr_b16 v[160:161], v244 offset:1536
	ds_read_b64_tr_b16 v[162:163], v244 offset:3584
	s_waitcnt lgkmcnt(8)
	v_mfma_f32_32x32x16_bf16 v[16:31], v[208:211], v[144:147], v[16:31]
	v_exp_f32_e32 v80, v80
	v_exp_f32_e32 v81, v81
	ds_read_b64_tr_b16 v[164:165], v244 offset:5632
	ds_read_b64_tr_b16 v[166:167], v244 offset:7680
	s_waitcnt lgkmcnt(8)
	v_mfma_f32_32x32x16_bf16 v[16:31], v[212:215], v[148:151], v[16:31]
	v_exp_f32_e32 v82, v82
	v_exp_f32_e32 v83, v83
	ds_read_b64_tr_b16 v[168:169], v244 offset:9728
	ds_read_b64_tr_b16 v[170:171], v244 offset:11776
	s_waitcnt lgkmcnt(8)
	v_mfma_f32_32x32x16_bf16 v[16:31], v[224:227], v[152:155], v[16:31]
	v_exp_f32_e32 v84, v84
	v_exp_f32_e32 v85, v85
	ds_read_b64_tr_b16 v[172:173], v244 offset:13824
	ds_read_b64_tr_b16 v[174:175], v244 offset:15872
	s_waitcnt lgkmcnt(8)
	v_mfma_f32_32x32x16_bf16 v[16:31], v[228:231], v[156:159], v[16:31]
	v_exp_f32_e32 v86, v86
	v_exp_f32_e32 v87, v87
	v_add_u32_e32 v244, 0x4000, v244
	s_waitcnt lgkmcnt(6)
	v_mfma_f32_32x32x16_bf16 v[0:15], v[208:211], v[160:163], v[0:15]
	v_exp_f32_e32 v88, v88
	v_exp_f32_e32 v89, v89
	s_waitcnt lgkmcnt(4)
	v_mfma_f32_32x32x16_bf16 v[0:15], v[212:215], v[164:167], v[0:15]
	v_exp_f32_e32 v90, v90
	v_exp_f32_e32 v91, v91
	s_waitcnt lgkmcnt(2)
	v_mfma_f32_32x32x16_bf16 v[0:15], v[224:227], v[168:171], v[0:15]
	v_exp_f32_e32 v92, v92
	v_exp_f32_e32 v93, v93
	s_waitcnt lgkmcnt(0)
	v_mfma_f32_32x32x16_bf16 v[0:15], v[228:231], v[172:175], v[0:15]
	v_exp_f32_e32 v94, v94
	v_exp_f32_e32 v95, v95
	s_waitcnt vmcnt(5)
	s_barrier
	ds_read_b128 v[144:147], v240 offset:0
	ds_read_b128 v[148:151], v240 offset:12288
	ds_read_b128 v[152:155], v241 offset:0
	ds_read_b128 v[156:159], v241 offset:12288
	ds_read_b128 v[160:163], v242 offset:0
	ds_read_b128 v[164:167], v242 offset:12288
	v_add_f32_e32 v245, v64, v245
	v_add_f32_e32 v246, v65, v246
	v_add_f32_e32 v245, v66, v245
	v_add_f32_e32 v246, v67, v246
	v_add_f32_e32 v245, v68, v245
	v_add_f32_e32 v246, v69, v246
	v_add_f32_e32 v245, v70, v245
	v_add_f32_e32 v246, v71, v246
	ds_read_b128 v[168:171], v243 offset:0
	s_waitcnt lgkmcnt(6)
	v_mfma_f32_32x32x16_bf16 v[208:223], v[144:147], v[96:99], 0
	v_add_f32_e32 v245, v72, v245
	v_add_f32_e32 v246, v73, v246
	ds_read_b128 v[172:175], v243 offset:12288
	s_waitcnt lgkmcnt(6)
	v_mfma_f32_32x32x16_bf16 v[224:239], v[148:151], v[96:99], 0
	v_add_f32_e32 v245, v74, v245
	v_add_f32_e32 v246, v75, v246
	ds_read_b128 v[144:147], v240 offset:128
	s_waitcnt lgkmcnt(6)
	v_mfma_f32_32x32x16_bf16 v[208:223], v[152:155], v[100:103], v[208:223]
	v_add_f32_e32 v245, v76, v245
	s_add_i32 m0, s60, 0xc000
	s_nop 0
	global_load_lds_dwordx4 v182, s[42:43]
	ds_read_b128 v[148:151], v240 offset:12416
	s_waitcnt lgkmcnt(6)
	v_mfma_f32_32x32x16_bf16 v[224:239], v[156:159], v[100:103], v[224:239]
	v_add_f32_e32 v246, v77, v246
	v_add_f32_e32 v245, v78, v245
	ds_read_b128 v[152:155], v241 offset:128
	s_waitcnt lgkmcnt(6)
	v_mfma_f32_32x32x16_bf16 v[208:223], v[160:163], v[104:107], v[208:223]
	v_add_f32_e32 v246, v79, v246
	v_add_f32_e32 v245, v80, v245
	ds_read_b128 v[156:159], v241 offset:12416
	s_waitcnt lgkmcnt(6)
	v_mfma_f32_32x32x16_bf16 v[224:239], v[164:167], v[104:107], v[224:239]
	v_add_f32_e32 v246, v81, v246
	s_add_i32 m0, s60, 0xc400
	s_nop 0
	global_load_lds_dwordx4 v183, s[42:43]
	ds_read_b128 v[160:163], v242 offset:128
	s_waitcnt lgkmcnt(6)
	v_mfma_f32_32x32x16_bf16 v[208:223], v[168:171], v[108:111], v[208:223]
	v_add_f32_e32 v245, v82, v245
	v_add_f32_e32 v246, v83, v246
	ds_read_b128 v[164:167], v242 offset:12416
	s_waitcnt lgkmcnt(6)
	v_mfma_f32_32x32x16_bf16 v[224:239], v[172:175], v[108:111], v[224:239]
	v_add_f32_e32 v245, v84, v245
	v_add_f32_e32 v246, v85, v246
	ds_read_b128 v[168:171], v243 offset:128
	s_waitcnt lgkmcnt(6)
	v_mfma_f32_32x32x16_bf16 v[208:223], v[144:147], v[112:115], v[208:223]
	v_add_f32_e32 v245, v86, v245
	s_add_i32 m0, s60, 0xc800
	s_nop 0
	global_load_lds_dwordx4 v184, s[42:43]
	ds_read_b128 v[172:175], v243 offset:12416
	s_waitcnt lgkmcnt(6)
	v_mfma_f32_32x32x16_bf16 v[224:239], v[148:151], v[112:115], v[224:239]
	v_add_f32_e32 v246, v87, v246
	v_add_f32_e32 v245, v88, v245
	ds_read_b128 v[144:147], v240 offset:256
	s_waitcnt lgkmcnt(6)
	v_mfma_f32_32x32x16_bf16 v[208:223], v[152:155], v[116:119], v[208:223]
	v_add_f32_e32 v246, v89, v246
	v_add_f32_e32 v245, v90, v245
	ds_read_b128 v[148:151], v240 offset:12544
	s_waitcnt lgkmcnt(6)
	v_mfma_f32_32x32x16_bf16 v[224:239], v[156:159], v[116:119], v[224:239]
	v_add_f32_e32 v246, v91, v246
	s_add_i32 m0, s61, 0x4000
	s_nop 0
	global_load_lds_dwordx4 v185, s[46:47]
	ds_read_b128 v[152:155], v241 offset:256
	s_waitcnt lgkmcnt(6)
	v_mfma_f32_32x32x16_bf16 v[208:223], v[160:163], v[120:123], v[208:223]
	v_add_f32_e32 v245, v92, v245
	v_add_f32_e32 v246, v93, v246
	ds_read_b128 v[156:159], v241 offset:12544
	s_waitcnt lgkmcnt(6)
	v_mfma_f32_32x32x16_bf16 v[224:239], v[164:167], v[120:123], v[224:239]
	v_add_f32_e32 v245, v94, v245
	v_add_f32_e32 v246, v95, v246
	ds_read_b128 v[160:163], v242 offset:256
	s_waitcnt lgkmcnt(6)
	v_mfma_f32_32x32x16_bf16 v[208:223], v[168:171], v[124:127], v[208:223]
	v_cvt_pk_bf16_f32 v64, v64, v65
	s_add_i32 m0, s61, 0x4400
	s_nop 0
	global_load_lds_dwordx4 v186, s[46:47]
	ds_read_b128 v[164:167], v242 offset:12544
	s_waitcnt lgkmcnt(6)
	v_mfma_f32_32x32x16_bf16 v[224:239], v[172:175], v[124:127], v[224:239]
	v_cvt_pk_bf16_f32 v65, v66, v67
	v_cvt_pk_bf16_f32 v66, v68, v69
	ds_read_b128 v[168:171], v243 offset:256
	s_waitcnt lgkmcnt(6)
	v_mfma_f32_32x32x16_bf16 v[208:223], v[144:147], v[128:131], v[208:223]
	v_cvt_pk_bf16_f32 v67, v70, v71
	v_cvt_pk_bf16_f32 v68, v72, v73
	ds_read_b128 v[172:175], v243 offset:12544
	s_waitcnt lgkmcnt(6)
	v_mfma_f32_32x32x16_bf16 v[224:239], v[148:151], v[128:131], v[224:239]
	v_cvt_pk_bf16_f32 v69, v74, v75
	s_add_u32 s42, s42, 0x6000
	s_addc_u32 s43, s43, 0
	v_add_u32_e32 v240, 0x6000, v240
	ds_read_b64_tr_b16 v[144:145], v244 offset:0
	ds_read_b64_tr_b16 v[146:147], v244 offset:2048
	s_waitcnt lgkmcnt(7)
	v_mfma_f32_32x32x16_bf16 v[208:223], v[152:155], v[132:135], v[208:223]
	v_cvt_pk_bf16_f32 v70, v76, v77
	v_cvt_pk_bf16_f32 v71, v78, v79
	v_add_u32_e32 v241, 0x6000, v241
	ds_read_b64_tr_b16 v[148:149], v244 offset:4096
	ds_read_b64_tr_b16 v[150:151], v244 offset:6144
	s_waitcnt lgkmcnt(8)
	v_mfma_f32_32x32x16_bf16 v[224:239], v[156:159], v[132:135], v[224:239]
	v_cvt_pk_bf16_f32 v80, v80, v81
	v_cvt_pk_bf16_f32 v81, v82, v83
	v_add_u32_e32 v242, 0x6000, v242
	ds_read_b64_tr_b16 v[152:153], v244 offset:8192
	ds_read_b64_tr_b16 v[154:155], v244 offset:10240
	s_waitcnt lgkmcnt(9)
	v_mfma_f32_32x32x16_bf16 v[208:223], v[160:163], v[136:139], v[208:223]
	v_cvt_pk_bf16_f32 v82, v84, v85
	s_add_u32 s46, s46, 0x40000
	s_addc_u32 s47, s47, 0
	v_add_u32_e32 v243, 0x6000, v243
	ds_read_b64_tr_b16 v[156:157], v244 offset:12288
	ds_read_b64_tr_b16 v[158:159], v244 offset:14336
	s_waitcnt lgkmcnt(10)
	v_mfma_f32_32x32x16_bf16 v[224:239], v[164:167], v[136:139], v[224:239]
	v_cvt_pk_bf16_f32 v83, v86, v87
	v_cvt_pk_bf16_f32 v84, v88, v89
	ds_read_b64_tr_b16 v[160:161], v244 offset:512
	ds_read_b64_tr_b16 v[162:163], v244 offset:2560
	s_waitcnt lgkmcnt(11)
	v_mfma_f32_32x32x16_bf16 v[208:223], v[168:171], v[140:143], v[208:223]
	v_cvt_pk_bf16_f32 v85, v90, v91
	v_cvt_pk_bf16_f32 v86, v92, v93
	ds_read_b64_tr_b16 v[164:165], v244 offset:4608
	ds_read_b64_tr_b16 v[166:167], v244 offset:6656
	s_waitcnt lgkmcnt(12)
	v_mfma_f32_32x32x16_bf16 v[224:239], v[172:175], v[140:143], v[224:239]
	v_cvt_pk_bf16_f32 v87, v94, v95
	s_waitcnt lgkmcnt(10)
	v_mfma_f32_32x32x16_bf16 v[48:63], v[64:67], v[144:147], v[48:63]
	s_waitcnt lgkmcnt(8)
	v_mfma_f32_32x32x16_bf16 v[48:63], v[68:71], v[148:151], v[48:63]
	ds_read_b64_tr_b16 v[168:169], v244 offset:8704
	ds_read_b64_tr_b16 v[170:171], v244 offset:10752
	s_waitcnt lgkmcnt(8)
	v_mfma_f32_32x32x16_bf16 v[48:63], v[80:83], v[152:155], v[48:63]
	v_exp_f32_e32 v208, v208
	v_exp_f32_e32 v209, v209
	v_exp_f32_e32 v210, v210
	ds_read_b64_tr_b16 v[172:173], v244 offset:12800
	ds_read_b64_tr_b16 v[174:175], v244 offset:14848
	s_waitcnt lgkmcnt(8)
	v_mfma_f32_32x32x16_bf16 v[48:63], v[84:87], v[156:159], v[48:63]
	v_exp_f32_e32 v211, v211
	v_exp_f32_e32 v212, v212
	v_exp_f32_e32 v213, v213
	ds_read_b64_tr_b16 v[144:145], v244 offset:1024
	ds_read_b64_tr_b16 v[146:147], v244 offset:3072
	s_waitcnt lgkmcnt(8)
	v_mfma_f32_32x32x16_bf16 v[32:47], v[64:67], v[160:163], v[32:47]
	v_exp_f32_e32 v214, v214
	v_exp_f32_e32 v215, v215
	v_exp_f32_e32 v216, v216
	ds_read_b64_tr_b16 v[148:149], v244 offset:5120
	ds_read_b64_tr_b16 v[150:151], v244 offset:7168
	s_waitcnt lgkmcnt(8)
	v_mfma_f32_32x32x16_bf16 v[32:47], v[68:71], v[164:167], v[32:47]
	v_exp_f32_e32 v217, v217
	v_exp_f32_e32 v218, v218
	v_exp_f32_e32 v219, v219
	ds_read_b64_tr_b16 v[152:153], v244 offset:9216
	ds_read_b64_tr_b16 v[154:155], v244 offset:11264
	s_waitcnt lgkmcnt(8)
	v_mfma_f32_32x32x16_bf16 v[32:47], v[80:83], v[168:171], v[32:47]
	v_exp_f32_e32 v220, v220
	v_exp_f32_e32 v221, v221
	ds_read_b64_tr_b16 v[156:157], v244 offset:13312
	ds_read_b64_tr_b16 v[158:159], v244 offset:15360
	s_waitcnt lgkmcnt(8)
	v_mfma_f32_32x32x16_bf16 v[32:47], v[84:87], v[172:175], v[32:47]
	v_exp_f32_e32 v222, v222
	v_exp_f32_e32 v223, v223
	ds_read_b64_tr_b16 v[160:161], v244 offset:1536
	ds_read_b64_tr_b16 v[162:163], v244 offset:3584
	s_waitcnt lgkmcnt(8)
	v_mfma_f32_32x32x16_bf16 v[16:31], v[64:67], v[144:147], v[16:31]
	v_exp_f32_e32 v224, v224
	v_exp_f32_e32 v225, v225
	ds_read_b64_tr_b16 v[164:165], v244 offset:5632
	ds_read_b64_tr_b16 v[166:167], v244 offset:7680
	s_waitcnt lgkmcnt(8)
	v_mfma_f32_32x32x16_bf16 v[16:31], v[68:71], v[148:151], v[16:31]
	v_exp_f32_e32 v226, v226
	v_exp_f32_e32 v227, v227
	ds_read_b64_tr_b16 v[168:169], v244 offset:9728
	ds_read_b64_tr_b16 v[170:171], v244 offset:11776
	s_waitcnt lgkmcnt(8)
	v_mfma_f32_32x32x16_bf16 v[16:31], v[80:83], v[152:155], v[16:31]
	v_exp_f32_e32 v228, v228
	v_exp_f32_e32 v229, v229
	ds_read_b64_tr_b16 v[172:173], v244 offset:13824
	ds_read_b64_tr_b16 v[174:175], v244 offset:15872
	s_waitcnt lgkmcnt(8)
	v_mfma_f32_32x32x16_bf16 v[16:31], v[84:87], v[156:159], v[16:31]
	v_exp_f32_e32 v230, v230
	v_exp_f32_e32 v231, v231
	v_add_u32_e32 v244, 0xffff8000, v244
	s_waitcnt lgkmcnt(6)
	v_mfma_f32_32x32x16_bf16 v[0:15], v[64:67], v[160:163], v[0:15]
	v_exp_f32_e32 v232, v232
	v_exp_f32_e32 v233, v233
	s_waitcnt lgkmcnt(4)
	v_mfma_f32_32x32x16_bf16 v[0:15], v[68:71], v[164:167], v[0:15]
	v_exp_f32_e32 v234, v234
	v_exp_f32_e32 v235, v235
	s_waitcnt lgkmcnt(2)
	v_mfma_f32_32x32x16_bf16 v[0:15], v[80:83], v[168:171], v[0:15]
	v_exp_f32_e32 v236, v236
	v_exp_f32_e32 v237, v237
	s_waitcnt lgkmcnt(0)
	v_mfma_f32_32x32x16_bf16 v[0:15], v[84:87], v[172:175], v[0:15]
	v_exp_f32_e32 v238, v238
	v_exp_f32_e32 v239, v239
	s_sub_i32 s78, s78, 1
	s_cmp_lg_u32 s78, 0
	s_cbranch_scc1 .Lattn_loop
	s_waitcnt vmcnt(0)
	s_barrier
	ds_read_b128 v[144:147], v240 offset:0
	ds_read_b128 v[148:151], v240 offset:12288
	ds_read_b128 v[152:155], v241 offset:0
	ds_read_b128 v[156:159], v241 offset:12288
	ds_read_b128 v[160:163], v242 offset:0
	ds_read_b128 v[164:167], v242 offset:12288
	v_add_f32_e32 v245, v208, v245
	v_add_f32_e32 v246, v209, v246
	v_add_f32_e32 v245, v210, v245
	v_add_f32_e32 v246, v211, v246
	v_add_f32_e32 v245, v212, v245
	v_add_f32_e32 v246, v213, v246
	v_add_f32_e32 v245, v214, v245
	v_add_f32_e32 v246, v215, v246
	ds_read_b128 v[168:171], v243 offset:0
	s_waitcnt lgkmcnt(6)
	v_mfma_f32_32x32x16_bf16 v[64:79], v[144:147], v[96:99], 0
	v_add_f32_e32 v245, v216, v245
	v_add_f32_e32 v246, v217, v246
	ds_read_b128 v[172:175], v243 offset:12288
	s_waitcnt lgkmcnt(6)
	v_mfma_f32_32x32x16_bf16 v[80:95], v[148:151], v[96:99], 0
	v_add_f32_e32 v245, v218, v245
	v_add_f32_e32 v246, v219, v246
	ds_read_b128 v[144:147], v240 offset:128
	s_waitcnt lgkmcnt(6)
	v_mfma_f32_32x32x16_bf16 v[64:79], v[152:155], v[100:103], v[64:79]
	v_add_f32_e32 v245, v220, v245
	v_add_f32_e32 v246, v221, v246
	ds_read_b128 v[148:151], v240 offset:12416
	s_waitcnt lgkmcnt(6)
	v_mfma_f32_32x32x16_bf16 v[80:95], v[156:159], v[100:103], v[80:95]
	v_add_f32_e32 v245, v222, v245
	v_add_f32_e32 v246, v223, v246
	ds_read_b128 v[152:155], v241 offset:128
	s_waitcnt lgkmcnt(6)
	v_mfma_f32_32x32x16_bf16 v[64:79], v[160:163], v[104:107], v[64:79]
	v_add_f32_e32 v245, v224, v245
	v_add_f32_e32 v246, v225, v246
	ds_read_b128 v[156:159], v241 offset:12416
	s_waitcnt lgkmcnt(6)
	v_mfma_f32_32x32x16_bf16 v[80:95], v[164:167], v[104:107], v[80:95]
	v_add_f32_e32 v245, v226, v245
	v_add_f32_e32 v246, v227, v246
	ds_read_b128 v[160:163], v242 offset:128
	s_waitcnt lgkmcnt(6)
	v_mfma_f32_32x32x16_bf16 v[64:79], v[168:171], v[108:111], v[64:79]
	v_add_f32_e32 v245, v228, v245
	v_add_f32_e32 v246, v229, v246
	ds_read_b128 v[164:167], v242 offset:12416
	s_waitcnt lgkmcnt(6)
	v_mfma_f32_32x32x16_bf16 v[80:95], v[172:175], v[108:111], v[80:95]
	v_add_f32_e32 v245, v230, v245
	v_add_f32_e32 v246, v231, v246
	ds_read_b128 v[168:171], v243 offset:128
	s_waitcnt lgkmcnt(6)
	v_mfma_f32_32x32x16_bf16 v[64:79], v[144:147], v[112:115], v[64:79]
	v_add_f32_e32 v245, v232, v245
	v_add_f32_e32 v246, v233, v246
	ds_read_b128 v[172:175], v243 offset:12416
	s_waitcnt lgkmcnt(6)
	v_mfma_f32_32x32x16_bf16 v[80:95], v[148:151], v[112:115], v[80:95]
	v_add_f32_e32 v245, v234, v245
	v_add_f32_e32 v246, v235, v246
	ds_read_b128 v[144:147], v240 offset:256
	s_waitcnt lgkmcnt(6)
	v_mfma_f32_32x32x16_bf16 v[64:79], v[152:155], v[116:119], v[64:79]
	v_add_f32_e32 v245, v236, v245
	v_add_f32_e32 v246, v237, v246
	ds_read_b128 v[148:151], v240 offset:12544
	s_waitcnt lgkmcnt(6)
	v_mfma_f32_32x32x16_bf16 v[80:95], v[156:159], v[116:119], v[80:95]
	v_add_f32_e32 v245, v238, v245
	v_add_f32_e32 v246, v239, v246
	ds_read_b128 v[152:155], v241 offset:256
	s_waitcnt lgkmcnt(6)
	v_mfma_f32_32x32x16_bf16 v[64:79], v[160:163], v[120:123], v[64:79]
	v_cvt_pk_bf16_f32 v208, v208, v209
	v_cvt_pk_bf16_f32 v209, v210, v211
	ds_read_b128 v[156:159], v241 offset:12544
	s_waitcnt lgkmcnt(6)
	v_mfma_f32_32x32x16_bf16 v[80:95], v[164:167], v[120:123], v[80:95]
	v_cvt_pk_bf16_f32 v210, v212, v213
	v_cvt_pk_bf16_f32 v211, v214, v215
	ds_read_b128 v[160:163], v242 offset:256
	s_waitcnt lgkmcnt(6)
	v_mfma_f32_32x32x16_bf16 v[64:79], v[168:171], v[124:127], v[64:79]
	v_cvt_pk_bf16_f32 v212, v216, v217
	v_cvt_pk_bf16_f32 v213, v218, v219
	ds_read_b128 v[164:167], v242 offset:12544
	s_waitcnt lgkmcnt(6)
	v_mfma_f32_32x32x16_bf16 v[80:95], v[172:175], v[124:127], v[80:95]
	v_cvt_pk_bf16_f32 v214, v220, v221
	v_cvt_pk_bf16_f32 v215, v222, v223
	ds_read_b128 v[168:171], v243 offset:256
	s_waitcnt lgkmcnt(6)
	v_mfma_f32_32x32x16_bf16 v[64:79], v[144:147], v[128:131], v[64:79]
	v_cvt_pk_bf16_f32 v224, v224, v225
	ds_read_b128 v[172:175], v243 offset:12544
	s_waitcnt lgkmcnt(6)
	v_mfma_f32_32x32x16_bf16 v[80:95], v[148:151], v[128:131], v[80:95]
	v_cvt_pk_bf16_f32 v225, v226, v227
	ds_read_b64_tr_b16 v[144:145], v244 offset:0
	ds_read_b64_tr_b16 v[146:147], v244 offset:2048
	s_waitcnt lgkmcnt(7)
	v_mfma_f32_32x32x16_bf16 v[64:79], v[152:155], v[132:135], v[64:79]
	v_cvt_pk_bf16_f32 v226, v228, v229
	ds_read_b64_tr_b16 v[148:149], v244 offset:4096
	ds_read_b64_tr_b16 v[150:151], v244 offset:6144
	s_waitcnt lgkmcnt(8)
	v_mfma_f32_32x32x16_bf16 v[80:95], v[156:159], v[132:135], v[80:95]
	v_cvt_pk_bf16_f32 v227, v230, v231
	ds_read_b64_tr_b16 v[152:153], v244 offset:8192
	ds_read_b64_tr_b16 v[154:155], v244 offset:10240
	s_waitcnt lgkmcnt(9)
	v_mfma_f32_32x32x16_bf16 v[64:79], v[160:163], v[136:139], v[64:79]
	v_cvt_pk_bf16_f32 v228, v232, v233
	ds_read_b64_tr_b16 v[156:157], v244 offset:12288
	ds_read_b64_tr_b16 v[158:159], v244 offset:14336
	s_waitcnt lgkmcnt(10)
	v_mfma_f32_32x32x16_bf16 v[80:95], v[164:167], v[136:139], v[80:95]
	v_cvt_pk_bf16_f32 v229, v234, v235
	ds_read_b64_tr_b16 v[160:161], v244 offset:512
	ds_read_b64_tr_b16 v[162:163], v244 offset:2560
	s_waitcnt lgkmcnt(11)
	v_mfma_f32_32x32x16_bf16 v[64:79], v[168:171], v[140:143], v[64:79]
	v_cvt_pk_bf16_f32 v230, v236, v237
	ds_read_b64_tr_b16 v[164:165], v244 offset:4608
	ds_read_b64_tr_b16 v[166:167], v244 offset:6656
	s_waitcnt lgkmcnt(12)
	v_mfma_f32_32x32x16_bf16 v[80:95], v[172:175], v[140:143], v[80:95]
	v_cvt_pk_bf16_f32 v231, v238, v239
	s_waitcnt lgkmcnt(10)
	v_mfma_f32_32x32x16_bf16 v[48:63], v[208:211], v[144:147], v[48:63]
	s_waitcnt lgkmcnt(8)
	v_mfma_f32_32x32x16_bf16 v[48:63], v[212:215], v[148:151], v[48:63]
	ds_read_b64_tr_b16 v[168:169], v244 offset:8704
	ds_read_b64_tr_b16 v[170:171], v244 offset:10752
	s_waitcnt lgkmcnt(8)
	v_mfma_f32_32x32x16_bf16 v[48:63], v[224:227], v[152:155], v[48:63]
	v_exp_f32_e32 v64, v64
	v_exp_f32_e32 v65, v65
	v_exp_f32_e32 v66, v66
	ds_read_b64_tr_b16 v[172:173], v244 offset:12800
	ds_read_b64_tr_b16 v[174:175], v244 offset:14848
	s_waitcnt lgkmcnt(8)
	v_mfma_f32_32x32x16_bf16 v[48:63], v[228:231], v[156:159], v[48:63]
	v_exp_f32_e32 v67, v67
	v_exp_f32_e32 v68, v68
	v_exp_f32_e32 v69, v69
	ds_read_b64_tr_b16 v[144:145], v244 offset:1024
	ds_read_b64_tr_b16 v[146:147], v244 offset:3072
	s_waitcnt lgkmcnt(8)
	v_mfma_f32_32x32x16_bf16 v[32:47], v[208:211], v[160:163], v[32:47]
	v_exp_f32_e32 v70, v70
	v_exp_f32_e32 v71, v71
	v_exp_f32_e32 v72, v72
	ds_read_b64_tr_b16 v[148:149], v244 offset:5120
	ds_read_b64_tr_b16 v[150:151], v244 offset:7168
	s_waitcnt lgkmcnt(8)
	v_mfma_f32_32x32x16_bf16 v[32:47], v[212:215], v[164:167], v[32:47]
	v_exp_f32_e32 v73, v73
	v_exp_f32_e32 v74, v74
	v_exp_f32_e32 v75, v75
	ds_read_b64_tr_b16 v[152:153], v244 offset:9216
	ds_read_b64_tr_b16 v[154:155], v244 offset:11264
	s_waitcnt lgkmcnt(8)
	v_mfma_f32_32x32x16_bf16 v[32:47], v[224:227], v[168:171], v[32:47]
	v_exp_f32_e32 v76, v76
	v_exp_f32_e32 v77, v77
	ds_read_b64_tr_b16 v[156:157], v244 offset:13312
	ds_read_b64_tr_b16 v[158:159], v244 offset:15360
	s_waitcnt lgkmcnt(8)
	v_mfma_f32_32x32x16_bf16 v[32:47], v[228:231], v[172:175], v[32:47]
	v_exp_f32_e32 v78, v78
	v_exp_f32_e32 v79, v79
	ds_read_b64_tr_b16 v[160:161], v244 offset:1536
	ds_read_b64_tr_b16 v[162:163], v244 offset:3584
	s_waitcnt lgkmcnt(8)
	v_mfma_f32_32x32x16_bf16 v[16:31], v[208:211], v[144:147], v[16:31]
	v_exp_f32_e32 v80, v80
	v_exp_f32_e32 v81, v81
	ds_read_b64_tr_b16 v[164:165], v244 offset:5632
	ds_read_b64_tr_b16 v[166:167], v244 offset:7680
	s_waitcnt lgkmcnt(8)
	v_mfma_f32_32x32x16_bf16 v[16:31], v[212:215], v[148:151], v[16:31]
	v_exp_f32_e32 v82, v82
	v_exp_f32_e32 v83, v83
	ds_read_b64_tr_b16 v[168:169], v244 offset:9728
	ds_read_b64_tr_b16 v[170:171], v244 offset:11776
	s_waitcnt lgkmcnt(8)
	v_mfma_f32_32x32x16_bf16 v[16:31], v[224:227], v[152:155], v[16:31]
	v_exp_f32_e32 v84, v84
	v_exp_f32_e32 v85, v85
	ds_read_b64_tr_b16 v[172:173], v244 offset:13824
	ds_read_b64_tr_b16 v[174:175], v244 offset:15872
	s_waitcnt lgkmcnt(8)
	v_mfma_f32_32x32x16_bf16 v[16:31], v[228:231], v[156:159], v[16:31]
	v_exp_f32_e32 v86, v86
	v_exp_f32_e32 v87, v87
	v_add_u32_e32 v244, 0x4000, v244
	s_waitcnt lgkmcnt(6)
	v_mfma_f32_32x32x16_bf16 v[0:15], v[208:211], v[160:163], v[0:15]
	v_exp_f32_e32 v88, v88
	v_exp_f32_e32 v89, v89
	s_waitcnt lgkmcnt(4)
	v_mfma_f32_32x32x16_bf16 v[0:15], v[212:215], v[164:167], v[0:15]
	v_exp_f32_e32 v90, v90
	v_exp_f32_e32 v91, v91
	s_waitcnt lgkmcnt(2)
	v_mfma_f32_32x32x16_bf16 v[0:15], v[224:227], v[168:171], v[0:15]
	v_exp_f32_e32 v92, v92
	v_exp_f32_e32 v93, v93
	s_waitcnt lgkmcnt(0)
	v_mfma_f32_32x32x16_bf16 v[0:15], v[228:231], v[172:175], v[0:15]
	v_exp_f32_e32 v94, v94
	v_exp_f32_e32 v95, v95
	ds_read_b64_tr_b16 v[144:145], v244 offset:0
	ds_read_b64_tr_b16 v[146:147], v244 offset:2048
	ds_read_b64_tr_b16 v[148:149], v244 offset:4096
	ds_read_b64_tr_b16 v[150:151], v244 offset:6144
	ds_read_b64_tr_b16 v[152:153], v244 offset:8192
	ds_read_b64_tr_b16 v[154:155], v244 offset:10240
	ds_read_b64_tr_b16 v[156:157], v244 offset:12288
	ds_read_b64_tr_b16 v[158:159], v244 offset:14336
	v_add_f32_e32 v245, v64, v245
	v_add_f32_e32 v246, v65, v246
	v_add_f32_e32 v245, v66, v245
	v_add_f32_e32 v246, v67, v246
	v_add_f32_e32 v245, v68, v245
	v_add_f32_e32 v246, v69, v246
	v_add_f32_e32 v245, v70, v245
	v_add_f32_e32 v246, v71, v246
	v_add_f32_e32 v245, v72, v245
	v_add_f32_e32 v246, v73, v246
	v_add_f32_e32 v245, v74, v245
	v_add_f32_e32 v246, v75, v246
	v_add_f32_e32 v245, v76, v245
	v_add_f32_e32 v246, v77, v246
	v_add_f32_e32 v245, v78, v245
	v_add_f32_e32 v246, v79, v246
	v_add_f32_e32 v245, v80, v245
	v_add_f32_e32 v246, v81, v246
	v_add_f32_e32 v245, v82, v245
	v_add_f32_e32 v246, v83, v246
	v_add_f32_e32 v245, v84, v245
	v_add_f32_e32 v246, v85, v246
	v_add_f32_e32 v245, v86, v245
	v_add_f32_e32 v246, v87, v246
	v_add_f32_e32 v245, v88, v245
	v_add_f32_e32 v246, v89, v246
	v_add_f32_e32 v245, v90, v245
	v_add_f32_e32 v246, v91, v246
	v_add_f32_e32 v245, v92, v245
	v_add_f32_e32 v246, v93, v246
	v_add_f32_e32 v245, v94, v245
	v_add_f32_e32 v246, v95, v246
	v_cvt_pk_bf16_f32 v64, v64, v65
	v_cvt_pk_bf16_f32 v65, v66, v67
	v_cvt_pk_bf16_f32 v66, v68, v69
	v_cvt_pk_bf16_f32 v67, v70, v71
	v_cvt_pk_bf16_f32 v68, v72, v73
	v_cvt_pk_bf16_f32 v69, v74, v75
	v_cvt_pk_bf16_f32 v70, v76, v77
	v_cvt_pk_bf16_f32 v71, v78, v79
	v_cvt_pk_bf16_f32 v80, v80, v81
	v_cvt_pk_bf16_f32 v81, v82, v83
	v_cvt_pk_bf16_f32 v82, v84, v85
	v_cvt_pk_bf16_f32 v83, v86, v87
	v_cvt_pk_bf16_f32 v84, v88, v89
	v_cvt_pk_bf16_f32 v85, v90, v91
	v_cvt_pk_bf16_f32 v86, v92, v93
	v_cvt_pk_bf16_f32 v87, v94, v95
	ds_read_b64_tr_b16 v[160:161], v244 offset:512
	ds_read_b64_tr_b16 v[162:163], v244 offset:2560
	s_waitcnt lgkmcnt(8)
	v_mfma_f32_32x32x16_bf16 v[48:63], v[64:67], v[144:147], v[48:63]
	ds_read_b64_tr_b16 v[164:165], v244 offset:4608
	ds_read_b64_tr_b16 v[166:167], v244 offset:6656
	s_waitcnt lgkmcnt(8)
	v_mfma_f32_32x32x16_bf16 v[48:63], v[68:71], v[148:151], v[48:63]
	ds_read_b64_tr_b16 v[168:169], v244 offset:8704
	ds_read_b64_tr_b16 v[170:171], v244 offset:10752
	s_waitcnt lgkmcnt(8)
	v_mfma_f32_32x32x16_bf16 v[48:63], v[80:83], v[152:155], v[48:63]
	ds_read_b64_tr_b16 v[172:173], v244 offset:12800
	ds_read_b64_tr_b16 v[174:175], v244 offset:14848
	s_waitcnt lgkmcnt(8)
	v_mfma_f32_32x32x16_bf16 v[48:63], v[84:87], v[156:159], v[48:63]
	ds_read_b64_tr_b16 v[144:145], v244 offset:1024
	ds_read_b64_tr_b16 v[146:147], v244 offset:3072
	s_waitcnt lgkmcnt(8)
	v_mfma_f32_32x32x16_bf16 v[32:47], v[64:67], v[160:163], v[32:47]
	ds_read_b64_tr_b16 v[148:149], v244 offset:5120
	ds_read_b64_tr_b16 v[150:151], v244 offset:7168
	s_waitcnt lgkmcnt(8)
	v_mfma_f32_32x32x16_bf16 v[32:47], v[68:71], v[164:167], v[32:47]
	ds_read_b64_tr_b16 v[152:153], v244 offset:9216
	ds_read_b64_tr_b16 v[154:155], v244 offset:11264
	s_waitcnt lgkmcnt(8)
	v_mfma_f32_32x32x16_bf16 v[32:47], v[80:83], v[168:171], v[32:47]
	ds_read_b64_tr_b16 v[156:157], v244 offset:13312
	ds_read_b64_tr_b16 v[158:159], v244 offset:15360
	s_waitcnt lgkmcnt(8)
	v_mfma_f32_32x32x16_bf16 v[32:47], v[84:87], v[172:175], v[32:47]
	ds_read_b64_tr_b16 v[160:161], v244 offset:1536
	ds_read_b64_tr_b16 v[162:163], v244 offset:3584
	s_waitcnt lgkmcnt(8)
	v_mfma_f32_32x32x16_bf16 v[16:31], v[64:67], v[144:147], v[16:31]
	ds_read_b64_tr_b16 v[164:165], v244 offset:5632
	ds_read_b64_tr_b16 v[166:167], v244 offset:7680
	s_waitcnt lgkmcnt(8)
	v_mfma_f32_32x32x16_bf16 v[16:31], v[68:71], v[148:151], v[16:31]
	ds_read_b64_tr_b16 v[168:169], v244 offset:9728
	ds_read_b64_tr_b16 v[170:171], v244 offset:11776
	s_waitcnt lgkmcnt(8)
	v_mfma_f32_32x32x16_bf16 v[16:31], v[80:83], v[152:155], v[16:31]
	ds_read_b64_tr_b16 v[172:173], v244 offset:13824
	ds_read_b64_tr_b16 v[174:175], v244 offset:15872
	s_waitcnt lgkmcnt(8)
	v_mfma_f32_32x32x16_bf16 v[16:31], v[84:87], v[156:159], v[16:31]
	s_waitcnt lgkmcnt(6)
	v_mfma_f32_32x32x16_bf16 v[0:15], v[64:67], v[160:163], v[0:15]
	s_waitcnt lgkmcnt(4)
	v_mfma_f32_32x32x16_bf16 v[0:15], v[68:71], v[164:167], v[0:15]
	s_waitcnt lgkmcnt(2)
	v_mfma_f32_32x32x16_bf16 v[0:15], v[80:83], v[168:171], v[0:15]
	s_waitcnt lgkmcnt(0)
	v_mfma_f32_32x32x16_bf16 v[0:15], v[84:87], v[172:175], v[0:15]
	v_add_f32_e32 v245, v245, v246
	v_mov_b32_e32 v246, v245
	s_nop 1
	v_permlane32_swap_b32_e32 v245, v246
	v_add_f32_e32 v245, v245, v246
	v_cmp_gt_u32_e32 vcc, 32, v200
	v_lshl_add_u32 v247, v196, 2, s44
	s_and_saveexec_b64 s[42:43], vcc
	ds_write_b32 v247, v245
	s_or_b64 exec, exec, s[42:43]
	s_lshl_b64 s[2:3], s[40:41], 13
	s_or_b64 s[12:13], s[2:3], s[34:35]
	s_mul_i32 s1, s13, 0x3600
	s_mul_hi_u32 s2, s12, 0x3600
	s_add_i32 s1, s2, s1
	s_mul_i32 s14, s12, 0x3600
	s_lshl_b64 s[2:3], s[12:13], 12
	s_lshl_b64 s[12:13], s[12:13], 5
	s_add_u32 s14, s38, s14
	s_addc_u32 s1, s39, s1
	s_add_u32 s15, s72, s2
	s_addc_u32 s30, s73, s3
	s_lshl_b32 s31, s49, 8
	v_lshl_or_b32 v164, v198, 2, s52
	s_add_u32 s2, s14, s31
	s_addc_u32 s3, s1, 0
	s_add_u32 s2, s2, 0x11802c80
	s_addc_u32 s3, s3, 0
	v_subrev_u32_e32 v165, s52, v164
	v_lshl_add_u32 v166, v165, 2, s44
	s_add_u32 s14, s15, s31
	s_addc_u32 s15, s30, 0
	s_add_u32 s1, s74, s12
	s_addc_u32 s12, s75, s13
	s_lshl_b32 s13, s49, 2
	s_add_u32 s42, s1, s13
	s_addc_u32 s43, s12, 0
	v_lshlrev_b32_e32 v167, 1, v196
	v_mul_u32_u24_e32 v168, 0x3600, v164
	v_lshl_add_u32 v169, v164, 12, v167
	v_add_u32_e32 v168, v168, v167
	v_lshlrev_b32_e32 v170, 5, v164
	s_waitcnt lgkmcnt(0)
	ds_read_b32 v128, v166 offset:0
	ds_read_b32 v129, v166 offset:4
	ds_read_b32 v130, v166 offset:8
	ds_read_b32 v131, v166 offset:12
	ds_read_b32 v132, v166 offset:32
	ds_read_b32 v133, v166 offset:36
	ds_read_b32 v134, v166 offset:40
	ds_read_b32 v135, v166 offset:44
	ds_read_b32 v136, v166 offset:64
	ds_read_b32 v137, v166 offset:68
	ds_read_b32 v138, v166 offset:72
	ds_read_b32 v139, v166 offset:76
	ds_read_b32 v140, v166 offset:96
	ds_read_b32 v141, v166 offset:100
	ds_read_b32 v142, v166 offset:104
	ds_read_b32 v143, v166 offset:108
	v_mov_b32_e32 v171, v168
	global_load_ushort v64, v171, s[2:3] offset:0
	global_load_ushort v65, v171, s[2:3] offset:64
	global_load_ushort v66, v171, s[2:3] offset:128
	global_load_ushort v67, v171, s[2:3] offset:192
	v_add_u32_e32 v172, 0x3600, v168
	global_load_ushort v68, v172, s[2:3] offset:0
	global_load_ushort v69, v172, s[2:3] offset:64
	global_load_ushort v70, v172, s[2:3] offset:128
	global_load_ushort v71, v172, s[2:3] offset:192
	v_add_u32_e32 v173, 0x6c00, v168
	global_load_ushort v72, v173, s[2:3] offset:0
	global_load_ushort v73, v173, s[2:3] offset:64
	global_load_ushort v74, v173, s[2:3] offset:128
	global_load_ushort v75, v173, s[2:3] offset:192
	v_add_u32_e32 v174, 0xa200, v168
	global_load_ushort v76, v174, s[2:3] offset:0
	global_load_ushort v77, v174, s[2:3] offset:64
	global_load_ushort v78, v174, s[2:3] offset:128
	global_load_ushort v79, v174, s[2:3] offset:192
	v_add_u32_e32 v171, 0x1b000, v168
	global_load_ushort v80, v171, s[2:3] offset:0
	global_load_ushort v81, v171, s[2:3] offset:64
	global_load_ushort v82, v171, s[2:3] offset:128
	global_load_ushort v83, v171, s[2:3] offset:192
	v_add_u32_e32 v172, 0x1e600, v168
	global_load_ushort v84, v172, s[2:3] offset:0
	global_load_ushort v85, v172, s[2:3] offset:64
	global_load_ushort v86, v172, s[2:3] offset:128
	global_load_ushort v87, v172, s[2:3] offset:192
	v_add_u32_e32 v173, 0x21c00, v168
	global_load_ushort v88, v173, s[2:3] offset:0
	global_load_ushort v89, v173, s[2:3] offset:64
	global_load_ushort v90, v173, s[2:3] offset:128
	global_load_ushort v91, v173, s[2:3] offset:192
	v_add_u32_e32 v174, 0x25200, v168
	global_load_ushort v92, v174, s[2:3] offset:0
	global_load_ushort v93, v174, s[2:3] offset:64
	global_load_ushort v94, v174, s[2:3] offset:128
	global_load_ushort v95, v174, s[2:3] offset:192
	v_add_u32_e32 v171, 0x36000, v168
	global_load_ushort v96, v171, s[2:3] offset:0
	global_load_ushort v97, v171, s[2:3] offset:64
	global_load_ushort v98, v171, s[2:3] offset:128
	global_load_ushort v99, v171, s[2:3] offset:192
	v_add_u32_e32 v172, 0x39600, v168
	global_load_ushort v100, v172, s[2:3] offset:0
	global_load_ushort v101, v172, s[2:3] offset:64
	global_load_ushort v102, v172, s[2:3] offset:128
	global_load_ushort v103, v172, s[2:3] offset:192
	v_add_u32_e32 v173, 0x3cc00, v168
	global_load_ushort v104, v173, s[2:3] offset:0
	global_load_ushort v105, v173, s[2:3] offset:64
	global_load_ushort v106, v173, s[2:3] offset:128
	global_load_ushort v107, v173, s[2:3] offset:192
	v_add_u32_e32 v174, 0x40200, v168
	global_load_ushort v108, v174, s[2:3] offset:0
	global_load_ushort v109, v174, s[2:3] offset:64
	global_load_ushort v110, v174, s[2:3] offset:128
	global_load_ushort v111, v174, s[2:3] offset:192
	v_add_u32_e32 v171, 0x51000, v168
	global_load_ushort v112, v171, s[2:3] offset:0
	global_load_ushort v113, v171, s[2:3] offset:64
	global_load_ushort v114, v171, s[2:3] offset:128
	global_load_ushort v115, v171, s[2:3] offset:192
	v_add_u32_e32 v172, 0x54600, v168
	global_load_ushort v116, v172, s[2:3] offset:0
	global_load_ushort v117, v172, s[2:3] offset:64
	global_load_ushort v118, v172, s[2:3] offset:128
	global_load_ushort v119, v172, s[2:3] offset:192
	v_add_u32_e32 v173, 0x57c00, v168
	global_load_ushort v120, v173, s[2:3] offset:0
	global_load_ushort v121, v173, s[2:3] offset:64
	global_load_ushort v122, v173, s[2:3] offset:128
	global_load_ushort v123, v173, s[2:3] offset:192
	v_add_u32_e32 v174, 0x5b200, v168
	global_load_ushort v124, v174, s[2:3] offset:0
	global_load_ushort v125, v174, s[2:3] offset:64
	global_load_ushort v126, v174, s[2:3] offset:128
	global_load_ushort v127, v174, s[2:3] offset:192
	s_waitcnt lgkmcnt(0)
	v_rcp_f32_e32 v128, v128
	v_rcp_f32_e32 v129, v129
	v_rcp_f32_e32 v130, v130
	v_rcp_f32_e32 v131, v131
	v_rcp_f32_e32 v132, v132
	v_rcp_f32_e32 v133, v133
	v_rcp_f32_e32 v134, v134
	v_rcp_f32_e32 v135, v135
	v_rcp_f32_e32 v136, v136
	v_rcp_f32_e32 v137, v137
	v_rcp_f32_e32 v138, v138
	v_rcp_f32_e32 v139, v139
	v_rcp_f32_e32 v140, v140
	v_rcp_f32_e32 v141, v141
	v_rcp_f32_e32 v142, v142
	v_rcp_f32_e32 v143, v143
	v_mul_f32_e32 v48, v48, v128
	v_mul_f32_e32 v32, v32, v128
	v_mul_f32_e32 v16, v16, v128
	v_mul_f32_e32 v0, v0, v128
	v_mul_f32_e32 v49, v49, v129
	v_mul_f32_e32 v33, v33, v129
	v_mul_f32_e32 v17, v17, v129
	v_mul_f32_e32 v1, v1, v129
	v_mul_f32_e32 v50, v50, v130
	v_mul_f32_e32 v34, v34, v130
	v_mul_f32_e32 v18, v18, v130
	v_mul_f32_e32 v2, v2, v130
	v_mul_f32_e32 v51, v51, v131
	v_mul_f32_e32 v35, v35, v131
	v_mul_f32_e32 v19, v19, v131
	v_mul_f32_e32 v3, v3, v131
	v_mul_f32_e32 v52, v52, v132
	v_mul_f32_e32 v36, v36, v132
	v_mul_f32_e32 v20, v20, v132
	v_mul_f32_e32 v4, v4, v132
	v_mul_f32_e32 v53, v53, v133
	v_mul_f32_e32 v37, v37, v133
	v_mul_f32_e32 v21, v21, v133
	v_mul_f32_e32 v5, v5, v133
	v_mul_f32_e32 v54, v54, v134
	v_mul_f32_e32 v38, v38, v134
	v_mul_f32_e32 v22, v22, v134
	v_mul_f32_e32 v6, v6, v134
	v_mul_f32_e32 v55, v55, v135
	v_mul_f32_e32 v39, v39, v135
	v_mul_f32_e32 v23, v23, v135
	v_mul_f32_e32 v7, v7, v135
	v_mul_f32_e32 v56, v56, v136
	v_mul_f32_e32 v40, v40, v136
	v_mul_f32_e32 v24, v24, v136
	v_mul_f32_e32 v8, v8, v136
	v_mul_f32_e32 v57, v57, v137
	v_mul_f32_e32 v41, v41, v137
	v_mul_f32_e32 v25, v25, v137
	v_mul_f32_e32 v9, v9, v137
	v_mul_f32_e32 v58, v58, v138
	v_mul_f32_e32 v42, v42, v138
	v_mul_f32_e32 v26, v26, v138
	v_mul_f32_e32 v10, v10, v138
	v_mul_f32_e32 v59, v59, v139
	v_mul_f32_e32 v43, v43, v139
	v_mul_f32_e32 v27, v27, v139
	v_mul_f32_e32 v11, v11, v139
	v_mul_f32_e32 v60, v60, v140
	v_mul_f32_e32 v44, v44, v140
	v_mul_f32_e32 v28, v28, v140
	v_mul_f32_e32 v12, v12, v140
	v_mul_f32_e32 v61, v61, v141
	v_mul_f32_e32 v45, v45, v141
	v_mul_f32_e32 v29, v29, v141
	v_mul_f32_e32 v13, v13, v141
	v_mul_f32_e32 v62, v62, v142
	v_mul_f32_e32 v46, v46, v142
	v_mul_f32_e32 v30, v30, v142
	v_mul_f32_e32 v14, v14, v142
	v_mul_f32_e32 v63, v63, v143
	v_mul_f32_e32 v47, v47, v143
	v_mul_f32_e32 v31, v31, v143
	v_mul_f32_e32 v15, v15, v143
	s_waitcnt vmcnt(60)
	v_mov_b32_e32 v182, v169
	v_lshlrev_b32_e32 v64, 16, v64
	v_lshlrev_b32_e32 v65, 16, v65
	v_lshlrev_b32_e32 v66, 16, v66
	v_lshlrev_b32_e32 v67, 16, v67
	v_mul_f32_e32 v208, 0xbfb8aa3b, v64
	v_mul_f32_e32 v214, 0xbfb8aa3b, v65
	v_mul_f32_e32 v220, 0xbfb8aa3b, v66
	v_mul_f32_e32 v226, 0xbfb8aa3b, v67
	v_exp_f32_e32 v208, v208
	v_exp_f32_e32 v214, v214
	v_exp_f32_e32 v220, v220
	v_exp_f32_e32 v226, v226
	v_add_f32_e32 v208, 1.0, v208
	v_add_f32_e32 v214, 1.0, v214
	v_add_f32_e32 v220, 1.0, v220
	v_add_f32_e32 v226, 1.0, v226
	v_div_scale_f32 v209, s[12:13], v208, v208, v64
	v_div_scale_f32 v215, s[12:13], v214, v214, v65
	v_div_scale_f32 v221, s[12:13], v220, v220, v66
	v_div_scale_f32 v227, s[12:13], v226, v226, v67
	v_rcp_f32_e32 v210, v209
	v_rcp_f32_e32 v216, v215
	v_rcp_f32_e32 v222, v221
	v_rcp_f32_e32 v228, v227
	v_fma_f32 v211, -v209, v210, 1.0
	v_fma_f32 v217, -v215, v216, 1.0
	v_fma_f32 v223, -v221, v222, 1.0
	v_fma_f32 v229, -v227, v228, 1.0
	v_fmac_f32_e32 v210, v211, v210
	v_fmac_f32_e32 v216, v217, v216
	v_fmac_f32_e32 v222, v223, v222
	v_fmac_f32_e32 v228, v229, v228
	v_div_scale_f32 v211, vcc, v64, v208, v64
	v_mul_f32_e32 v212, v211, v210
	v_fma_f32 v213, -v209, v212, v211
	v_fmac_f32_e32 v212, v213, v210
	v_fma_f32 v209, -v209, v212, v211
	v_div_fmas_f32 v209, v209, v210, v212
	v_div_fixup_f32 v64, v209, v208, v64
	v_div_scale_f32 v217, vcc, v65, v214, v65
	v_mul_f32_e32 v218, v217, v216
	v_fma_f32 v219, -v215, v218, v217
	v_fmac_f32_e32 v218, v219, v216
	v_fma_f32 v215, -v215, v218, v217
	v_div_fmas_f32 v215, v215, v216, v218
	v_div_fixup_f32 v65, v215, v214, v65
	v_div_scale_f32 v223, vcc, v66, v220, v66
	v_mul_f32_e32 v224, v223, v222
	v_fma_f32 v225, -v221, v224, v223
	v_fmac_f32_e32 v224, v225, v222
	v_fma_f32 v221, -v221, v224, v223
	v_div_fmas_f32 v221, v221, v222, v224
	v_div_fixup_f32 v66, v221, v220, v66
	v_div_scale_f32 v229, vcc, v67, v226, v67
	v_mul_f32_e32 v230, v229, v228
	v_fma_f32 v231, -v227, v230, v229
	v_fmac_f32_e32 v230, v231, v228
	v_fma_f32 v227, -v227, v230, v229
	v_div_fmas_f32 v227, v227, v228, v230
	v_div_fixup_f32 v67, v227, v226, v67
	v_mul_f32_e32 v48, v48, v64
	v_mul_f32_e32 v32, v32, v65
	v_mul_f32_e32 v16, v16, v66
	v_mul_f32_e32 v0, v0, v67
	v_mul_f32_e32 v148, v32, v32
	v_fmac_f32_e32 v148, v48, v48
	v_fmac_f32_e32 v148, v16, v16
	v_fmac_f32_e32 v148, v0, v0
	v_cvt_pk_bf16_f32 v64, v48, v177
	v_cvt_pk_bf16_f32 v65, v32, v177
	v_cvt_pk_bf16_f32 v66, v16, v177
	v_cvt_pk_bf16_f32 v67, v0, v177
	global_store_short v182, v64, s[14:15] offset:0
	global_store_short v182, v65, s[14:15] offset:64
	global_store_short v182, v66, s[14:15] offset:128
	global_store_short v182, v67, s[14:15] offset:192
	s_waitcnt vmcnt(60)
	v_add_u32_e32 v175, 0x1000, v169
	v_lshlrev_b32_e32 v68, 16, v68
	v_lshlrev_b32_e32 v69, 16, v69
	v_lshlrev_b32_e32 v70, 16, v70
	v_lshlrev_b32_e32 v71, 16, v71
	v_mul_f32_e32 v208, 0xbfb8aa3b, v68
	v_mul_f32_e32 v214, 0xbfb8aa3b, v69
	v_mul_f32_e32 v220, 0xbfb8aa3b, v70
	v_mul_f32_e32 v226, 0xbfb8aa3b, v71
	v_exp_f32_e32 v208, v208
	v_exp_f32_e32 v214, v214
	v_exp_f32_e32 v220, v220
	v_exp_f32_e32 v226, v226
	v_add_f32_e32 v208, 1.0, v208
	v_add_f32_e32 v214, 1.0, v214
	v_add_f32_e32 v220, 1.0, v220
	v_add_f32_e32 v226, 1.0, v226
	v_div_scale_f32 v209, s[12:13], v208, v208, v68
	v_div_scale_f32 v215, s[12:13], v214, v214, v69
	v_div_scale_f32 v221, s[12:13], v220, v220, v70
	v_div_scale_f32 v227, s[12:13], v226, v226, v71
	v_rcp_f32_e32 v210, v209
	v_rcp_f32_e32 v216, v215
	v_rcp_f32_e32 v222, v221
	v_rcp_f32_e32 v228, v227
	v_fma_f32 v211, -v209, v210, 1.0
	v_fma_f32 v217, -v215, v216, 1.0
	v_fma_f32 v223, -v221, v222, 1.0
	v_fma_f32 v229, -v227, v228, 1.0
	v_fmac_f32_e32 v210, v211, v210
	v_fmac_f32_e32 v216, v217, v216
	v_fmac_f32_e32 v222, v223, v222
	v_fmac_f32_e32 v228, v229, v228
	v_div_scale_f32 v211, vcc, v68, v208, v68
	v_mul_f32_e32 v212, v211, v210
	v_fma_f32 v213, -v209, v212, v211
	v_fmac_f32_e32 v212, v213, v210
	v_fma_f32 v209, -v209, v212, v211
	v_div_fmas_f32 v209, v209, v210, v212
	v_div_fixup_f32 v68, v209, v208, v68
	v_div_scale_f32 v217, vcc, v69, v214, v69
	v_mul_f32_e32 v218, v217, v216
	v_fma_f32 v219, -v215, v218, v217
	v_fmac_f32_e32 v218, v219, v216
	v_fma_f32 v215, -v215, v218, v217
	v_div_fmas_f32 v215, v215, v216, v218
	v_div_fixup_f32 v69, v215, v214, v69
	v_div_scale_f32 v223, vcc, v70, v220, v70
	v_mul_f32_e32 v224, v223, v222
	v_fma_f32 v225, -v221, v224, v223
	v_fmac_f32_e32 v224, v225, v222
	v_fma_f32 v221, -v221, v224, v223
	v_div_fmas_f32 v221, v221, v222, v224
	v_div_fixup_f32 v70, v221, v220, v70
	v_div_scale_f32 v229, vcc, v71, v226, v71
	v_mul_f32_e32 v230, v229, v228
	v_fma_f32 v231, -v227, v230, v229
	v_fmac_f32_e32 v230, v231, v228
	v_fma_f32 v227, -v227, v230, v229
	v_div_fmas_f32 v227, v227, v228, v230
	v_div_fixup_f32 v71, v227, v226, v71
	v_mul_f32_e32 v49, v49, v68
	v_mul_f32_e32 v33, v33, v69
	v_mul_f32_e32 v17, v17, v70
	v_mul_f32_e32 v1, v1, v71
	v_mul_f32_e32 v149, v33, v33
	v_fmac_f32_e32 v149, v49, v49
	v_fmac_f32_e32 v149, v17, v17
	v_fmac_f32_e32 v149, v1, v1
	v_cvt_pk_bf16_f32 v68, v49, v177
	v_cvt_pk_bf16_f32 v69, v33, v177
	v_cvt_pk_bf16_f32 v70, v17, v177
	v_cvt_pk_bf16_f32 v71, v1, v177
	global_store_short v175, v68, s[14:15] offset:0
	global_store_short v175, v69, s[14:15] offset:64
	global_store_short v175, v70, s[14:15] offset:128
	global_store_short v175, v71, s[14:15] offset:192
	s_waitcnt vmcnt(60)
	v_add_u32_e32 v182, 0x2000, v169
	v_lshlrev_b32_e32 v72, 16, v72
	v_lshlrev_b32_e32 v73, 16, v73
	v_lshlrev_b32_e32 v74, 16, v74
	v_lshlrev_b32_e32 v75, 16, v75
	v_mul_f32_e32 v208, 0xbfb8aa3b, v72
	v_mul_f32_e32 v214, 0xbfb8aa3b, v73
	v_mul_f32_e32 v220, 0xbfb8aa3b, v74
	v_mul_f32_e32 v226, 0xbfb8aa3b, v75
	v_exp_f32_e32 v208, v208
	v_exp_f32_e32 v214, v214
	v_exp_f32_e32 v220, v220
	v_exp_f32_e32 v226, v226
	v_add_f32_e32 v208, 1.0, v208
	v_add_f32_e32 v214, 1.0, v214
	v_add_f32_e32 v220, 1.0, v220
	v_add_f32_e32 v226, 1.0, v226
	v_div_scale_f32 v209, s[12:13], v208, v208, v72
	v_div_scale_f32 v215, s[12:13], v214, v214, v73
	v_div_scale_f32 v221, s[12:13], v220, v220, v74
	v_div_scale_f32 v227, s[12:13], v226, v226, v75
	v_rcp_f32_e32 v210, v209
	v_rcp_f32_e32 v216, v215
	v_rcp_f32_e32 v222, v221
	v_rcp_f32_e32 v228, v227
	v_fma_f32 v211, -v209, v210, 1.0
	v_fma_f32 v217, -v215, v216, 1.0
	v_fma_f32 v223, -v221, v222, 1.0
	v_fma_f32 v229, -v227, v228, 1.0
	v_fmac_f32_e32 v210, v211, v210
	v_fmac_f32_e32 v216, v217, v216
	v_fmac_f32_e32 v222, v223, v222
	v_fmac_f32_e32 v228, v229, v228
	v_div_scale_f32 v211, vcc, v72, v208, v72
	v_mul_f32_e32 v212, v211, v210
	v_fma_f32 v213, -v209, v212, v211
	v_fmac_f32_e32 v212, v213, v210
	v_fma_f32 v209, -v209, v212, v211
	v_div_fmas_f32 v209, v209, v210, v212
	v_div_fixup_f32 v72, v209, v208, v72
	v_div_scale_f32 v217, vcc, v73, v214, v73
	v_mul_f32_e32 v218, v217, v216
	v_fma_f32 v219, -v215, v218, v217
	v_fmac_f32_e32 v218, v219, v216
	v_fma_f32 v215, -v215, v218, v217
	v_div_fmas_f32 v215, v215, v216, v218
	v_div_fixup_f32 v73, v215, v214, v73
	v_div_scale_f32 v223, vcc, v74, v220, v74
	v_mul_f32_e32 v224, v223, v222
	v_fma_f32 v225, -v221, v224, v223
	v_fmac_f32_e32 v224, v225, v222
	v_fma_f32 v221, -v221, v224, v223
	v_div_fmas_f32 v221, v221, v222, v224
	v_div_fixup_f32 v74, v221, v220, v74
	v_div_scale_f32 v229, vcc, v75, v226, v75
	v_mul_f32_e32 v230, v229, v228
	v_fma_f32 v231, -v227, v230, v229
	v_fmac_f32_e32 v230, v231, v228
	v_fma_f32 v227, -v227, v230, v229
	v_div_fmas_f32 v227, v227, v228, v230
	v_div_fixup_f32 v75, v227, v226, v75
	v_mul_f32_e32 v50, v50, v72
	v_mul_f32_e32 v34, v34, v73
	v_mul_f32_e32 v18, v18, v74
	v_mul_f32_e32 v2, v2, v75
	v_mul_f32_e32 v150, v34, v34
	v_fmac_f32_e32 v150, v50, v50
	v_fmac_f32_e32 v150, v18, v18
	v_fmac_f32_e32 v150, v2, v2
	v_cvt_pk_bf16_f32 v72, v50, v177
	v_cvt_pk_bf16_f32 v73, v34, v177
	v_cvt_pk_bf16_f32 v74, v18, v177
	v_cvt_pk_bf16_f32 v75, v2, v177
	global_store_short v182, v72, s[14:15] offset:0
	global_store_short v182, v73, s[14:15] offset:64
	global_store_short v182, v74, s[14:15] offset:128
	global_store_short v182, v75, s[14:15] offset:192
	s_waitcnt vmcnt(60)
	v_add_u32_e32 v175, 0x3000, v169
	v_lshlrev_b32_e32 v76, 16, v76
	v_lshlrev_b32_e32 v77, 16, v77
	v_lshlrev_b32_e32 v78, 16, v78
	v_lshlrev_b32_e32 v79, 16, v79
	v_mul_f32_e32 v208, 0xbfb8aa3b, v76
	v_mul_f32_e32 v214, 0xbfb8aa3b, v77
	v_mul_f32_e32 v220, 0xbfb8aa3b, v78
	v_mul_f32_e32 v226, 0xbfb8aa3b, v79
	v_exp_f32_e32 v208, v208
	v_exp_f32_e32 v214, v214
	v_exp_f32_e32 v220, v220
	v_exp_f32_e32 v226, v226
	v_add_f32_e32 v208, 1.0, v208
	v_add_f32_e32 v214, 1.0, v214
	v_add_f32_e32 v220, 1.0, v220
	v_add_f32_e32 v226, 1.0, v226
	v_div_scale_f32 v209, s[12:13], v208, v208, v76
	v_div_scale_f32 v215, s[12:13], v214, v214, v77
	v_div_scale_f32 v221, s[12:13], v220, v220, v78
	v_div_scale_f32 v227, s[12:13], v226, v226, v79
	v_rcp_f32_e32 v210, v209
	v_rcp_f32_e32 v216, v215
	v_rcp_f32_e32 v222, v221
	v_rcp_f32_e32 v228, v227
	v_fma_f32 v211, -v209, v210, 1.0
	v_fma_f32 v217, -v215, v216, 1.0
	v_fma_f32 v223, -v221, v222, 1.0
	v_fma_f32 v229, -v227, v228, 1.0
	v_fmac_f32_e32 v210, v211, v210
	v_fmac_f32_e32 v216, v217, v216
	v_fmac_f32_e32 v222, v223, v222
	v_fmac_f32_e32 v228, v229, v228
	v_div_scale_f32 v211, vcc, v76, v208, v76
	v_mul_f32_e32 v212, v211, v210
	v_fma_f32 v213, -v209, v212, v211
	v_fmac_f32_e32 v212, v213, v210
	v_fma_f32 v209, -v209, v212, v211
	v_div_fmas_f32 v209, v209, v210, v212
	v_div_fixup_f32 v76, v209, v208, v76
	v_div_scale_f32 v217, vcc, v77, v214, v77
	v_mul_f32_e32 v218, v217, v216
	v_fma_f32 v219, -v215, v218, v217
	v_fmac_f32_e32 v218, v219, v216
	v_fma_f32 v215, -v215, v218, v217
	v_div_fmas_f32 v215, v215, v216, v218
	v_div_fixup_f32 v77, v215, v214, v77
	v_div_scale_f32 v223, vcc, v78, v220, v78
	v_mul_f32_e32 v224, v223, v222
	v_fma_f32 v225, -v221, v224, v223
	v_fmac_f32_e32 v224, v225, v222
	v_fma_f32 v221, -v221, v224, v223
	v_div_fmas_f32 v221, v221, v222, v224
	v_div_fixup_f32 v78, v221, v220, v78
	v_div_scale_f32 v229, vcc, v79, v226, v79
	v_mul_f32_e32 v230, v229, v228
	v_fma_f32 v231, -v227, v230, v229
	v_fmac_f32_e32 v230, v231, v228
	v_fma_f32 v227, -v227, v230, v229
	v_div_fmas_f32 v227, v227, v228, v230
	v_div_fixup_f32 v79, v227, v226, v79
	v_mul_f32_e32 v51, v51, v76
	v_mul_f32_e32 v35, v35, v77
	v_mul_f32_e32 v19, v19, v78
	v_mul_f32_e32 v3, v3, v79
	v_mul_f32_e32 v151, v35, v35
	v_fmac_f32_e32 v151, v51, v51
	v_fmac_f32_e32 v151, v19, v19
	v_fmac_f32_e32 v151, v3, v3
	v_cvt_pk_bf16_f32 v76, v51, v177
	v_cvt_pk_bf16_f32 v77, v35, v177
	v_cvt_pk_bf16_f32 v78, v19, v177
	v_cvt_pk_bf16_f32 v79, v3, v177
	global_store_short v175, v76, s[14:15] offset:0
	global_store_short v175, v77, s[14:15] offset:64
	global_store_short v175, v78, s[14:15] offset:128
	global_store_short v175, v79, s[14:15] offset:192
	s_waitcnt vmcnt(60)
	v_add_u32_e32 v182, 0x8000, v169
	v_lshlrev_b32_e32 v80, 16, v80
	v_lshlrev_b32_e32 v81, 16, v81
	v_lshlrev_b32_e32 v82, 16, v82
	v_lshlrev_b32_e32 v83, 16, v83
	v_mul_f32_e32 v208, 0xbfb8aa3b, v80
	v_mul_f32_e32 v214, 0xbfb8aa3b, v81
	v_mul_f32_e32 v220, 0xbfb8aa3b, v82
	v_mul_f32_e32 v226, 0xbfb8aa3b, v83
	v_exp_f32_e32 v208, v208
	v_exp_f32_e32 v214, v214
	v_exp_f32_e32 v220, v220
	v_exp_f32_e32 v226, v226
	v_add_f32_e32 v208, 1.0, v208
	v_add_f32_e32 v214, 1.0, v214
	v_add_f32_e32 v220, 1.0, v220
	v_add_f32_e32 v226, 1.0, v226
	v_div_scale_f32 v209, s[12:13], v208, v208, v80
	v_div_scale_f32 v215, s[12:13], v214, v214, v81
	v_div_scale_f32 v221, s[12:13], v220, v220, v82
	v_div_scale_f32 v227, s[12:13], v226, v226, v83
	v_rcp_f32_e32 v210, v209
	v_rcp_f32_e32 v216, v215
	v_rcp_f32_e32 v222, v221
	v_rcp_f32_e32 v228, v227
	v_fma_f32 v211, -v209, v210, 1.0
	v_fma_f32 v217, -v215, v216, 1.0
	v_fma_f32 v223, -v221, v222, 1.0
	v_fma_f32 v229, -v227, v228, 1.0
	v_fmac_f32_e32 v210, v211, v210
	v_fmac_f32_e32 v216, v217, v216
	v_fmac_f32_e32 v222, v223, v222
	v_fmac_f32_e32 v228, v229, v228
	v_div_scale_f32 v211, vcc, v80, v208, v80
	v_mul_f32_e32 v212, v211, v210
	v_fma_f32 v213, -v209, v212, v211
	v_fmac_f32_e32 v212, v213, v210
	v_fma_f32 v209, -v209, v212, v211
	v_div_fmas_f32 v209, v209, v210, v212
	v_div_fixup_f32 v80, v209, v208, v80
	v_div_scale_f32 v217, vcc, v81, v214, v81
	v_mul_f32_e32 v218, v217, v216
	v_fma_f32 v219, -v215, v218, v217
	v_fmac_f32_e32 v218, v219, v216
	v_fma_f32 v215, -v215, v218, v217
	v_div_fmas_f32 v215, v215, v216, v218
	v_div_fixup_f32 v81, v215, v214, v81
	v_div_scale_f32 v223, vcc, v82, v220, v82
	v_mul_f32_e32 v224, v223, v222
	v_fma_f32 v225, -v221, v224, v223
	v_fmac_f32_e32 v224, v225, v222
	v_fma_f32 v221, -v221, v224, v223
	v_div_fmas_f32 v221, v221, v222, v224
	v_div_fixup_f32 v82, v221, v220, v82
	v_div_scale_f32 v229, vcc, v83, v226, v83
	v_mul_f32_e32 v230, v229, v228
	v_fma_f32 v231, -v227, v230, v229
	v_fmac_f32_e32 v230, v231, v228
	v_fma_f32 v227, -v227, v230, v229
	v_div_fmas_f32 v227, v227, v228, v230
	v_div_fixup_f32 v83, v227, v226, v83
	v_mul_f32_e32 v52, v52, v80
	v_mul_f32_e32 v36, v36, v81
	v_mul_f32_e32 v20, v20, v82
	v_mul_f32_e32 v4, v4, v83
	v_mul_f32_e32 v152, v36, v36
	v_fmac_f32_e32 v152, v52, v52
	v_fmac_f32_e32 v152, v20, v20
	v_fmac_f32_e32 v152, v4, v4
	v_cvt_pk_bf16_f32 v80, v52, v177
	v_cvt_pk_bf16_f32 v81, v36, v177
	v_cvt_pk_bf16_f32 v82, v20, v177
	v_cvt_pk_bf16_f32 v83, v4, v177
	global_store_short v182, v80, s[14:15] offset:0
	global_store_short v182, v81, s[14:15] offset:64
	global_store_short v182, v82, s[14:15] offset:128
	global_store_short v182, v83, s[14:15] offset:192
	s_waitcnt vmcnt(60)
	v_add_u32_e32 v175, 0x9000, v169
	v_lshlrev_b32_e32 v84, 16, v84
	v_lshlrev_b32_e32 v85, 16, v85
	v_lshlrev_b32_e32 v86, 16, v86
	v_lshlrev_b32_e32 v87, 16, v87
	v_mul_f32_e32 v208, 0xbfb8aa3b, v84
	v_mul_f32_e32 v214, 0xbfb8aa3b, v85
	v_mul_f32_e32 v220, 0xbfb8aa3b, v86
	v_mul_f32_e32 v226, 0xbfb8aa3b, v87
	v_exp_f32_e32 v208, v208
	v_exp_f32_e32 v214, v214
	v_exp_f32_e32 v220, v220
	v_exp_f32_e32 v226, v226
	v_add_f32_e32 v208, 1.0, v208
	v_add_f32_e32 v214, 1.0, v214
	v_add_f32_e32 v220, 1.0, v220
	v_add_f32_e32 v226, 1.0, v226
	v_div_scale_f32 v209, s[12:13], v208, v208, v84
	v_div_scale_f32 v215, s[12:13], v214, v214, v85
	v_div_scale_f32 v221, s[12:13], v220, v220, v86
	v_div_scale_f32 v227, s[12:13], v226, v226, v87
	v_rcp_f32_e32 v210, v209
	v_rcp_f32_e32 v216, v215
	v_rcp_f32_e32 v222, v221
	v_rcp_f32_e32 v228, v227
	v_fma_f32 v211, -v209, v210, 1.0
	v_fma_f32 v217, -v215, v216, 1.0
	v_fma_f32 v223, -v221, v222, 1.0
	v_fma_f32 v229, -v227, v228, 1.0
	v_fmac_f32_e32 v210, v211, v210
	v_fmac_f32_e32 v216, v217, v216
	v_fmac_f32_e32 v222, v223, v222
	v_fmac_f32_e32 v228, v229, v228
	v_div_scale_f32 v211, vcc, v84, v208, v84
	v_mul_f32_e32 v212, v211, v210
	v_fma_f32 v213, -v209, v212, v211
	v_fmac_f32_e32 v212, v213, v210
	v_fma_f32 v209, -v209, v212, v211
	v_div_fmas_f32 v209, v209, v210, v212
	v_div_fixup_f32 v84, v209, v208, v84
	v_div_scale_f32 v217, vcc, v85, v214, v85
	v_mul_f32_e32 v218, v217, v216
	v_fma_f32 v219, -v215, v218, v217
	v_fmac_f32_e32 v218, v219, v216
	v_fma_f32 v215, -v215, v218, v217
	v_div_fmas_f32 v215, v215, v216, v218
	v_div_fixup_f32 v85, v215, v214, v85
	v_div_scale_f32 v223, vcc, v86, v220, v86
	v_mul_f32_e32 v224, v223, v222
	v_fma_f32 v225, -v221, v224, v223
	v_fmac_f32_e32 v224, v225, v222
	v_fma_f32 v221, -v221, v224, v223
	v_div_fmas_f32 v221, v221, v222, v224
	v_div_fixup_f32 v86, v221, v220, v86
	v_div_scale_f32 v229, vcc, v87, v226, v87
	v_mul_f32_e32 v230, v229, v228
	v_fma_f32 v231, -v227, v230, v229
	v_fmac_f32_e32 v230, v231, v228
	v_fma_f32 v227, -v227, v230, v229
	v_div_fmas_f32 v227, v227, v228, v230
	v_div_fixup_f32 v87, v227, v226, v87
	v_mul_f32_e32 v53, v53, v84
	v_mul_f32_e32 v37, v37, v85
	v_mul_f32_e32 v21, v21, v86
	v_mul_f32_e32 v5, v5, v87
	v_mul_f32_e32 v153, v37, v37
	v_fmac_f32_e32 v153, v53, v53
	v_fmac_f32_e32 v153, v21, v21
	v_fmac_f32_e32 v153, v5, v5
	v_cvt_pk_bf16_f32 v84, v53, v177
	v_cvt_pk_bf16_f32 v85, v37, v177
	v_cvt_pk_bf16_f32 v86, v21, v177
	v_cvt_pk_bf16_f32 v87, v5, v177
	global_store_short v175, v84, s[14:15] offset:0
	global_store_short v175, v85, s[14:15] offset:64
	global_store_short v175, v86, s[14:15] offset:128
	global_store_short v175, v87, s[14:15] offset:192
	s_waitcnt vmcnt(60)
	v_add_u32_e32 v182, 0xa000, v169
	v_lshlrev_b32_e32 v88, 16, v88
	v_lshlrev_b32_e32 v89, 16, v89
	v_lshlrev_b32_e32 v90, 16, v90
	v_lshlrev_b32_e32 v91, 16, v91
	v_mul_f32_e32 v208, 0xbfb8aa3b, v88
	v_mul_f32_e32 v214, 0xbfb8aa3b, v89
	v_mul_f32_e32 v220, 0xbfb8aa3b, v90
	v_mul_f32_e32 v226, 0xbfb8aa3b, v91
	v_exp_f32_e32 v208, v208
	v_exp_f32_e32 v214, v214
	v_exp_f32_e32 v220, v220
	v_exp_f32_e32 v226, v226
	v_add_f32_e32 v208, 1.0, v208
	v_add_f32_e32 v214, 1.0, v214
	v_add_f32_e32 v220, 1.0, v220
	v_add_f32_e32 v226, 1.0, v226
	v_div_scale_f32 v209, s[12:13], v208, v208, v88
	v_div_scale_f32 v215, s[12:13], v214, v214, v89
	v_div_scale_f32 v221, s[12:13], v220, v220, v90
	v_div_scale_f32 v227, s[12:13], v226, v226, v91
	v_rcp_f32_e32 v210, v209
	v_rcp_f32_e32 v216, v215
	v_rcp_f32_e32 v222, v221
	v_rcp_f32_e32 v228, v227
	v_fma_f32 v211, -v209, v210, 1.0
	v_fma_f32 v217, -v215, v216, 1.0
	v_fma_f32 v223, -v221, v222, 1.0
	v_fma_f32 v229, -v227, v228, 1.0
	v_fmac_f32_e32 v210, v211, v210
	v_fmac_f32_e32 v216, v217, v216
	v_fmac_f32_e32 v222, v223, v222
	v_fmac_f32_e32 v228, v229, v228
	v_div_scale_f32 v211, vcc, v88, v208, v88
	v_mul_f32_e32 v212, v211, v210
	v_fma_f32 v213, -v209, v212, v211
	v_fmac_f32_e32 v212, v213, v210
	v_fma_f32 v209, -v209, v212, v211
	v_div_fmas_f32 v209, v209, v210, v212
	v_div_fixup_f32 v88, v209, v208, v88
	v_div_scale_f32 v217, vcc, v89, v214, v89
	v_mul_f32_e32 v218, v217, v216
	v_fma_f32 v219, -v215, v218, v217
	v_fmac_f32_e32 v218, v219, v216
	v_fma_f32 v215, -v215, v218, v217
	v_div_fmas_f32 v215, v215, v216, v218
	v_div_fixup_f32 v89, v215, v214, v89
	v_div_scale_f32 v223, vcc, v90, v220, v90
	v_mul_f32_e32 v224, v223, v222
	v_fma_f32 v225, -v221, v224, v223
	v_fmac_f32_e32 v224, v225, v222
	v_fma_f32 v221, -v221, v224, v223
	v_div_fmas_f32 v221, v221, v222, v224
	v_div_fixup_f32 v90, v221, v220, v90
	v_div_scale_f32 v229, vcc, v91, v226, v91
	v_mul_f32_e32 v230, v229, v228
	v_fma_f32 v231, -v227, v230, v229
	v_fmac_f32_e32 v230, v231, v228
	v_fma_f32 v227, -v227, v230, v229
	v_div_fmas_f32 v227, v227, v228, v230
	v_div_fixup_f32 v91, v227, v226, v91
	v_mul_f32_e32 v54, v54, v88
	v_mul_f32_e32 v38, v38, v89
	v_mul_f32_e32 v22, v22, v90
	v_mul_f32_e32 v6, v6, v91
	v_mul_f32_e32 v154, v38, v38
	v_fmac_f32_e32 v154, v54, v54
	v_fmac_f32_e32 v154, v22, v22
	v_fmac_f32_e32 v154, v6, v6
	v_cvt_pk_bf16_f32 v88, v54, v177
	v_cvt_pk_bf16_f32 v89, v38, v177
	v_cvt_pk_bf16_f32 v90, v22, v177
	v_cvt_pk_bf16_f32 v91, v6, v177
	global_store_short v182, v88, s[14:15] offset:0
	global_store_short v182, v89, s[14:15] offset:64
	global_store_short v182, v90, s[14:15] offset:128
	global_store_short v182, v91, s[14:15] offset:192
	s_waitcnt vmcnt(60)
	v_add_u32_e32 v175, 0xb000, v169
	v_lshlrev_b32_e32 v92, 16, v92
	v_lshlrev_b32_e32 v93, 16, v93
	v_lshlrev_b32_e32 v94, 16, v94
	v_lshlrev_b32_e32 v95, 16, v95
	v_mul_f32_e32 v208, 0xbfb8aa3b, v92
	v_mul_f32_e32 v214, 0xbfb8aa3b, v93
	v_mul_f32_e32 v220, 0xbfb8aa3b, v94
	v_mul_f32_e32 v226, 0xbfb8aa3b, v95
	v_exp_f32_e32 v208, v208
	v_exp_f32_e32 v214, v214
	v_exp_f32_e32 v220, v220
	v_exp_f32_e32 v226, v226
	v_add_f32_e32 v208, 1.0, v208
	v_add_f32_e32 v214, 1.0, v214
	v_add_f32_e32 v220, 1.0, v220
	v_add_f32_e32 v226, 1.0, v226
	v_div_scale_f32 v209, s[12:13], v208, v208, v92
	v_div_scale_f32 v215, s[12:13], v214, v214, v93
	v_div_scale_f32 v221, s[12:13], v220, v220, v94
	v_div_scale_f32 v227, s[12:13], v226, v226, v95
	v_rcp_f32_e32 v210, v209
	v_rcp_f32_e32 v216, v215
	v_rcp_f32_e32 v222, v221
	v_rcp_f32_e32 v228, v227
	v_fma_f32 v211, -v209, v210, 1.0
	v_fma_f32 v217, -v215, v216, 1.0
	v_fma_f32 v223, -v221, v222, 1.0
	v_fma_f32 v229, -v227, v228, 1.0
	v_fmac_f32_e32 v210, v211, v210
	v_fmac_f32_e32 v216, v217, v216
	v_fmac_f32_e32 v222, v223, v222
	v_fmac_f32_e32 v228, v229, v228
	v_div_scale_f32 v211, vcc, v92, v208, v92
	v_mul_f32_e32 v212, v211, v210
	v_fma_f32 v213, -v209, v212, v211
	v_fmac_f32_e32 v212, v213, v210
	v_fma_f32 v209, -v209, v212, v211
	v_div_fmas_f32 v209, v209, v210, v212
	v_div_fixup_f32 v92, v209, v208, v92
	v_div_scale_f32 v217, vcc, v93, v214, v93
	v_mul_f32_e32 v218, v217, v216
	v_fma_f32 v219, -v215, v218, v217
	v_fmac_f32_e32 v218, v219, v216
	v_fma_f32 v215, -v215, v218, v217
	v_div_fmas_f32 v215, v215, v216, v218
	v_div_fixup_f32 v93, v215, v214, v93
	v_div_scale_f32 v223, vcc, v94, v220, v94
	v_mul_f32_e32 v224, v223, v222
	v_fma_f32 v225, -v221, v224, v223
	v_fmac_f32_e32 v224, v225, v222
	v_fma_f32 v221, -v221, v224, v223
	v_div_fmas_f32 v221, v221, v222, v224
	v_div_fixup_f32 v94, v221, v220, v94
	v_div_scale_f32 v229, vcc, v95, v226, v95
	v_mul_f32_e32 v230, v229, v228
	v_fma_f32 v231, -v227, v230, v229
	v_fmac_f32_e32 v230, v231, v228
	v_fma_f32 v227, -v227, v230, v229
	v_div_fmas_f32 v227, v227, v228, v230
	v_div_fixup_f32 v95, v227, v226, v95
	v_mul_f32_e32 v55, v55, v92
	v_mul_f32_e32 v39, v39, v93
	v_mul_f32_e32 v23, v23, v94
	v_mul_f32_e32 v7, v7, v95
	v_mul_f32_e32 v155, v39, v39
	v_fmac_f32_e32 v155, v55, v55
	v_fmac_f32_e32 v155, v23, v23
	v_fmac_f32_e32 v155, v7, v7
	v_cvt_pk_bf16_f32 v92, v55, v177
	v_cvt_pk_bf16_f32 v93, v39, v177
	v_cvt_pk_bf16_f32 v94, v23, v177
	v_cvt_pk_bf16_f32 v95, v7, v177
	global_store_short v175, v92, s[14:15] offset:0
	global_store_short v175, v93, s[14:15] offset:64
	global_store_short v175, v94, s[14:15] offset:128
	global_store_short v175, v95, s[14:15] offset:192
	s_waitcnt vmcnt(60)
	v_add_u32_e32 v182, 0x10000, v169
	v_lshlrev_b32_e32 v96, 16, v96
	v_lshlrev_b32_e32 v97, 16, v97
	v_lshlrev_b32_e32 v98, 16, v98
	v_lshlrev_b32_e32 v99, 16, v99
	v_mul_f32_e32 v208, 0xbfb8aa3b, v96
	v_mul_f32_e32 v214, 0xbfb8aa3b, v97
	v_mul_f32_e32 v220, 0xbfb8aa3b, v98
	v_mul_f32_e32 v226, 0xbfb8aa3b, v99
	v_exp_f32_e32 v208, v208
	v_exp_f32_e32 v214, v214
	v_exp_f32_e32 v220, v220
	v_exp_f32_e32 v226, v226
	v_add_f32_e32 v208, 1.0, v208
	v_add_f32_e32 v214, 1.0, v214
	v_add_f32_e32 v220, 1.0, v220
	v_add_f32_e32 v226, 1.0, v226
	v_div_scale_f32 v209, s[12:13], v208, v208, v96
	v_div_scale_f32 v215, s[12:13], v214, v214, v97
	v_div_scale_f32 v221, s[12:13], v220, v220, v98
	v_div_scale_f32 v227, s[12:13], v226, v226, v99
	v_rcp_f32_e32 v210, v209
	v_rcp_f32_e32 v216, v215
	v_rcp_f32_e32 v222, v221
	v_rcp_f32_e32 v228, v227
	v_fma_f32 v211, -v209, v210, 1.0
	v_fma_f32 v217, -v215, v216, 1.0
	v_fma_f32 v223, -v221, v222, 1.0
	v_fma_f32 v229, -v227, v228, 1.0
	v_fmac_f32_e32 v210, v211, v210
	v_fmac_f32_e32 v216, v217, v216
	v_fmac_f32_e32 v222, v223, v222
	v_fmac_f32_e32 v228, v229, v228
	v_div_scale_f32 v211, vcc, v96, v208, v96
	v_mul_f32_e32 v212, v211, v210
	v_fma_f32 v213, -v209, v212, v211
	v_fmac_f32_e32 v212, v213, v210
	v_fma_f32 v209, -v209, v212, v211
	v_div_fmas_f32 v209, v209, v210, v212
	v_div_fixup_f32 v96, v209, v208, v96
	v_div_scale_f32 v217, vcc, v97, v214, v97
	v_mul_f32_e32 v218, v217, v216
	v_fma_f32 v219, -v215, v218, v217
	v_fmac_f32_e32 v218, v219, v216
	v_fma_f32 v215, -v215, v218, v217
	v_div_fmas_f32 v215, v215, v216, v218
	v_div_fixup_f32 v97, v215, v214, v97
	v_div_scale_f32 v223, vcc, v98, v220, v98
	v_mul_f32_e32 v224, v223, v222
	v_fma_f32 v225, -v221, v224, v223
	v_fmac_f32_e32 v224, v225, v222
	v_fma_f32 v221, -v221, v224, v223
	v_div_fmas_f32 v221, v221, v222, v224
	v_div_fixup_f32 v98, v221, v220, v98
	v_div_scale_f32 v229, vcc, v99, v226, v99
	v_mul_f32_e32 v230, v229, v228
	v_fma_f32 v231, -v227, v230, v229
	v_fmac_f32_e32 v230, v231, v228
	v_fma_f32 v227, -v227, v230, v229
	v_div_fmas_f32 v227, v227, v228, v230
	v_div_fixup_f32 v99, v227, v226, v99
	v_mul_f32_e32 v56, v56, v96
	v_mul_f32_e32 v40, v40, v97
	v_mul_f32_e32 v24, v24, v98
	v_mul_f32_e32 v8, v8, v99
	v_mul_f32_e32 v156, v40, v40
	v_fmac_f32_e32 v156, v56, v56
	v_fmac_f32_e32 v156, v24, v24
	v_fmac_f32_e32 v156, v8, v8
	v_cvt_pk_bf16_f32 v96, v56, v177
	v_cvt_pk_bf16_f32 v97, v40, v177
	v_cvt_pk_bf16_f32 v98, v24, v177
	v_cvt_pk_bf16_f32 v99, v8, v177
	global_store_short v182, v96, s[14:15] offset:0
	global_store_short v182, v97, s[14:15] offset:64
	global_store_short v182, v98, s[14:15] offset:128
	global_store_short v182, v99, s[14:15] offset:192
	s_waitcnt vmcnt(60)
	v_add_u32_e32 v175, 0x11000, v169
	v_lshlrev_b32_e32 v100, 16, v100
	v_lshlrev_b32_e32 v101, 16, v101
	v_lshlrev_b32_e32 v102, 16, v102
	v_lshlrev_b32_e32 v103, 16, v103
	v_mul_f32_e32 v208, 0xbfb8aa3b, v100
	v_mul_f32_e32 v214, 0xbfb8aa3b, v101
	v_mul_f32_e32 v220, 0xbfb8aa3b, v102
	v_mul_f32_e32 v226, 0xbfb8aa3b, v103
	v_exp_f32_e32 v208, v208
	v_exp_f32_e32 v214, v214
	v_exp_f32_e32 v220, v220
	v_exp_f32_e32 v226, v226
	v_add_f32_e32 v208, 1.0, v208
	v_add_f32_e32 v214, 1.0, v214
	v_add_f32_e32 v220, 1.0, v220
	v_add_f32_e32 v226, 1.0, v226
	v_div_scale_f32 v209, s[12:13], v208, v208, v100
	v_div_scale_f32 v215, s[12:13], v214, v214, v101
	v_div_scale_f32 v221, s[12:13], v220, v220, v102
	v_div_scale_f32 v227, s[12:13], v226, v226, v103
	v_rcp_f32_e32 v210, v209
	v_rcp_f32_e32 v216, v215
	v_rcp_f32_e32 v222, v221
	v_rcp_f32_e32 v228, v227
	v_fma_f32 v211, -v209, v210, 1.0
	v_fma_f32 v217, -v215, v216, 1.0
	v_fma_f32 v223, -v221, v222, 1.0
	v_fma_f32 v229, -v227, v228, 1.0
	v_fmac_f32_e32 v210, v211, v210
	v_fmac_f32_e32 v216, v217, v216
	v_fmac_f32_e32 v222, v223, v222
	v_fmac_f32_e32 v228, v229, v228
	v_div_scale_f32 v211, vcc, v100, v208, v100
	v_mul_f32_e32 v212, v211, v210
	v_fma_f32 v213, -v209, v212, v211
	v_fmac_f32_e32 v212, v213, v210
	v_fma_f32 v209, -v209, v212, v211
	v_div_fmas_f32 v209, v209, v210, v212
	v_div_fixup_f32 v100, v209, v208, v100
	v_div_scale_f32 v217, vcc, v101, v214, v101
	v_mul_f32_e32 v218, v217, v216
	v_fma_f32 v219, -v215, v218, v217
	v_fmac_f32_e32 v218, v219, v216
	v_fma_f32 v215, -v215, v218, v217
	v_div_fmas_f32 v215, v215, v216, v218
	v_div_fixup_f32 v101, v215, v214, v101
	v_div_scale_f32 v223, vcc, v102, v220, v102
	v_mul_f32_e32 v224, v223, v222
	v_fma_f32 v225, -v221, v224, v223
	v_fmac_f32_e32 v224, v225, v222
	v_fma_f32 v221, -v221, v224, v223
	v_div_fmas_f32 v221, v221, v222, v224
	v_div_fixup_f32 v102, v221, v220, v102
	v_div_scale_f32 v229, vcc, v103, v226, v103
	v_mul_f32_e32 v230, v229, v228
	v_fma_f32 v231, -v227, v230, v229
	v_fmac_f32_e32 v230, v231, v228
	v_fma_f32 v227, -v227, v230, v229
	v_div_fmas_f32 v227, v227, v228, v230
	v_div_fixup_f32 v103, v227, v226, v103
	v_mul_f32_e32 v57, v57, v100
	v_mul_f32_e32 v41, v41, v101
	v_mul_f32_e32 v25, v25, v102
	v_mul_f32_e32 v9, v9, v103
	v_mul_f32_e32 v157, v41, v41
	v_fmac_f32_e32 v157, v57, v57
	v_fmac_f32_e32 v157, v25, v25
	v_fmac_f32_e32 v157, v9, v9
	v_cvt_pk_bf16_f32 v100, v57, v177
	v_cvt_pk_bf16_f32 v101, v41, v177
	v_cvt_pk_bf16_f32 v102, v25, v177
	v_cvt_pk_bf16_f32 v103, v9, v177
	global_store_short v175, v100, s[14:15] offset:0
	global_store_short v175, v101, s[14:15] offset:64
	global_store_short v175, v102, s[14:15] offset:128
	global_store_short v175, v103, s[14:15] offset:192
	s_waitcnt vmcnt(60)
	v_add_u32_e32 v182, 0x12000, v169
	v_lshlrev_b32_e32 v104, 16, v104
	v_lshlrev_b32_e32 v105, 16, v105
	v_lshlrev_b32_e32 v106, 16, v106
	v_lshlrev_b32_e32 v107, 16, v107
	v_mul_f32_e32 v208, 0xbfb8aa3b, v104
	v_mul_f32_e32 v214, 0xbfb8aa3b, v105
	v_mul_f32_e32 v220, 0xbfb8aa3b, v106
	v_mul_f32_e32 v226, 0xbfb8aa3b, v107
	v_exp_f32_e32 v208, v208
	v_exp_f32_e32 v214, v214
	v_exp_f32_e32 v220, v220
	v_exp_f32_e32 v226, v226
	v_add_f32_e32 v208, 1.0, v208
	v_add_f32_e32 v214, 1.0, v214
	v_add_f32_e32 v220, 1.0, v220
	v_add_f32_e32 v226, 1.0, v226
	v_div_scale_f32 v209, s[12:13], v208, v208, v104
	v_div_scale_f32 v215, s[12:13], v214, v214, v105
	v_div_scale_f32 v221, s[12:13], v220, v220, v106
	v_div_scale_f32 v227, s[12:13], v226, v226, v107
	v_rcp_f32_e32 v210, v209
	v_rcp_f32_e32 v216, v215
	v_rcp_f32_e32 v222, v221
	v_rcp_f32_e32 v228, v227
	v_fma_f32 v211, -v209, v210, 1.0
	v_fma_f32 v217, -v215, v216, 1.0
	v_fma_f32 v223, -v221, v222, 1.0
	v_fma_f32 v229, -v227, v228, 1.0
	v_fmac_f32_e32 v210, v211, v210
	v_fmac_f32_e32 v216, v217, v216
	v_fmac_f32_e32 v222, v223, v222
	v_fmac_f32_e32 v228, v229, v228
	v_div_scale_f32 v211, vcc, v104, v208, v104
	v_mul_f32_e32 v212, v211, v210
	v_fma_f32 v213, -v209, v212, v211
	v_fmac_f32_e32 v212, v213, v210
	v_fma_f32 v209, -v209, v212, v211
	v_div_fmas_f32 v209, v209, v210, v212
	v_div_fixup_f32 v104, v209, v208, v104
	v_div_scale_f32 v217, vcc, v105, v214, v105
	v_mul_f32_e32 v218, v217, v216
	v_fma_f32 v219, -v215, v218, v217
	v_fmac_f32_e32 v218, v219, v216
	v_fma_f32 v215, -v215, v218, v217
	v_div_fmas_f32 v215, v215, v216, v218
	v_div_fixup_f32 v105, v215, v214, v105
	v_div_scale_f32 v223, vcc, v106, v220, v106
	v_mul_f32_e32 v224, v223, v222
	v_fma_f32 v225, -v221, v224, v223
	v_fmac_f32_e32 v224, v225, v222
	v_fma_f32 v221, -v221, v224, v223
	v_div_fmas_f32 v221, v221, v222, v224
	v_div_fixup_f32 v106, v221, v220, v106
	v_div_scale_f32 v229, vcc, v107, v226, v107
	v_mul_f32_e32 v230, v229, v228
	v_fma_f32 v231, -v227, v230, v229
	v_fmac_f32_e32 v230, v231, v228
	v_fma_f32 v227, -v227, v230, v229
	v_div_fmas_f32 v227, v227, v228, v230
	v_div_fixup_f32 v107, v227, v226, v107
	v_mul_f32_e32 v58, v58, v104
	v_mul_f32_e32 v42, v42, v105
	v_mul_f32_e32 v26, v26, v106
	v_mul_f32_e32 v10, v10, v107
	v_mul_f32_e32 v158, v42, v42
	v_fmac_f32_e32 v158, v58, v58
	v_fmac_f32_e32 v158, v26, v26
	v_fmac_f32_e32 v158, v10, v10
	v_cvt_pk_bf16_f32 v104, v58, v177
	v_cvt_pk_bf16_f32 v105, v42, v177
	v_cvt_pk_bf16_f32 v106, v26, v177
	v_cvt_pk_bf16_f32 v107, v10, v177
	global_store_short v182, v104, s[14:15] offset:0
	global_store_short v182, v105, s[14:15] offset:64
	global_store_short v182, v106, s[14:15] offset:128
	global_store_short v182, v107, s[14:15] offset:192
	s_waitcnt vmcnt(60)
	v_add_u32_e32 v175, 0x13000, v169
	v_lshlrev_b32_e32 v108, 16, v108
	v_lshlrev_b32_e32 v109, 16, v109
	v_lshlrev_b32_e32 v110, 16, v110
	v_lshlrev_b32_e32 v111, 16, v111
	v_mul_f32_e32 v208, 0xbfb8aa3b, v108
	v_mul_f32_e32 v214, 0xbfb8aa3b, v109
	v_mul_f32_e32 v220, 0xbfb8aa3b, v110
	v_mul_f32_e32 v226, 0xbfb8aa3b, v111
	v_exp_f32_e32 v208, v208
	v_exp_f32_e32 v214, v214
	v_exp_f32_e32 v220, v220
	v_exp_f32_e32 v226, v226
	v_add_f32_e32 v208, 1.0, v208
	v_add_f32_e32 v214, 1.0, v214
	v_add_f32_e32 v220, 1.0, v220
	v_add_f32_e32 v226, 1.0, v226
	v_div_scale_f32 v209, s[12:13], v208, v208, v108
	v_div_scale_f32 v215, s[12:13], v214, v214, v109
	v_div_scale_f32 v221, s[12:13], v220, v220, v110
	v_div_scale_f32 v227, s[12:13], v226, v226, v111
	v_rcp_f32_e32 v210, v209
	v_rcp_f32_e32 v216, v215
	v_rcp_f32_e32 v222, v221
	v_rcp_f32_e32 v228, v227
	v_fma_f32 v211, -v209, v210, 1.0
	v_fma_f32 v217, -v215, v216, 1.0
	v_fma_f32 v223, -v221, v222, 1.0
	v_fma_f32 v229, -v227, v228, 1.0
	v_fmac_f32_e32 v210, v211, v210
	v_fmac_f32_e32 v216, v217, v216
	v_fmac_f32_e32 v222, v223, v222
	v_fmac_f32_e32 v228, v229, v228
	v_div_scale_f32 v211, vcc, v108, v208, v108
	v_mul_f32_e32 v212, v211, v210
	v_fma_f32 v213, -v209, v212, v211
	v_fmac_f32_e32 v212, v213, v210
	v_fma_f32 v209, -v209, v212, v211
	v_div_fmas_f32 v209, v209, v210, v212
	v_div_fixup_f32 v108, v209, v208, v108
	v_div_scale_f32 v217, vcc, v109, v214, v109
	v_mul_f32_e32 v218, v217, v216
	v_fma_f32 v219, -v215, v218, v217
	v_fmac_f32_e32 v218, v219, v216
	v_fma_f32 v215, -v215, v218, v217
	v_div_fmas_f32 v215, v215, v216, v218
	v_div_fixup_f32 v109, v215, v214, v109
	v_div_scale_f32 v223, vcc, v110, v220, v110
	v_mul_f32_e32 v224, v223, v222
	v_fma_f32 v225, -v221, v224, v223
	v_fmac_f32_e32 v224, v225, v222
	v_fma_f32 v221, -v221, v224, v223
	v_div_fmas_f32 v221, v221, v222, v224
	v_div_fixup_f32 v110, v221, v220, v110
	v_div_scale_f32 v229, vcc, v111, v226, v111
	v_mul_f32_e32 v230, v229, v228
	v_fma_f32 v231, -v227, v230, v229
	v_fmac_f32_e32 v230, v231, v228
	v_fma_f32 v227, -v227, v230, v229
	v_div_fmas_f32 v227, v227, v228, v230
	v_div_fixup_f32 v111, v227, v226, v111
	v_mul_f32_e32 v59, v59, v108
	v_mul_f32_e32 v43, v43, v109
	v_mul_f32_e32 v27, v27, v110
	v_mul_f32_e32 v11, v11, v111
	v_mul_f32_e32 v159, v43, v43
	v_fmac_f32_e32 v159, v59, v59
	v_fmac_f32_e32 v159, v27, v27
	v_fmac_f32_e32 v159, v11, v11
	v_cvt_pk_bf16_f32 v108, v59, v177
	v_cvt_pk_bf16_f32 v109, v43, v177
	v_cvt_pk_bf16_f32 v110, v27, v177
	v_cvt_pk_bf16_f32 v111, v11, v177
	global_store_short v175, v108, s[14:15] offset:0
	global_store_short v175, v109, s[14:15] offset:64
	global_store_short v175, v110, s[14:15] offset:128
	global_store_short v175, v111, s[14:15] offset:192
	s_waitcnt vmcnt(60)
	v_add_u32_e32 v182, 0x18000, v169
	v_lshlrev_b32_e32 v112, 16, v112
	v_lshlrev_b32_e32 v113, 16, v113
	v_lshlrev_b32_e32 v114, 16, v114
	v_lshlrev_b32_e32 v115, 16, v115
	v_mul_f32_e32 v208, 0xbfb8aa3b, v112
	v_mul_f32_e32 v214, 0xbfb8aa3b, v113
	v_mul_f32_e32 v220, 0xbfb8aa3b, v114
	v_mul_f32_e32 v226, 0xbfb8aa3b, v115
	v_exp_f32_e32 v208, v208
	v_exp_f32_e32 v214, v214
	v_exp_f32_e32 v220, v220
	v_exp_f32_e32 v226, v226
	v_add_f32_e32 v208, 1.0, v208
	v_add_f32_e32 v214, 1.0, v214
	v_add_f32_e32 v220, 1.0, v220
	v_add_f32_e32 v226, 1.0, v226
	v_div_scale_f32 v209, s[12:13], v208, v208, v112
	v_div_scale_f32 v215, s[12:13], v214, v214, v113
	v_div_scale_f32 v221, s[12:13], v220, v220, v114
	v_div_scale_f32 v227, s[12:13], v226, v226, v115
	v_rcp_f32_e32 v210, v209
	v_rcp_f32_e32 v216, v215
	v_rcp_f32_e32 v222, v221
	v_rcp_f32_e32 v228, v227
	v_fma_f32 v211, -v209, v210, 1.0
	v_fma_f32 v217, -v215, v216, 1.0
	v_fma_f32 v223, -v221, v222, 1.0
	v_fma_f32 v229, -v227, v228, 1.0
	v_fmac_f32_e32 v210, v211, v210
	v_fmac_f32_e32 v216, v217, v216
	v_fmac_f32_e32 v222, v223, v222
	v_fmac_f32_e32 v228, v229, v228
	v_div_scale_f32 v211, vcc, v112, v208, v112
	v_mul_f32_e32 v212, v211, v210
	v_fma_f32 v213, -v209, v212, v211
	v_fmac_f32_e32 v212, v213, v210
	v_fma_f32 v209, -v209, v212, v211
	v_div_fmas_f32 v209, v209, v210, v212
	v_div_fixup_f32 v112, v209, v208, v112
	v_div_scale_f32 v217, vcc, v113, v214, v113
	v_mul_f32_e32 v218, v217, v216
	v_fma_f32 v219, -v215, v218, v217
	v_fmac_f32_e32 v218, v219, v216
	v_fma_f32 v215, -v215, v218, v217
	v_div_fmas_f32 v215, v215, v216, v218
	v_div_fixup_f32 v113, v215, v214, v113
	v_div_scale_f32 v223, vcc, v114, v220, v114
	v_mul_f32_e32 v224, v223, v222
	v_fma_f32 v225, -v221, v224, v223
	v_fmac_f32_e32 v224, v225, v222
	v_fma_f32 v221, -v221, v224, v223
	v_div_fmas_f32 v221, v221, v222, v224
	v_div_fixup_f32 v114, v221, v220, v114
	v_div_scale_f32 v229, vcc, v115, v226, v115
	v_mul_f32_e32 v230, v229, v228
	v_fma_f32 v231, -v227, v230, v229
	v_fmac_f32_e32 v230, v231, v228
	v_fma_f32 v227, -v227, v230, v229
	v_div_fmas_f32 v227, v227, v228, v230
	v_div_fixup_f32 v115, v227, v226, v115
	v_mul_f32_e32 v60, v60, v112
	v_mul_f32_e32 v44, v44, v113
	v_mul_f32_e32 v28, v28, v114
	v_mul_f32_e32 v12, v12, v115
	v_mul_f32_e32 v160, v44, v44
	v_fmac_f32_e32 v160, v60, v60
	v_fmac_f32_e32 v160, v28, v28
	v_fmac_f32_e32 v160, v12, v12
	v_cvt_pk_bf16_f32 v112, v60, v177
	v_cvt_pk_bf16_f32 v113, v44, v177
	v_cvt_pk_bf16_f32 v114, v28, v177
	v_cvt_pk_bf16_f32 v115, v12, v177
	global_store_short v182, v112, s[14:15] offset:0
	global_store_short v182, v113, s[14:15] offset:64
	global_store_short v182, v114, s[14:15] offset:128
	global_store_short v182, v115, s[14:15] offset:192
	s_waitcnt vmcnt(60)
	v_add_u32_e32 v175, 0x19000, v169
	v_lshlrev_b32_e32 v116, 16, v116
	v_lshlrev_b32_e32 v117, 16, v117
	v_lshlrev_b32_e32 v118, 16, v118
	v_lshlrev_b32_e32 v119, 16, v119
	v_mul_f32_e32 v208, 0xbfb8aa3b, v116
	v_mul_f32_e32 v214, 0xbfb8aa3b, v117
	v_mul_f32_e32 v220, 0xbfb8aa3b, v118
	v_mul_f32_e32 v226, 0xbfb8aa3b, v119
	v_exp_f32_e32 v208, v208
	v_exp_f32_e32 v214, v214
	v_exp_f32_e32 v220, v220
	v_exp_f32_e32 v226, v226
	v_add_f32_e32 v208, 1.0, v208
	v_add_f32_e32 v214, 1.0, v214
	v_add_f32_e32 v220, 1.0, v220
	v_add_f32_e32 v226, 1.0, v226
	v_div_scale_f32 v209, s[12:13], v208, v208, v116
	v_div_scale_f32 v215, s[12:13], v214, v214, v117
	v_div_scale_f32 v221, s[12:13], v220, v220, v118
	v_div_scale_f32 v227, s[12:13], v226, v226, v119
	v_rcp_f32_e32 v210, v209
	v_rcp_f32_e32 v216, v215
	v_rcp_f32_e32 v222, v221
	v_rcp_f32_e32 v228, v227
	v_fma_f32 v211, -v209, v210, 1.0
	v_fma_f32 v217, -v215, v216, 1.0
	v_fma_f32 v223, -v221, v222, 1.0
	v_fma_f32 v229, -v227, v228, 1.0
	v_fmac_f32_e32 v210, v211, v210
	v_fmac_f32_e32 v216, v217, v216
	v_fmac_f32_e32 v222, v223, v222
	v_fmac_f32_e32 v228, v229, v228
	v_div_scale_f32 v211, vcc, v116, v208, v116
	v_mul_f32_e32 v212, v211, v210
	v_fma_f32 v213, -v209, v212, v211
	v_fmac_f32_e32 v212, v213, v210
	v_fma_f32 v209, -v209, v212, v211
	v_div_fmas_f32 v209, v209, v210, v212
	v_div_fixup_f32 v116, v209, v208, v116
	v_div_scale_f32 v217, vcc, v117, v214, v117
	v_mul_f32_e32 v218, v217, v216
	v_fma_f32 v219, -v215, v218, v217
	v_fmac_f32_e32 v218, v219, v216
	v_fma_f32 v215, -v215, v218, v217
	v_div_fmas_f32 v215, v215, v216, v218
	v_div_fixup_f32 v117, v215, v214, v117
	v_div_scale_f32 v223, vcc, v118, v220, v118
	v_mul_f32_e32 v224, v223, v222
	v_fma_f32 v225, -v221, v224, v223
	v_fmac_f32_e32 v224, v225, v222
	v_fma_f32 v221, -v221, v224, v223
	v_div_fmas_f32 v221, v221, v222, v224
	v_div_fixup_f32 v118, v221, v220, v118
	v_div_scale_f32 v229, vcc, v119, v226, v119
	v_mul_f32_e32 v230, v229, v228
	v_fma_f32 v231, -v227, v230, v229
	v_fmac_f32_e32 v230, v231, v228
	v_fma_f32 v227, -v227, v230, v229
	v_div_fmas_f32 v227, v227, v228, v230
	v_div_fixup_f32 v119, v227, v226, v119
	v_mul_f32_e32 v61, v61, v116
	v_mul_f32_e32 v45, v45, v117
	v_mul_f32_e32 v29, v29, v118
	v_mul_f32_e32 v13, v13, v119
	v_mul_f32_e32 v161, v45, v45
	v_fmac_f32_e32 v161, v61, v61
	v_fmac_f32_e32 v161, v29, v29
	v_fmac_f32_e32 v161, v13, v13
	v_cvt_pk_bf16_f32 v116, v61, v177
	v_cvt_pk_bf16_f32 v117, v45, v177
	v_cvt_pk_bf16_f32 v118, v29, v177
	v_cvt_pk_bf16_f32 v119, v13, v177
	global_store_short v175, v116, s[14:15] offset:0
	global_store_short v175, v117, s[14:15] offset:64
	global_store_short v175, v118, s[14:15] offset:128
	global_store_short v175, v119, s[14:15] offset:192
	s_waitcnt vmcnt(60)
	v_add_u32_e32 v182, 0x1a000, v169
	v_lshlrev_b32_e32 v120, 16, v120
	v_lshlrev_b32_e32 v121, 16, v121
	v_lshlrev_b32_e32 v122, 16, v122
	v_lshlrev_b32_e32 v123, 16, v123
	v_mul_f32_e32 v208, 0xbfb8aa3b, v120
	v_mul_f32_e32 v214, 0xbfb8aa3b, v121
	v_mul_f32_e32 v220, 0xbfb8aa3b, v122
	v_mul_f32_e32 v226, 0xbfb8aa3b, v123
	v_exp_f32_e32 v208, v208
	v_exp_f32_e32 v214, v214
	v_exp_f32_e32 v220, v220
	v_exp_f32_e32 v226, v226
	v_add_f32_e32 v208, 1.0, v208
	v_add_f32_e32 v214, 1.0, v214
	v_add_f32_e32 v220, 1.0, v220
	v_add_f32_e32 v226, 1.0, v226
	v_div_scale_f32 v209, s[12:13], v208, v208, v120
	v_div_scale_f32 v215, s[12:13], v214, v214, v121
	v_div_scale_f32 v221, s[12:13], v220, v220, v122
	v_div_scale_f32 v227, s[12:13], v226, v226, v123
	v_rcp_f32_e32 v210, v209
	v_rcp_f32_e32 v216, v215
	v_rcp_f32_e32 v222, v221
	v_rcp_f32_e32 v228, v227
	v_fma_f32 v211, -v209, v210, 1.0
	v_fma_f32 v217, -v215, v216, 1.0
	v_fma_f32 v223, -v221, v222, 1.0
	v_fma_f32 v229, -v227, v228, 1.0
	v_fmac_f32_e32 v210, v211, v210
	v_fmac_f32_e32 v216, v217, v216
	v_fmac_f32_e32 v222, v223, v222
	v_fmac_f32_e32 v228, v229, v228
	v_div_scale_f32 v211, vcc, v120, v208, v120
	v_mul_f32_e32 v212, v211, v210
	v_fma_f32 v213, -v209, v212, v211
	v_fmac_f32_e32 v212, v213, v210
	v_fma_f32 v209, -v209, v212, v211
	v_div_fmas_f32 v209, v209, v210, v212
	v_div_fixup_f32 v120, v209, v208, v120
	v_div_scale_f32 v217, vcc, v121, v214, v121
	v_mul_f32_e32 v218, v217, v216
	v_fma_f32 v219, -v215, v218, v217
	v_fmac_f32_e32 v218, v219, v216
	v_fma_f32 v215, -v215, v218, v217
	v_div_fmas_f32 v215, v215, v216, v218
	v_div_fixup_f32 v121, v215, v214, v121
	v_div_scale_f32 v223, vcc, v122, v220, v122
	v_mul_f32_e32 v224, v223, v222
	v_fma_f32 v225, -v221, v224, v223
	v_fmac_f32_e32 v224, v225, v222
	v_fma_f32 v221, -v221, v224, v223
	v_div_fmas_f32 v221, v221, v222, v224
	v_div_fixup_f32 v122, v221, v220, v122
	v_div_scale_f32 v229, vcc, v123, v226, v123
	v_mul_f32_e32 v230, v229, v228
	v_fma_f32 v231, -v227, v230, v229
	v_fmac_f32_e32 v230, v231, v228
	v_fma_f32 v227, -v227, v230, v229
	v_div_fmas_f32 v227, v227, v228, v230
	v_div_fixup_f32 v123, v227, v226, v123
	v_mul_f32_e32 v62, v62, v120
	v_mul_f32_e32 v46, v46, v121
	v_mul_f32_e32 v30, v30, v122
	v_mul_f32_e32 v14, v14, v123
	v_mul_f32_e32 v162, v46, v46
	v_fmac_f32_e32 v162, v62, v62
	v_fmac_f32_e32 v162, v30, v30
	v_fmac_f32_e32 v162, v14, v14
	v_cvt_pk_bf16_f32 v120, v62, v177
	v_cvt_pk_bf16_f32 v121, v46, v177
	v_cvt_pk_bf16_f32 v122, v30, v177
	v_cvt_pk_bf16_f32 v123, v14, v177
	global_store_short v182, v120, s[14:15] offset:0
	global_store_short v182, v121, s[14:15] offset:64
	global_store_short v182, v122, s[14:15] offset:128
	global_store_short v182, v123, s[14:15] offset:192
	s_waitcnt vmcnt(60)
	v_add_u32_e32 v175, 0x1b000, v169
	v_lshlrev_b32_e32 v124, 16, v124
	v_lshlrev_b32_e32 v125, 16, v125
	v_lshlrev_b32_e32 v126, 16, v126
	v_lshlrev_b32_e32 v127, 16, v127
	v_mul_f32_e32 v208, 0xbfb8aa3b, v124
	v_mul_f32_e32 v214, 0xbfb8aa3b, v125
	v_mul_f32_e32 v220, 0xbfb8aa3b, v126
	v_mul_f32_e32 v226, 0xbfb8aa3b, v127
	v_exp_f32_e32 v208, v208
	v_exp_f32_e32 v214, v214
	v_exp_f32_e32 v220, v220
	v_exp_f32_e32 v226, v226
	v_add_f32_e32 v208, 1.0, v208
	v_add_f32_e32 v214, 1.0, v214
	v_add_f32_e32 v220, 1.0, v220
	v_add_f32_e32 v226, 1.0, v226
	v_div_scale_f32 v209, s[12:13], v208, v208, v124
	v_div_scale_f32 v215, s[12:13], v214, v214, v125
	v_div_scale_f32 v221, s[12:13], v220, v220, v126
	v_div_scale_f32 v227, s[12:13], v226, v226, v127
	v_rcp_f32_e32 v210, v209
	v_rcp_f32_e32 v216, v215
	v_rcp_f32_e32 v222, v221
	v_rcp_f32_e32 v228, v227
	v_fma_f32 v211, -v209, v210, 1.0
	v_fma_f32 v217, -v215, v216, 1.0
	v_fma_f32 v223, -v221, v222, 1.0
	v_fma_f32 v229, -v227, v228, 1.0
	v_fmac_f32_e32 v210, v211, v210
	v_fmac_f32_e32 v216, v217, v216
	v_fmac_f32_e32 v222, v223, v222
	v_fmac_f32_e32 v228, v229, v228
	v_div_scale_f32 v211, vcc, v124, v208, v124
	v_mul_f32_e32 v212, v211, v210
	v_fma_f32 v213, -v209, v212, v211
	v_fmac_f32_e32 v212, v213, v210
	v_fma_f32 v209, -v209, v212, v211
	v_div_fmas_f32 v209, v209, v210, v212
	v_div_fixup_f32 v124, v209, v208, v124
	v_div_scale_f32 v217, vcc, v125, v214, v125
	v_mul_f32_e32 v218, v217, v216
	v_fma_f32 v219, -v215, v218, v217
	v_fmac_f32_e32 v218, v219, v216
	v_fma_f32 v215, -v215, v218, v217
	v_div_fmas_f32 v215, v215, v216, v218
	v_div_fixup_f32 v125, v215, v214, v125
	v_div_scale_f32 v223, vcc, v126, v220, v126
	v_mul_f32_e32 v224, v223, v222
	v_fma_f32 v225, -v221, v224, v223
	v_fmac_f32_e32 v224, v225, v222
	v_fma_f32 v221, -v221, v224, v223
	v_div_fmas_f32 v221, v221, v222, v224
	v_div_fixup_f32 v126, v221, v220, v126
	v_div_scale_f32 v229, vcc, v127, v226, v127
	v_mul_f32_e32 v230, v229, v228
	v_fma_f32 v231, -v227, v230, v229
	v_fmac_f32_e32 v230, v231, v228
	v_fma_f32 v227, -v227, v230, v229
	v_div_fmas_f32 v227, v227, v228, v230
	v_div_fixup_f32 v127, v227, v226, v127
	v_mul_f32_e32 v63, v63, v124
	v_mul_f32_e32 v47, v47, v125
	v_mul_f32_e32 v31, v31, v126
	v_mul_f32_e32 v15, v15, v127
	v_mul_f32_e32 v163, v47, v47
	v_fmac_f32_e32 v163, v63, v63
	v_fmac_f32_e32 v163, v31, v31
	v_fmac_f32_e32 v163, v15, v15
	v_cvt_pk_bf16_f32 v124, v63, v177
	v_cvt_pk_bf16_f32 v125, v47, v177
	v_cvt_pk_bf16_f32 v126, v31, v177
	v_cvt_pk_bf16_f32 v127, v15, v177
	global_store_short v175, v124, s[14:15] offset:0
	global_store_short v175, v125, s[14:15] offset:64
	global_store_short v175, v126, s[14:15] offset:128
	global_store_short v175, v127, s[14:15] offset:192
	v_add_f32_dpp v148, v148, v148 quad_perm:[1,0,3,2] row_mask:0xf bank_mask:0xf
	v_add_f32_dpp v149, v149, v149 quad_perm:[1,0,3,2] row_mask:0xf bank_mask:0xf
	v_add_f32_dpp v150, v150, v150 quad_perm:[1,0,3,2] row_mask:0xf bank_mask:0xf
	v_add_f32_dpp v151, v151, v151 quad_perm:[1,0,3,2] row_mask:0xf bank_mask:0xf
	v_add_f32_dpp v152, v152, v152 quad_perm:[1,0,3,2] row_mask:0xf bank_mask:0xf
	v_add_f32_dpp v153, v153, v153 quad_perm:[1,0,3,2] row_mask:0xf bank_mask:0xf
	v_add_f32_dpp v154, v154, v154 quad_perm:[1,0,3,2] row_mask:0xf bank_mask:0xf
	v_add_f32_dpp v155, v155, v155 quad_perm:[1,0,3,2] row_mask:0xf bank_mask:0xf
	v_add_f32_dpp v156, v156, v156 quad_perm:[1,0,3,2] row_mask:0xf bank_mask:0xf
	v_add_f32_dpp v157, v157, v157 quad_perm:[1,0,3,2] row_mask:0xf bank_mask:0xf
	v_add_f32_dpp v158, v158, v158 quad_perm:[1,0,3,2] row_mask:0xf bank_mask:0xf
	v_add_f32_dpp v159, v159, v159 quad_perm:[1,0,3,2] row_mask:0xf bank_mask:0xf
	v_add_f32_dpp v160, v160, v160 quad_perm:[1,0,3,2] row_mask:0xf bank_mask:0xf
	v_add_f32_dpp v161, v161, v161 quad_perm:[1,0,3,2] row_mask:0xf bank_mask:0xf
	v_add_f32_dpp v162, v162, v162 quad_perm:[1,0,3,2] row_mask:0xf bank_mask:0xf
	v_add_f32_dpp v163, v163, v163 quad_perm:[1,0,3,2] row_mask:0xf bank_mask:0xf
	v_add_f32_dpp v148, v148, v148 quad_perm:[2,3,0,1] row_mask:0xf bank_mask:0xf
	v_add_f32_dpp v149, v149, v149 quad_perm:[2,3,0,1] row_mask:0xf bank_mask:0xf
	v_add_f32_dpp v150, v150, v150 quad_perm:[2,3,0,1] row_mask:0xf bank_mask:0xf
	v_add_f32_dpp v151, v151, v151 quad_perm:[2,3,0,1] row_mask:0xf bank_mask:0xf
	v_add_f32_dpp v152, v152, v152 quad_perm:[2,3,0,1] row_mask:0xf bank_mask:0xf
	v_add_f32_dpp v153, v153, v153 quad_perm:[2,3,0,1] row_mask:0xf bank_mask:0xf
	v_add_f32_dpp v154, v154, v154 quad_perm:[2,3,0,1] row_mask:0xf bank_mask:0xf
	v_add_f32_dpp v155, v155, v155 quad_perm:[2,3,0,1] row_mask:0xf bank_mask:0xf
	v_add_f32_dpp v156, v156, v156 quad_perm:[2,3,0,1] row_mask:0xf bank_mask:0xf
	v_add_f32_dpp v157, v157, v157 quad_perm:[2,3,0,1] row_mask:0xf bank_mask:0xf
	v_add_f32_dpp v158, v158, v158 quad_perm:[2,3,0,1] row_mask:0xf bank_mask:0xf
	v_add_f32_dpp v159, v159, v159 quad_perm:[2,3,0,1] row_mask:0xf bank_mask:0xf
	v_add_f32_dpp v160, v160, v160 quad_perm:[2,3,0,1] row_mask:0xf bank_mask:0xf
	v_add_f32_dpp v161, v161, v161 quad_perm:[2,3,0,1] row_mask:0xf bank_mask:0xf
	v_add_f32_dpp v162, v162, v162 quad_perm:[2,3,0,1] row_mask:0xf bank_mask:0xf
	v_add_f32_dpp v163, v163, v163 quad_perm:[2,3,0,1] row_mask:0xf bank_mask:0xf
	v_add_f32_dpp v148, v148, v148 row_half_mirror row_mask:0xf bank_mask:0xf
	v_add_f32_dpp v149, v149, v149 row_half_mirror row_mask:0xf bank_mask:0xf
	v_add_f32_dpp v150, v150, v150 row_half_mirror row_mask:0xf bank_mask:0xf
	v_add_f32_dpp v151, v151, v151 row_half_mirror row_mask:0xf bank_mask:0xf
	v_add_f32_dpp v152, v152, v152 row_half_mirror row_mask:0xf bank_mask:0xf
	v_add_f32_dpp v153, v153, v153 row_half_mirror row_mask:0xf bank_mask:0xf
	v_add_f32_dpp v154, v154, v154 row_half_mirror row_mask:0xf bank_mask:0xf
	v_add_f32_dpp v155, v155, v155 row_half_mirror row_mask:0xf bank_mask:0xf
	v_add_f32_dpp v156, v156, v156 row_half_mirror row_mask:0xf bank_mask:0xf
	v_add_f32_dpp v157, v157, v157 row_half_mirror row_mask:0xf bank_mask:0xf
	v_add_f32_dpp v158, v158, v158 row_half_mirror row_mask:0xf bank_mask:0xf
	v_add_f32_dpp v159, v159, v159 row_half_mirror row_mask:0xf bank_mask:0xf
	v_add_f32_dpp v160, v160, v160 row_half_mirror row_mask:0xf bank_mask:0xf
	v_add_f32_dpp v161, v161, v161 row_half_mirror row_mask:0xf bank_mask:0xf
	v_add_f32_dpp v162, v162, v162 row_half_mirror row_mask:0xf bank_mask:0xf
	v_add_f32_dpp v163, v163, v163 row_half_mirror row_mask:0xf bank_mask:0xf
	v_add_f32_dpp v148, v148, v148 row_mirror row_mask:0xf bank_mask:0xf
	v_add_f32_dpp v149, v149, v149 row_mirror row_mask:0xf bank_mask:0xf
	v_add_f32_dpp v150, v150, v150 row_mirror row_mask:0xf bank_mask:0xf
	v_add_f32_dpp v151, v151, v151 row_mirror row_mask:0xf bank_mask:0xf
	v_add_f32_dpp v152, v152, v152 row_mirror row_mask:0xf bank_mask:0xf
	v_add_f32_dpp v153, v153, v153 row_mirror row_mask:0xf bank_mask:0xf
	v_add_f32_dpp v154, v154, v154 row_mirror row_mask:0xf bank_mask:0xf
	v_add_f32_dpp v155, v155, v155 row_mirror row_mask:0xf bank_mask:0xf
	v_add_f32_dpp v156, v156, v156 row_mirror row_mask:0xf bank_mask:0xf
	v_add_f32_dpp v157, v157, v157 row_mirror row_mask:0xf bank_mask:0xf
	v_add_f32_dpp v158, v158, v158 row_mirror row_mask:0xf bank_mask:0xf
	v_add_f32_dpp v159, v159, v159 row_mirror row_mask:0xf bank_mask:0xf
	v_add_f32_dpp v160, v160, v160 row_mirror row_mask:0xf bank_mask:0xf
	v_add_f32_dpp v161, v161, v161 row_mirror row_mask:0xf bank_mask:0xf
	v_add_f32_dpp v162, v162, v162 row_mirror row_mask:0xf bank_mask:0xf
	v_add_f32_dpp v163, v163, v163 row_mirror row_mask:0xf bank_mask:0xf
	ds_bpermute_b32 v208, v207, v148
	ds_bpermute_b32 v209, v207, v149
	ds_bpermute_b32 v210, v207, v150
	ds_bpermute_b32 v211, v207, v151
	ds_bpermute_b32 v212, v207, v152
	ds_bpermute_b32 v213, v207, v153
	ds_bpermute_b32 v214, v207, v154
	ds_bpermute_b32 v215, v207, v155
	ds_bpermute_b32 v216, v207, v156
	ds_bpermute_b32 v217, v207, v157
	ds_bpermute_b32 v218, v207, v158
	ds_bpermute_b32 v219, v207, v159
	ds_bpermute_b32 v220, v207, v160
	ds_bpermute_b32 v221, v207, v161
	ds_bpermute_b32 v222, v207, v162
	ds_bpermute_b32 v223, v207, v163
	v_cmp_eq_u32_e64 s[40:41], 0, v196
	s_waitcnt lgkmcnt(0)
	v_add_f32_e32 v148, v148, v208
	v_add_f32_e32 v149, v149, v209
	v_add_f32_e32 v150, v150, v210
	v_add_f32_e32 v151, v151, v211
	v_add_f32_e32 v152, v152, v212
	v_add_f32_e32 v153, v153, v213
	v_add_f32_e32 v154, v154, v214
	v_add_f32_e32 v155, v155, v215
	v_add_f32_e32 v156, v156, v216
	v_add_f32_e32 v157, v157, v217
	v_add_f32_e32 v158, v158, v218
	v_add_f32_e32 v159, v159, v219
	v_add_f32_e32 v160, v160, v220
	v_add_f32_e32 v161, v161, v221
	v_add_f32_e32 v162, v162, v222
	v_add_f32_e32 v163, v163, v223
	s_and_saveexec_b64 s[44:45], s[40:41]
	v_mov_b32_e32 v171, v170
	global_store_dword v171, v148, s[42:43]
	v_add_u32_e32 v172, 0x20, v170
	global_store_dword v172, v149, s[42:43]
	v_add_u32_e32 v173, 0x40, v170
	global_store_dword v173, v150, s[42:43]
	v_add_u32_e32 v174, 0x60, v170
	global_store_dword v174, v151, s[42:43]
	v_add_u32_e32 v171, 0x100, v170
	global_store_dword v171, v152, s[42:43]
	v_add_u32_e32 v172, 0x120, v170
	global_store_dword v172, v153, s[42:43]
	v_add_u32_e32 v173, 0x140, v170
	global_store_dword v173, v154, s[42:43]
	v_add_u32_e32 v174, 0x160, v170
	global_store_dword v174, v155, s[42:43]
	v_add_u32_e32 v171, 0x200, v170
	global_store_dword v171, v156, s[42:43]
	v_add_u32_e32 v172, 0x220, v170
	global_store_dword v172, v157, s[42:43]
	v_add_u32_e32 v173, 0x240, v170
	global_store_dword v173, v158, s[42:43]
	v_add_u32_e32 v174, 0x260, v170
	global_store_dword v174, v159, s[42:43]
	v_add_u32_e32 v171, 0x300, v170
	global_store_dword v171, v160, s[42:43]
	v_add_u32_e32 v172, 0x320, v170
	global_store_dword v172, v161, s[42:43]
	v_add_u32_e32 v173, 0x340, v170
	global_store_dword v173, v162, s[42:43]
	v_add_u32_e32 v174, 0x360, v170
	global_store_dword v174, v163, s[42:43]
	s_or_b64 exec, exec, s[44:45]
	s_branch .LBB0_416
